# GEMM K-loops: first iteration peeled with SrcC=0 on each accumulator's first MFMA, removing the 128 v_mov accumulator zeroing per unit from the MFMA-idle gap between units
# speedup vs baseline: 1.0072x; 1.0072x over previous
; #define PG8_STAGE(bufoff, gbase, voff) do { _Pragma("unroll") for (int _i = 0; _i < 2; ++_i) \
;         __builtin_amdgcn_global_load_lds((const unsigned*)((const char*)(gbase) + (voff)[_i]), (LAS unsigned*)(lds + (bufoff) + ldsw + _i * 8192), 16, 0, 0); } while (0)
; #define PG8_LDA(dst, b, h) do { _Pragma("unroll") for (int m = 0; m < 4; ++m) _Pragma("unroll") for (int k = 0; k < 2; ++k) dst[m][k] = *(const LAS bf16x8*)(lds + PG8_SA(b, h) + aoff + m * 2048 + k * 1024); } while (0)
; #define PG8_LDB(dst, b, h) do { _Pragma("unroll") for (int n = 0; n < 2; ++n) _Pragma("unroll") for (int k = 0; k < 2; ++k) dst[n][k] = *(const LAS bf16x8*)(lds + PG8_SB(b, h) + boff + n * 2048 + k * 1024); } while (0)
; #define PG8_WAIT_V(n) asm volatile("s_waitcnt vmcnt(" #n ")" ::: "memory")
; #define PG8_WAIT_L(n) asm volatile("s_waitcnt lgkmcnt(" #n ")" ::: "memory")
; #define PG8_BAR __builtin_amdgcn_s_barrier()
; #define PG8_SCHED __builtin_amdgcn_sched_barrier(0)
; template <class Epi, class Sched = StaticOrder, class EpiSub = NoSub, bool FAST = false>
; __device__ __forceinline__ void gemm_phase(LAS unsigned char* lds, const Gemm g, const Sched& S, const Epi& E, const EpiSub& ES = EpiSub()) {
;     ...
;         const bool has_next = S.next(ui + 1, nxt);
;         const size_t nko = (has_next && nxt.kb >= 0) ? nxt.kb * ksubB : 0;
;         const char* nA = has_next ? (const char*)g.A + (size_t)nxt.pm * tstepA + (size_t)nxt.pn * g.acs + nko : cA; const char* nB = has_next ? (const char*)g.Bt + (size_t)nxt.pn * tstepB + nko : cB;
;         const int nt = cur.kb < 0 ? ntMain : ntSub;
;         for (int t = 0; t < nt; t += 2) {
;             const bool last = (t == nt - 2);
;             const char* a1 = cA + (size_t)(t + 1) * kstep;
;             const char* a2 = last ? nA : cA + (size_t)(t + 2) * kstep; const char* b2 = last ? nB : cB + (size_t)(t + 2) * kstep;
;             const char* a3 = a2 + kstep; const char* b3 = b2 + kstep;
;             if constexpr (FAST && PG8_SP2) {
;             PG8_LDB(B0, 0, 0); PG8_LDB(B1, 0, 1); PG8_SCHED; PG8_LDA(At, 0, 0); PG8_STAGE(PG8_SA(1, 1), a1 + hstepA, voffA);
;             PG8_WAIT_V(8); PG8_WAIT_L(0); PG8_BAR; PG8_MMA(0, 0, At, B0); PG8_MMA(0, 1, At, B1); PG8_BAR; PG8_SCHED;
;             PG8_LDA(At, 0, 1); PG8_STAGE(PG8_SB(0, 0), b2, voffB); PG8_STAGE(PG8_SB(0, 1), b2 + hstepB, voffB); PG8_STAGE(PG8_SA(0, 0), a2, voffA);
.LBB0_215:
	s_ashr_i32 s15, s14, 31
	s_lshl_b64 s[2:3], s[14:15], 20
	v_readlane_b32 s16, v254, 36
	v_readlane_b32 s17, v254, 37
	s_add_u32 s16, s16, s2
	s_addc_u32 s17, s17, s3
	s_and_b64 s[2:3], s[0:1], exec
	s_cselect_b32 s2, s17, s23
	s_cselect_b32 s3, s16, s22
	s_ashr_i32 s13, s12, 31
	s_lshl_b64 s[18:19], s[12:13], 20
	s_add_u32 s18, s28, s18
	s_addc_u32 s19, s29, s19
	s_and_b64 s[26:27], s[0:1], exec
	s_cselect_b32 s13, s19, s25
	s_cselect_b32 s15, s18, s24
	s_add_u32 s22, s22, 0x80080
	s_addc_u32 s23, s23, 0
	s_add_u32 s48, s24, 0x100
	s_addc_u32 s49, s25, 0
	s_mov_b32 s50, -2
	ds_read_b128 v[154:157], v150
	ds_read_b128 v[158:161], v150 offset:1024
	ds_read_b128 v[162:165], v150 offset:2048
	ds_read_b128 v[166:169], v150 offset:3072
	ds_read_b128 v[170:173], v151
	ds_read_b128 v[174:177], v151 offset:1024
	ds_read_b128 v[178:181], v151 offset:2048
	ds_read_b128 v[182:185], v151 offset:3072
	s_add_u32 s24, s22, 0xfff80080
	s_addc_u32 s25, s23, -1
	s_cmp_eq_u32 s50, 28
	s_cselect_b32 s27, s2, s25
	s_cselect_b32 s26, s3, s24
	s_cselect_b32 s25, s13, s49
	s_cselect_b32 s24, s15, s48
	v_lshl_add_u64 v[144:145], s[22:23], 0, v[136:137]
	s_add_i32 m0, s21, 0xc000
	ds_read_b128 v[186:189], v152
	ds_read_b128 v[194:197], v152 offset:1024
	ds_read_b128 v[198:201], v152 offset:2048
	ds_read_b128 v[202:205], v152 offset:3072
	ds_read_b128 v[206:209], v152 offset:4096
	ds_read_b128 v[210:213], v152 offset:5120
	ds_read_b128 v[214:217], v152 offset:6144
	ds_read_b128 v[218:221], v152 offset:7168
	global_load_lds_dwordx4 v[144:145], off
	v_lshl_add_u64 v[144:145], s[22:23], 0, v[138:139]
	s_add_i32 m0, s21, 0xe000
	s_nop 0
	global_load_lds_dwordx4 v[144:145], off
	s_waitcnt vmcnt(8)
	s_waitcnt lgkmcnt(0)
	s_setprio 1
	s_barrier
	v_mfma_f32_16x16x32_bf16 v[124:127], v[154:157], v[186:189], 0
	v_mfma_f32_16x16x32_bf16 v[120:123], v[162:165], v[186:189], 0
	v_mfma_f32_16x16x32_bf16 v[116:119], v[154:157], v[198:201], 0
	v_mfma_f32_16x16x32_bf16 v[108:111], v[162:165], v[198:201], 0
	v_mfma_f32_16x16x32_bf16 v[100:103], v[154:157], v[206:209], 0
	v_mfma_f32_16x16x32_bf16 v[92:95], v[162:165], v[206:209], 0
	v_mfma_f32_16x16x32_bf16 v[84:87], v[154:157], v[214:217], 0
	v_mfma_f32_16x16x32_bf16 v[76:79], v[162:165], v[214:217], 0
	v_mfma_f32_16x16x32_bf16 v[124:127], v[158:161], v[194:197], v[124:127]
	v_mfma_f32_16x16x32_bf16 v[120:123], v[166:169], v[194:197], v[120:123]
	v_mfma_f32_16x16x32_bf16 v[116:119], v[158:161], v[202:205], v[116:119]
	v_mfma_f32_16x16x32_bf16 v[108:111], v[166:169], v[202:205], v[108:111]
	v_mfma_f32_16x16x32_bf16 v[100:103], v[158:161], v[210:213], v[100:103]
	v_mfma_f32_16x16x32_bf16 v[92:95], v[166:169], v[210:213], v[92:95]
	v_mfma_f32_16x16x32_bf16 v[84:87], v[158:161], v[218:221], v[84:87]
	v_mfma_f32_16x16x32_bf16 v[76:79], v[166:169], v[218:221], v[76:79]
	v_mfma_f32_16x16x32_bf16 v[112:115], v[170:173], v[186:189], 0
	v_mfma_f32_16x16x32_bf16 v[104:107], v[178:181], v[186:189], 0
	v_mfma_f32_16x16x32_bf16 v[96:99], v[170:173], v[198:201], 0
	v_mfma_f32_16x16x32_bf16 v[88:91], v[178:181], v[198:201], 0
	v_mfma_f32_16x16x32_bf16 v[80:83], v[170:173], v[206:209], 0
	v_mfma_f32_16x16x32_bf16 v[72:75], v[178:181], v[206:209], 0
	v_mfma_f32_16x16x32_bf16 v[68:71], v[170:173], v[214:217], 0
	v_mfma_f32_16x16x32_bf16 v[64:67], v[178:181], v[214:217], 0
	v_mfma_f32_16x16x32_bf16 v[112:115], v[174:177], v[194:197], v[112:115]
	v_mfma_f32_16x16x32_bf16 v[104:107], v[182:185], v[194:197], v[104:107]
	v_mfma_f32_16x16x32_bf16 v[96:99], v[174:177], v[202:205], v[96:99]
	v_mfma_f32_16x16x32_bf16 v[88:91], v[182:185], v[202:205], v[88:91]
	v_mfma_f32_16x16x32_bf16 v[80:83], v[174:177], v[210:213], v[80:83]
	v_mfma_f32_16x16x32_bf16 v[72:75], v[182:185], v[210:213], v[72:75]
	v_mfma_f32_16x16x32_bf16 v[68:71], v[174:177], v[218:221], v[68:71]
	v_mfma_f32_16x16x32_bf16 v[64:67], v[182:185], v[218:221], v[64:67]
	s_barrier
	s_setprio 0
	s_add_i32 s51, s41, s30
	v_lshl_add_u64 v[144:145], s[24:25], 0, v[130:131]
	s_mov_b32 m0, s51
	ds_read_b128 v[186:189], v152 offset:16384
	ds_read_b128 v[194:197], v152 offset:17408
	ds_read_b128 v[198:201], v152 offset:18432
	ds_read_b128 v[202:205], v152 offset:19456
	ds_read_b128 v[206:209], v152 offset:20480
	ds_read_b128 v[210:213], v152 offset:21504
	ds_read_b128 v[214:217], v152 offset:22528
	ds_read_b128 v[218:221], v152 offset:23552
	global_load_lds_dwordx4 v[144:145], off
	s_add_i32 m0, s51, 0x2000
	s_add_u32 s68, s24, 0x80000
	v_lshl_add_u64 v[190:191], s[24:25], 0, v[134:135]
	s_addc_u32 s69, s25, 0
	s_add_i32 s51, s42, s30
	global_load_lds_dwordx4 v[190:191], off
	v_lshl_add_u64 v[222:223], s[68:69], 0, v[130:131]
	s_mov_b32 m0, s51
	v_lshl_add_u64 v[224:225], s[26:27], 0, v[132:133]
	global_load_lds_dwordx4 v[222:223], off
	v_lshl_add_u64 v[222:223], s[68:69], 0, v[134:135]
	s_add_i32 m0, s51, 0x2000
	s_nop 0
	global_load_lds_dwordx4 v[222:223], off
	v_lshl_add_u64 v[222:223], s[26:27], 0, v[128:129]
	s_mov_b32 m0, s21
	s_nop 0
	global_load_lds_dwordx4 v[222:223], off
	s_mov_b32 m0, s34
	s_nop 0
	global_load_lds_dwordx4 v[224:225], off
	s_waitcnt vmcnt(8)
	s_waitcnt lgkmcnt(0)
	s_setprio 1
	s_barrier
; #define PG8_STAGE(bufoff, gbase, voff) do { _Pragma("unroll") for (int _i = 0; _i < 2; ++_i) \
;         __builtin_amdgcn_global_load_lds((const unsigned*)((const char*)(gbase) + (voff)[_i]), (LAS unsigned*)(lds + (bufoff) + ldsw + _i * 8192), 16, 0, 0); } while (0)
; #define PG8_LDA(dst, b, h) do { _Pragma("unroll") for (int m = 0; m < 4; ++m) _Pragma("unroll") for (int k = 0; k < 2; ++k) dst[m][k] = *(const LAS bf16x8*)(lds + PG8_SA(b, h) + aoff + m * 2048 + k * 1024); } while (0)
; #define PG8_LDB(dst, b, h) do { _Pragma("unroll") for (int n = 0; n < 2; ++n) _Pragma("unroll") for (int k = 0; k < 2; ++k) dst[n][k] = *(const LAS bf16x8*)(lds + PG8_SB(b, h) + boff + n * 2048 + k * 1024); } while (0)
; #define PG8_MMA(ai, bj, At, Bt) do { __builtin_amdgcn_s_setprio(1); _Pragma("unroll") for (int m = 0; m < 4; ++m) _Pragma("unroll") for (int n = 0; n < 2; ++n) _Pragma("unroll") for (int k = 0; k < 2; ++k) \
;         acc[ai][bj][m][n] = __builtin_amdgcn_mfma_f32_16x16x32_bf16(Bt[n][k], At[m][k], acc[ai][bj][m][n], 0, 0, 0); __builtin_amdgcn_s_setprio(0); } while (0)
; #define PG8_WAIT_V(n) asm volatile("s_waitcnt vmcnt(" #n ")" ::: "memory")
; #define PG8_WAIT_L(n) asm volatile("s_waitcnt lgkmcnt(" #n ")" ::: "memory")
; #define PG8_BAR __builtin_amdgcn_s_barrier()
; #define PG8_SCHED __builtin_amdgcn_sched_barrier(0)
; template <class Epi, class Sched = StaticOrder, class EpiSub = NoSub, bool FAST = false>
; __device__ __forceinline__ void gemm_phase(LAS unsigned char* lds, const Gemm g, const Sched& S, const Epi& E, const EpiSub& ES = EpiSub()) {
;     ...
;             PG8_WAIT_V(8); PG8_WAIT_L(0); PG8_BAR; PG8_MMA(1, 0, At, B0); PG8_MMA(1, 1, At, B1); PG8_BAR; PG8_SCHED;
;             PG8_LDB(B0, 1, 0); PG8_LDB(B1, 1, 1); PG8_SCHED; PG8_LDA(At, 1, 0); PG8_STAGE(PG8_SA(0, 1), a2 + hstepA, voffA);
;             PG8_WAIT_V(8); PG8_WAIT_L(0); PG8_BAR; PG8_MMA(0, 0, At, B0); PG8_MMA(0, 1, At, B1); PG8_BAR; PG8_SCHED;
	v_mfma_f32_16x16x32_bf16 v[60:63], v[154:157], v[186:189], 0
	v_mfma_f32_16x16x32_bf16 v[56:59], v[162:165], v[186:189], 0
	v_mfma_f32_16x16x32_bf16 v[52:55], v[154:157], v[198:201], 0
	v_mfma_f32_16x16x32_bf16 v[44:47], v[162:165], v[198:201], 0
	v_mfma_f32_16x16x32_bf16 v[36:39], v[154:157], v[206:209], 0
	v_mfma_f32_16x16x32_bf16 v[28:31], v[162:165], v[206:209], 0
	v_mfma_f32_16x16x32_bf16 v[20:23], v[154:157], v[214:217], 0
	v_mfma_f32_16x16x32_bf16 v[12:15], v[162:165], v[214:217], 0
	v_mfma_f32_16x16x32_bf16 v[60:63], v[158:161], v[194:197], v[60:63]
	v_mfma_f32_16x16x32_bf16 v[56:59], v[166:169], v[194:197], v[56:59]
	v_mfma_f32_16x16x32_bf16 v[52:55], v[158:161], v[202:205], v[52:55]
	v_mfma_f32_16x16x32_bf16 v[44:47], v[166:169], v[202:205], v[44:47]
	v_mfma_f32_16x16x32_bf16 v[36:39], v[158:161], v[210:213], v[36:39]
	v_mfma_f32_16x16x32_bf16 v[28:31], v[166:169], v[210:213], v[28:31]
	v_mfma_f32_16x16x32_bf16 v[20:23], v[158:161], v[218:221], v[20:23]
	v_mfma_f32_16x16x32_bf16 v[12:15], v[166:169], v[218:221], v[12:15]
	v_mfma_f32_16x16x32_bf16 v[48:51], v[170:173], v[186:189], 0
	v_mfma_f32_16x16x32_bf16 v[40:43], v[178:181], v[186:189], 0
	v_mfma_f32_16x16x32_bf16 v[32:35], v[170:173], v[198:201], 0
	v_mfma_f32_16x16x32_bf16 v[24:27], v[178:181], v[198:201], 0
	v_mfma_f32_16x16x32_bf16 v[16:19], v[170:173], v[206:209], 0
	v_mfma_f32_16x16x32_bf16 v[8:11], v[178:181], v[206:209], 0
	v_mfma_f32_16x16x32_bf16 v[4:7], v[170:173], v[214:217], 0
	v_mfma_f32_16x16x32_bf16 v[0:3], v[178:181], v[214:217], 0
	v_mfma_f32_16x16x32_bf16 v[48:51], v[174:177], v[194:197], v[48:51]
	v_mfma_f32_16x16x32_bf16 v[40:43], v[182:185], v[194:197], v[40:43]
	v_mfma_f32_16x16x32_bf16 v[32:35], v[174:177], v[202:205], v[32:35]
	v_mfma_f32_16x16x32_bf16 v[24:27], v[182:185], v[202:205], v[24:27]
	v_mfma_f32_16x16x32_bf16 v[16:19], v[174:177], v[210:213], v[16:19]
	v_mfma_f32_16x16x32_bf16 v[8:11], v[182:185], v[210:213], v[8:11]
	v_mfma_f32_16x16x32_bf16 v[4:7], v[174:177], v[218:221], v[4:7]
	v_mfma_f32_16x16x32_bf16 v[0:3], v[182:185], v[218:221], v[0:3]
	s_barrier
	s_setprio 0
	s_add_i32 s51, 0, 0x18000
	v_add_u32_e32 v153, s51, v148
	s_add_i32 s68, 0, 0x1c000
	ds_read_b128 v[154:157], v153
	ds_read_b128 v[158:161], v153 offset:1024
	ds_read_b128 v[162:165], v153 offset:2048
	ds_read_b128 v[166:169], v153 offset:3072
	v_add_u32_e32 v153, s68, v148
	ds_read_b128 v[170:173], v153
	ds_read_b128 v[174:177], v153 offset:1024
	ds_read_b128 v[178:181], v153 offset:2048
	ds_read_b128 v[182:185], v153 offset:3072
	s_add_u32 s26, s26, 0x80000
	s_addc_u32 s27, s27, 0
	s_mov_b32 m0, s35
	v_lshl_add_u64 v[226:227], s[26:27], 0, v[128:129]
	ds_read_b128 v[186:189], v152 offset:32768
	ds_read_b128 v[194:197], v152 offset:33792
	ds_read_b128 v[198:201], v152 offset:34816
	ds_read_b128 v[202:205], v152 offset:35840
	ds_read_b128 v[206:209], v152 offset:36864
	ds_read_b128 v[210:213], v152 offset:37888
	ds_read_b128 v[214:217], v152 offset:38912
	ds_read_b128 v[218:221], v152 offset:39936
	global_load_lds_dwordx4 v[226:227], off
	v_lshl_add_u64 v[226:227], s[26:27], 0, v[132:133]
	s_mov_b32 m0, s36
	s_nop 0
	global_load_lds_dwordx4 v[226:227], off
	s_waitcnt vmcnt(8)
	s_waitcnt lgkmcnt(0)
	s_setprio 1
	s_barrier
	v_mfma_f32_16x16x32_bf16 v[124:127], v[154:157], v[186:189], v[124:127]
	v_mfma_f32_16x16x32_bf16 v[120:123], v[162:165], v[186:189], v[120:123]
	v_mfma_f32_16x16x32_bf16 v[116:119], v[154:157], v[198:201], v[116:119]
	v_mfma_f32_16x16x32_bf16 v[108:111], v[162:165], v[198:201], v[108:111]
	v_mfma_f32_16x16x32_bf16 v[100:103], v[154:157], v[206:209], v[100:103]
	v_mfma_f32_16x16x32_bf16 v[92:95], v[162:165], v[206:209], v[92:95]
	v_mfma_f32_16x16x32_bf16 v[84:87], v[154:157], v[214:217], v[84:87]
	v_mfma_f32_16x16x32_bf16 v[76:79], v[162:165], v[214:217], v[76:79]
	v_mfma_f32_16x16x32_bf16 v[124:127], v[158:161], v[194:197], v[124:127]
	v_mfma_f32_16x16x32_bf16 v[120:123], v[166:169], v[194:197], v[120:123]
	v_mfma_f32_16x16x32_bf16 v[116:119], v[158:161], v[202:205], v[116:119]
	v_mfma_f32_16x16x32_bf16 v[108:111], v[166:169], v[202:205], v[108:111]
	v_mfma_f32_16x16x32_bf16 v[100:103], v[158:161], v[210:213], v[100:103]
	v_mfma_f32_16x16x32_bf16 v[92:95], v[166:169], v[210:213], v[92:95]
	v_mfma_f32_16x16x32_bf16 v[84:87], v[158:161], v[218:221], v[84:87]
	v_mfma_f32_16x16x32_bf16 v[76:79], v[166:169], v[218:221], v[76:79]
	v_mfma_f32_16x16x32_bf16 v[112:115], v[170:173], v[186:189], v[112:115]
	v_mfma_f32_16x16x32_bf16 v[104:107], v[178:181], v[186:189], v[104:107]
	v_mfma_f32_16x16x32_bf16 v[96:99], v[170:173], v[198:201], v[96:99]
	v_mfma_f32_16x16x32_bf16 v[88:91], v[178:181], v[198:201], v[88:91]
	v_mfma_f32_16x16x32_bf16 v[80:83], v[170:173], v[206:209], v[80:83]
	v_mfma_f32_16x16x32_bf16 v[72:75], v[178:181], v[206:209], v[72:75]
	v_mfma_f32_16x16x32_bf16 v[68:71], v[170:173], v[214:217], v[68:71]
	v_mfma_f32_16x16x32_bf16 v[64:67], v[178:181], v[214:217], v[64:67]
	v_mfma_f32_16x16x32_bf16 v[112:115], v[174:177], v[194:197], v[112:115]
	v_mfma_f32_16x16x32_bf16 v[104:107], v[182:185], v[194:197], v[104:107]
	v_mfma_f32_16x16x32_bf16 v[96:99], v[174:177], v[202:205], v[96:99]
	v_mfma_f32_16x16x32_bf16 v[88:91], v[182:185], v[202:205], v[88:91]
	v_mfma_f32_16x16x32_bf16 v[80:83], v[174:177], v[210:213], v[80:83]
	v_mfma_f32_16x16x32_bf16 v[72:75], v[182:185], v[210:213], v[72:75]
	v_mfma_f32_16x16x32_bf16 v[68:71], v[174:177], v[218:221], v[68:71]
	v_mfma_f32_16x16x32_bf16 v[64:67], v[182:185], v[218:221], v[64:67]
	s_barrier
; #define PG8_STAGE(bufoff, gbase, voff) do { _Pragma("unroll") for (int _i = 0; _i < 2; ++_i) \
;         __builtin_amdgcn_global_load_lds((const unsigned*)((const char*)(gbase) + (voff)[_i]), (LAS unsigned*)(lds + (bufoff) + ldsw + _i * 8192), 16, 0, 0); } while (0)
; #define PG8_LDA(dst, b, h) do { _Pragma("unroll") for (int m = 0; m < 4; ++m) _Pragma("unroll") for (int k = 0; k < 2; ++k) dst[m][k] = *(const LAS bf16x8*)(lds + PG8_SA(b, h) + aoff + m * 2048 + k * 1024); } while (0)
; #define PG8_LDB(dst, b, h) do { _Pragma("unroll") for (int n = 0; n < 2; ++n) _Pragma("unroll") for (int k = 0; k < 2; ++k) dst[n][k] = *(const LAS bf16x8*)(lds + PG8_SB(b, h) + boff + n * 2048 + k * 1024); } while (0)
; template <class Epi, class Sched = StaticOrder, class EpiSub = NoSub, bool FAST = false>
; __device__ __forceinline__ void gemm_phase(LAS unsigned char* lds, const Gemm g, const Sched& S, const Epi& E, const EpiSub& ES = EpiSub()) {
;     ...
;         for (int t = 0; t < nt; t += 2) {
;             const bool last = (t == nt - 2);
;             const char* a1 = cA + (size_t)(t + 1) * kstep;
;             const char* a2 = last ? nA : cA + (size_t)(t + 2) * kstep; const char* b2 = last ? nB : cB + (size_t)(t + 2) * kstep;
;             const char* a3 = a2 + kstep; const char* b3 = b2 + kstep;
;             if constexpr (FAST && PG8_SP2) {
;             PG8_LDB(B0, 0, 0); PG8_LDB(B1, 0, 1); PG8_SCHED; PG8_LDA(At, 0, 0); PG8_STAGE(PG8_SA(1, 1), a1 + hstepA, voffA);
;             PG8_WAIT_V(8); PG8_WAIT_L(0); PG8_BAR; PG8_MMA(0, 0, At, B0); PG8_MMA(0, 1, At, B1); PG8_BAR; PG8_SCHED;
;             PG8_LDA(At, 0, 1); PG8_STAGE(PG8_SB(0, 0), b2, voffB); PG8_STAGE(PG8_SB(0, 1), b2 + hstepB, voffB); PG8_STAGE(PG8_SA(0, 0), a2, voffA);
;             PG8_WAIT_V(8); PG8_WAIT_L(0); PG8_BAR; PG8_MMA(1, 0, At, B0); PG8_MMA(1, 1, At, B1); PG8_BAR; PG8_SCHED;
;             PG8_LDB(B0, 1, 0); PG8_LDB(B1, 1, 1); PG8_SCHED; PG8_LDA(At, 1, 0); PG8_STAGE(PG8_SA(0, 1), a2 + hstepA, voffA);
;             PG8_WAIT_V(8); PG8_WAIT_L(0); PG8_BAR; PG8_MMA(0, 0, At, B0); PG8_MMA(0, 1, At, B1); PG8_BAR; PG8_SCHED;
;             PG8_LDA(At, 1, 1); PG8_STAGE(PG8_SB(1, 0), b3, voffB); PG8_STAGE(PG8_SB(1, 1), b3 + hstepB, voffB); PG8_STAGE(PG8_SA(1, 0), a3, voffA);
;             PG8_WAIT_V(8); PG8_WAIT_L(0); PG8_BAR; PG8_MMA(1, 0, At, B0); PG8_MMA(1, 1, At, B1); PG8_BAR; PG8_SCHED;
	s_setprio 0
	s_add_i32 s26, s51, s30
	v_lshl_add_u64 v[144:145], v[144:145], 0, s[8:9]
	s_mov_b32 m0, s26
	ds_read_b128 v[186:189], v152 offset:49152
	ds_read_b128 v[194:197], v152 offset:50176
	ds_read_b128 v[198:201], v152 offset:51200
	ds_read_b128 v[202:205], v152 offset:52224
	ds_read_b128 v[206:209], v152 offset:53248
	ds_read_b128 v[210:213], v152 offset:54272
	ds_read_b128 v[214:217], v152 offset:55296
	ds_read_b128 v[218:221], v152 offset:56320
	global_load_lds_dwordx4 v[144:145], off
	s_add_i32 m0, s26, 0x2000
	s_add_u32 s24, s24, 0x80080
	v_lshl_add_u64 v[144:145], v[190:191], 0, s[8:9]
	s_addc_u32 s25, s25, 0
	s_add_i32 s26, s68, s30
	global_load_lds_dwordx4 v[144:145], off
	v_lshl_add_u64 v[144:145], s[24:25], 0, v[130:131]
	s_mov_b32 m0, s26
	s_nop 0
	global_load_lds_dwordx4 v[144:145], off
	v_lshl_add_u64 v[144:145], s[24:25], 0, v[134:135]
	s_add_i32 m0, s26, 0x2000
	s_nop 0
	global_load_lds_dwordx4 v[144:145], off
	v_lshl_add_u64 v[144:145], v[222:223], 0, s[8:9]
	s_mov_b32 m0, s39
	s_nop 0
	global_load_lds_dwordx4 v[144:145], off
	v_lshl_add_u64 v[144:145], v[224:225], 0, s[8:9]
	s_mov_b32 m0, s40
	s_nop 0
	global_load_lds_dwordx4 v[144:145], off
	s_waitcnt vmcnt(8)
	s_waitcnt lgkmcnt(0)
	s_setprio 1
	s_barrier
	v_mfma_f32_16x16x32_bf16 v[60:63], v[154:157], v[186:189], v[60:63]
	v_mfma_f32_16x16x32_bf16 v[56:59], v[162:165], v[186:189], v[56:59]
	v_mfma_f32_16x16x32_bf16 v[52:55], v[154:157], v[198:201], v[52:55]
	v_mfma_f32_16x16x32_bf16 v[44:47], v[162:165], v[198:201], v[44:47]
	v_mfma_f32_16x16x32_bf16 v[36:39], v[154:157], v[206:209], v[36:39]
	v_mfma_f32_16x16x32_bf16 v[28:31], v[162:165], v[206:209], v[28:31]
	v_mfma_f32_16x16x32_bf16 v[20:23], v[154:157], v[214:217], v[20:23]
	v_mfma_f32_16x16x32_bf16 v[12:15], v[162:165], v[214:217], v[12:15]
	v_mfma_f32_16x16x32_bf16 v[60:63], v[158:161], v[194:197], v[60:63]
	v_mfma_f32_16x16x32_bf16 v[56:59], v[166:169], v[194:197], v[56:59]
	v_mfma_f32_16x16x32_bf16 v[52:55], v[158:161], v[202:205], v[52:55]
	v_mfma_f32_16x16x32_bf16 v[44:47], v[166:169], v[202:205], v[44:47]
	v_mfma_f32_16x16x32_bf16 v[36:39], v[158:161], v[210:213], v[36:39]
	v_mfma_f32_16x16x32_bf16 v[28:31], v[166:169], v[210:213], v[28:31]
	v_mfma_f32_16x16x32_bf16 v[20:23], v[158:161], v[218:221], v[20:23]
	v_mfma_f32_16x16x32_bf16 v[12:15], v[166:169], v[218:221], v[12:15]
	v_mfma_f32_16x16x32_bf16 v[48:51], v[170:173], v[186:189], v[48:51]
	v_mfma_f32_16x16x32_bf16 v[40:43], v[178:181], v[186:189], v[40:43]
	v_mfma_f32_16x16x32_bf16 v[32:35], v[170:173], v[198:201], v[32:35]
	v_mfma_f32_16x16x32_bf16 v[24:27], v[178:181], v[198:201], v[24:27]
	v_mfma_f32_16x16x32_bf16 v[16:19], v[170:173], v[206:209], v[16:19]
	v_mfma_f32_16x16x32_bf16 v[8:11], v[178:181], v[206:209], v[8:11]
	v_mfma_f32_16x16x32_bf16 v[4:7], v[170:173], v[214:217], v[4:7]
	v_mfma_f32_16x16x32_bf16 v[0:3], v[178:181], v[214:217], v[0:3]
	v_mfma_f32_16x16x32_bf16 v[48:51], v[174:177], v[194:197], v[48:51]
	v_mfma_f32_16x16x32_bf16 v[40:43], v[182:185], v[194:197], v[40:43]
	v_mfma_f32_16x16x32_bf16 v[32:35], v[174:177], v[202:205], v[32:35]
	v_mfma_f32_16x16x32_bf16 v[24:27], v[182:185], v[202:205], v[24:27]
	v_mfma_f32_16x16x32_bf16 v[16:19], v[174:177], v[210:213], v[16:19]
	v_mfma_f32_16x16x32_bf16 v[8:11], v[182:185], v[210:213], v[8:11]
	v_mfma_f32_16x16x32_bf16 v[4:7], v[174:177], v[218:221], v[4:7]
	v_mfma_f32_16x16x32_bf16 v[0:3], v[182:185], v[218:221], v[0:3]
	s_barrier
	s_setprio 0
	s_add_i32 s50, s50, 2
	s_add_u32 s22, s22, 0x100
	s_addc_u32 s23, s23, 0
	s_add_u32 s48, s48, 0x100
	s_addc_u32 s49, s49, 0
	s_cmp_gt_u32 s50, 29
	s_cbranch_scc1 .Lkpeel_216_exit
.LBB0_216:
	ds_read_b128 v[154:157], v150
	ds_read_b128 v[158:161], v150 offset:1024
	ds_read_b128 v[162:165], v150 offset:2048
	ds_read_b128 v[166:169], v150 offset:3072
	ds_read_b128 v[170:173], v151
	ds_read_b128 v[174:177], v151 offset:1024
	ds_read_b128 v[178:181], v151 offset:2048
	ds_read_b128 v[182:185], v151 offset:3072
	s_add_u32 s24, s22, 0xfff80080
	s_addc_u32 s25, s23, -1
	s_cmp_eq_u32 s50, 28
	s_cselect_b32 s27, s2, s25
	s_cselect_b32 s26, s3, s24
	s_cselect_b32 s25, s13, s49
	s_cselect_b32 s24, s15, s48
	v_lshl_add_u64 v[144:145], s[22:23], 0, v[136:137]
	s_add_i32 m0, s21, 0xc000
	ds_read_b128 v[186:189], v152
	ds_read_b128 v[194:197], v152 offset:1024
	ds_read_b128 v[198:201], v152 offset:2048
	ds_read_b128 v[202:205], v152 offset:3072
	ds_read_b128 v[206:209], v152 offset:4096
	ds_read_b128 v[210:213], v152 offset:5120
	ds_read_b128 v[214:217], v152 offset:6144
	ds_read_b128 v[218:221], v152 offset:7168
	global_load_lds_dwordx4 v[144:145], off
	v_lshl_add_u64 v[144:145], s[22:23], 0, v[138:139]
	s_add_i32 m0, s21, 0xe000
	s_nop 0
	global_load_lds_dwordx4 v[144:145], off
	s_waitcnt vmcnt(8)
	s_waitcnt lgkmcnt(0)
	s_setprio 1
	s_barrier
; #define PG8_STAGE(bufoff, gbase, voff) do { _Pragma("unroll") for (int _i = 0; _i < 2; ++_i) \
;         __builtin_amdgcn_global_load_lds((const unsigned*)((const char*)(gbase) + (voff)[_i]), (LAS unsigned*)(lds + (bufoff) + ldsw + _i * 8192), 16, 0, 0); } while (0)
; #define PG8_LDA(dst, b, h) do { _Pragma("unroll") for (int m = 0; m < 4; ++m) _Pragma("unroll") for (int k = 0; k < 2; ++k) dst[m][k] = *(const LAS bf16x8*)(lds + PG8_SA(b, h) + aoff + m * 2048 + k * 1024); } while (0)
; #define PG8_MMA(ai, bj, At, Bt) do { __builtin_amdgcn_s_setprio(1); _Pragma("unroll") for (int m = 0; m < 4; ++m) _Pragma("unroll") for (int n = 0; n < 2; ++n) _Pragma("unroll") for (int k = 0; k < 2; ++k) \
;         acc[ai][bj][m][n] = __builtin_amdgcn_mfma_f32_16x16x32_bf16(Bt[n][k], At[m][k], acc[ai][bj][m][n], 0, 0, 0); __builtin_amdgcn_s_setprio(0); } while (0)
; #define PG8_WAIT_V(n) asm volatile("s_waitcnt vmcnt(" #n ")" ::: "memory")
; #define PG8_WAIT_L(n) asm volatile("s_waitcnt lgkmcnt(" #n ")" ::: "memory")
; #define PG8_BAR __builtin_amdgcn_s_barrier()
; #define PG8_SCHED __builtin_amdgcn_sched_barrier(0)
; template <class Epi, class Sched = StaticOrder, class EpiSub = NoSub, bool FAST = false>
; __device__ __forceinline__ void gemm_phase(LAS unsigned char* lds, const Gemm g, const Sched& S, const Epi& E, const EpiSub& ES = EpiSub()) {
;     ...
;             PG8_WAIT_V(8); PG8_WAIT_L(0); PG8_BAR; PG8_MMA(0, 0, At, B0); PG8_MMA(0, 1, At, B1); PG8_BAR; PG8_SCHED;
;             PG8_LDA(At, 0, 1); PG8_STAGE(PG8_SB(0, 0), b2, voffB); PG8_STAGE(PG8_SB(0, 1), b2 + hstepB, voffB); PG8_STAGE(PG8_SA(0, 0), a2, voffA);
;             PG8_WAIT_V(8); PG8_WAIT_L(0); PG8_BAR; PG8_MMA(1, 0, At, B0); PG8_MMA(1, 1, At, B1); PG8_BAR; PG8_SCHED;
	v_mfma_f32_16x16x32_bf16 v[124:127], v[154:157], v[186:189], v[124:127]
	v_mfma_f32_16x16x32_bf16 v[120:123], v[162:165], v[186:189], v[120:123]
	v_mfma_f32_16x16x32_bf16 v[116:119], v[154:157], v[198:201], v[116:119]
	v_mfma_f32_16x16x32_bf16 v[108:111], v[162:165], v[198:201], v[108:111]
	v_mfma_f32_16x16x32_bf16 v[100:103], v[154:157], v[206:209], v[100:103]
	v_mfma_f32_16x16x32_bf16 v[92:95], v[162:165], v[206:209], v[92:95]
	v_mfma_f32_16x16x32_bf16 v[84:87], v[154:157], v[214:217], v[84:87]
	v_mfma_f32_16x16x32_bf16 v[76:79], v[162:165], v[214:217], v[76:79]
	v_mfma_f32_16x16x32_bf16 v[124:127], v[158:161], v[194:197], v[124:127]
	v_mfma_f32_16x16x32_bf16 v[120:123], v[166:169], v[194:197], v[120:123]
	v_mfma_f32_16x16x32_bf16 v[116:119], v[158:161], v[202:205], v[116:119]
	v_mfma_f32_16x16x32_bf16 v[108:111], v[166:169], v[202:205], v[108:111]
	v_mfma_f32_16x16x32_bf16 v[100:103], v[158:161], v[210:213], v[100:103]
	v_mfma_f32_16x16x32_bf16 v[92:95], v[166:169], v[210:213], v[92:95]
	v_mfma_f32_16x16x32_bf16 v[84:87], v[158:161], v[218:221], v[84:87]
	v_mfma_f32_16x16x32_bf16 v[76:79], v[166:169], v[218:221], v[76:79]
	v_mfma_f32_16x16x32_bf16 v[112:115], v[170:173], v[186:189], v[112:115]
	v_mfma_f32_16x16x32_bf16 v[104:107], v[178:181], v[186:189], v[104:107]
	v_mfma_f32_16x16x32_bf16 v[96:99], v[170:173], v[198:201], v[96:99]
	v_mfma_f32_16x16x32_bf16 v[88:91], v[178:181], v[198:201], v[88:91]
	v_mfma_f32_16x16x32_bf16 v[80:83], v[170:173], v[206:209], v[80:83]
	v_mfma_f32_16x16x32_bf16 v[72:75], v[178:181], v[206:209], v[72:75]
	v_mfma_f32_16x16x32_bf16 v[68:71], v[170:173], v[214:217], v[68:71]
	v_mfma_f32_16x16x32_bf16 v[64:67], v[178:181], v[214:217], v[64:67]
	v_mfma_f32_16x16x32_bf16 v[112:115], v[174:177], v[194:197], v[112:115]
	v_mfma_f32_16x16x32_bf16 v[104:107], v[182:185], v[194:197], v[104:107]
	v_mfma_f32_16x16x32_bf16 v[96:99], v[174:177], v[202:205], v[96:99]
	v_mfma_f32_16x16x32_bf16 v[88:91], v[182:185], v[202:205], v[88:91]
	v_mfma_f32_16x16x32_bf16 v[80:83], v[174:177], v[210:213], v[80:83]
	v_mfma_f32_16x16x32_bf16 v[72:75], v[182:185], v[210:213], v[72:75]
	v_mfma_f32_16x16x32_bf16 v[68:71], v[174:177], v[218:221], v[68:71]
	v_mfma_f32_16x16x32_bf16 v[64:67], v[182:185], v[218:221], v[64:67]
	s_barrier
	s_setprio 0
	s_add_i32 s51, s41, s30
	v_lshl_add_u64 v[144:145], s[24:25], 0, v[130:131]
	s_mov_b32 m0, s51
	ds_read_b128 v[186:189], v152 offset:16384
	ds_read_b128 v[194:197], v152 offset:17408
	ds_read_b128 v[198:201], v152 offset:18432
	ds_read_b128 v[202:205], v152 offset:19456
	ds_read_b128 v[206:209], v152 offset:20480
	ds_read_b128 v[210:213], v152 offset:21504
	ds_read_b128 v[214:217], v152 offset:22528
	ds_read_b128 v[218:221], v152 offset:23552
	global_load_lds_dwordx4 v[144:145], off
	s_add_i32 m0, s51, 0x2000
	s_add_u32 s68, s24, 0x80000
	v_lshl_add_u64 v[190:191], s[24:25], 0, v[134:135]
	s_addc_u32 s69, s25, 0
	s_add_i32 s51, s42, s30
	global_load_lds_dwordx4 v[190:191], off
	v_lshl_add_u64 v[222:223], s[68:69], 0, v[130:131]
	s_mov_b32 m0, s51
	v_lshl_add_u64 v[224:225], s[26:27], 0, v[132:133]
	global_load_lds_dwordx4 v[222:223], off
	v_lshl_add_u64 v[222:223], s[68:69], 0, v[134:135]
	s_add_i32 m0, s51, 0x2000
	s_nop 0
	global_load_lds_dwordx4 v[222:223], off
	v_lshl_add_u64 v[222:223], s[26:27], 0, v[128:129]
	s_mov_b32 m0, s21
	s_nop 0
	global_load_lds_dwordx4 v[222:223], off
	s_mov_b32 m0, s34
	s_nop 0
	global_load_lds_dwordx4 v[224:225], off
	s_waitcnt vmcnt(8)
	s_waitcnt lgkmcnt(0)
	s_setprio 1
	s_barrier
	v_mfma_f32_16x16x32_bf16 v[60:63], v[154:157], v[186:189], v[60:63]
	v_mfma_f32_16x16x32_bf16 v[56:59], v[162:165], v[186:189], v[56:59]
	v_mfma_f32_16x16x32_bf16 v[52:55], v[154:157], v[198:201], v[52:55]
	v_mfma_f32_16x16x32_bf16 v[44:47], v[162:165], v[198:201], v[44:47]
	v_mfma_f32_16x16x32_bf16 v[36:39], v[154:157], v[206:209], v[36:39]
	v_mfma_f32_16x16x32_bf16 v[28:31], v[162:165], v[206:209], v[28:31]
	v_mfma_f32_16x16x32_bf16 v[20:23], v[154:157], v[214:217], v[20:23]
	v_mfma_f32_16x16x32_bf16 v[12:15], v[162:165], v[214:217], v[12:15]
	v_mfma_f32_16x16x32_bf16 v[60:63], v[158:161], v[194:197], v[60:63]
	v_mfma_f32_16x16x32_bf16 v[56:59], v[166:169], v[194:197], v[56:59]
	v_mfma_f32_16x16x32_bf16 v[52:55], v[158:161], v[202:205], v[52:55]
	v_mfma_f32_16x16x32_bf16 v[44:47], v[166:169], v[202:205], v[44:47]
	v_mfma_f32_16x16x32_bf16 v[36:39], v[158:161], v[210:213], v[36:39]
	v_mfma_f32_16x16x32_bf16 v[28:31], v[166:169], v[210:213], v[28:31]
	v_mfma_f32_16x16x32_bf16 v[20:23], v[158:161], v[218:221], v[20:23]
	v_mfma_f32_16x16x32_bf16 v[12:15], v[166:169], v[218:221], v[12:15]
	v_mfma_f32_16x16x32_bf16 v[48:51], v[170:173], v[186:189], v[48:51]
	v_mfma_f32_16x16x32_bf16 v[40:43], v[178:181], v[186:189], v[40:43]
	v_mfma_f32_16x16x32_bf16 v[32:35], v[170:173], v[198:201], v[32:35]
	v_mfma_f32_16x16x32_bf16 v[24:27], v[178:181], v[198:201], v[24:27]
	v_mfma_f32_16x16x32_bf16 v[16:19], v[170:173], v[206:209], v[16:19]
	v_mfma_f32_16x16x32_bf16 v[8:11], v[178:181], v[206:209], v[8:11]
	v_mfma_f32_16x16x32_bf16 v[4:7], v[170:173], v[214:217], v[4:7]
	v_mfma_f32_16x16x32_bf16 v[0:3], v[178:181], v[214:217], v[0:3]
	v_mfma_f32_16x16x32_bf16 v[48:51], v[174:177], v[194:197], v[48:51]
	v_mfma_f32_16x16x32_bf16 v[40:43], v[182:185], v[194:197], v[40:43]
	v_mfma_f32_16x16x32_bf16 v[32:35], v[174:177], v[202:205], v[32:35]
	v_mfma_f32_16x16x32_bf16 v[24:27], v[182:185], v[202:205], v[24:27]
	v_mfma_f32_16x16x32_bf16 v[16:19], v[174:177], v[210:213], v[16:19]
	v_mfma_f32_16x16x32_bf16 v[8:11], v[182:185], v[210:213], v[8:11]
	v_mfma_f32_16x16x32_bf16 v[4:7], v[174:177], v[218:221], v[4:7]
	v_mfma_f32_16x16x32_bf16 v[0:3], v[182:185], v[218:221], v[0:3]
	s_barrier
; #define PG8_STAGE(bufoff, gbase, voff) do { _Pragma("unroll") for (int _i = 0; _i < 2; ++_i) \
;         __builtin_amdgcn_global_load_lds((const unsigned*)((const char*)(gbase) + (voff)[_i]), (LAS unsigned*)(lds + (bufoff) + ldsw + _i * 8192), 16, 0, 0); } while (0)
; #define PG8_LDA(dst, b, h) do { _Pragma("unroll") for (int m = 0; m < 4; ++m) _Pragma("unroll") for (int k = 0; k < 2; ++k) dst[m][k] = *(const LAS bf16x8*)(lds + PG8_SA(b, h) + aoff + m * 2048 + k * 1024); } while (0)
; #define PG8_LDB(dst, b, h) do { _Pragma("unroll") for (int n = 0; n < 2; ++n) _Pragma("unroll") for (int k = 0; k < 2; ++k) dst[n][k] = *(const LAS bf16x8*)(lds + PG8_SB(b, h) + boff + n * 2048 + k * 1024); } while (0)
; #define PG8_MMA(ai, bj, At, Bt) do { __builtin_amdgcn_s_setprio(1); _Pragma("unroll") for (int m = 0; m < 4; ++m) _Pragma("unroll") for (int n = 0; n < 2; ++n) _Pragma("unroll") for (int k = 0; k < 2; ++k) \
;         acc[ai][bj][m][n] = __builtin_amdgcn_mfma_f32_16x16x32_bf16(Bt[n][k], At[m][k], acc[ai][bj][m][n], 0, 0, 0); __builtin_amdgcn_s_setprio(0); } while (0)
; #define PG8_WAIT_V(n) asm volatile("s_waitcnt vmcnt(" #n ")" ::: "memory")
; #define PG8_WAIT_L(n) asm volatile("s_waitcnt lgkmcnt(" #n ")" ::: "memory")
; #define PG8_BAR __builtin_amdgcn_s_barrier()
; #define PG8_SCHED __builtin_amdgcn_sched_barrier(0)
; template <class Epi, class Sched = StaticOrder, class EpiSub = NoSub, bool FAST = false>
; __device__ __forceinline__ void gemm_phase(LAS unsigned char* lds, const Gemm g, const Sched& S, const Epi& E, const EpiSub& ES = EpiSub()) {
;     ...
;             PG8_LDB(B0, 1, 0); PG8_LDB(B1, 1, 1); PG8_SCHED; PG8_LDA(At, 1, 0); PG8_STAGE(PG8_SA(0, 1), a2 + hstepA, voffA);
;             PG8_WAIT_V(8); PG8_WAIT_L(0); PG8_BAR; PG8_MMA(0, 0, At, B0); PG8_MMA(0, 1, At, B1); PG8_BAR; PG8_SCHED;
	s_setprio 0
	s_add_i32 s51, 0, 0x18000
	v_add_u32_e32 v153, s51, v148
	s_add_i32 s68, 0, 0x1c000
	ds_read_b128 v[154:157], v153
	ds_read_b128 v[158:161], v153 offset:1024
	ds_read_b128 v[162:165], v153 offset:2048
	ds_read_b128 v[166:169], v153 offset:3072
	v_add_u32_e32 v153, s68, v148
	ds_read_b128 v[170:173], v153
	ds_read_b128 v[174:177], v153 offset:1024
	ds_read_b128 v[178:181], v153 offset:2048
	ds_read_b128 v[182:185], v153 offset:3072
	s_add_u32 s26, s26, 0x80000
	s_addc_u32 s27, s27, 0
	s_mov_b32 m0, s35
	v_lshl_add_u64 v[226:227], s[26:27], 0, v[128:129]
	ds_read_b128 v[186:189], v152 offset:32768
	ds_read_b128 v[194:197], v152 offset:33792
	ds_read_b128 v[198:201], v152 offset:34816
	ds_read_b128 v[202:205], v152 offset:35840
	ds_read_b128 v[206:209], v152 offset:36864
	ds_read_b128 v[210:213], v152 offset:37888
	ds_read_b128 v[214:217], v152 offset:38912
	ds_read_b128 v[218:221], v152 offset:39936
	global_load_lds_dwordx4 v[226:227], off
	v_lshl_add_u64 v[226:227], s[26:27], 0, v[132:133]
	s_mov_b32 m0, s36
	s_nop 0
	global_load_lds_dwordx4 v[226:227], off
	s_waitcnt vmcnt(8)
	s_waitcnt lgkmcnt(0)
	s_setprio 1
	s_barrier
	v_mfma_f32_16x16x32_bf16 v[124:127], v[154:157], v[186:189], v[124:127]
	v_mfma_f32_16x16x32_bf16 v[120:123], v[162:165], v[186:189], v[120:123]
	v_mfma_f32_16x16x32_bf16 v[116:119], v[154:157], v[198:201], v[116:119]
	v_mfma_f32_16x16x32_bf16 v[108:111], v[162:165], v[198:201], v[108:111]
	v_mfma_f32_16x16x32_bf16 v[100:103], v[154:157], v[206:209], v[100:103]
	v_mfma_f32_16x16x32_bf16 v[92:95], v[162:165], v[206:209], v[92:95]
	v_mfma_f32_16x16x32_bf16 v[84:87], v[154:157], v[214:217], v[84:87]
	v_mfma_f32_16x16x32_bf16 v[76:79], v[162:165], v[214:217], v[76:79]
	v_mfma_f32_16x16x32_bf16 v[124:127], v[158:161], v[194:197], v[124:127]
	v_mfma_f32_16x16x32_bf16 v[120:123], v[166:169], v[194:197], v[120:123]
	v_mfma_f32_16x16x32_bf16 v[116:119], v[158:161], v[202:205], v[116:119]
	v_mfma_f32_16x16x32_bf16 v[108:111], v[166:169], v[202:205], v[108:111]
	v_mfma_f32_16x16x32_bf16 v[100:103], v[158:161], v[210:213], v[100:103]
	v_mfma_f32_16x16x32_bf16 v[92:95], v[166:169], v[210:213], v[92:95]
	v_mfma_f32_16x16x32_bf16 v[84:87], v[158:161], v[218:221], v[84:87]
	v_mfma_f32_16x16x32_bf16 v[76:79], v[166:169], v[218:221], v[76:79]
	v_mfma_f32_16x16x32_bf16 v[112:115], v[170:173], v[186:189], v[112:115]
	v_mfma_f32_16x16x32_bf16 v[104:107], v[178:181], v[186:189], v[104:107]
	v_mfma_f32_16x16x32_bf16 v[96:99], v[170:173], v[198:201], v[96:99]
	v_mfma_f32_16x16x32_bf16 v[88:91], v[178:181], v[198:201], v[88:91]
	v_mfma_f32_16x16x32_bf16 v[80:83], v[170:173], v[206:209], v[80:83]
	v_mfma_f32_16x16x32_bf16 v[72:75], v[178:181], v[206:209], v[72:75]
	v_mfma_f32_16x16x32_bf16 v[68:71], v[170:173], v[214:217], v[68:71]
	v_mfma_f32_16x16x32_bf16 v[64:67], v[178:181], v[214:217], v[64:67]
	v_mfma_f32_16x16x32_bf16 v[112:115], v[174:177], v[194:197], v[112:115]
	v_mfma_f32_16x16x32_bf16 v[104:107], v[182:185], v[194:197], v[104:107]
	v_mfma_f32_16x16x32_bf16 v[96:99], v[174:177], v[202:205], v[96:99]
	v_mfma_f32_16x16x32_bf16 v[88:91], v[182:185], v[202:205], v[88:91]
	v_mfma_f32_16x16x32_bf16 v[80:83], v[174:177], v[210:213], v[80:83]
	v_mfma_f32_16x16x32_bf16 v[72:75], v[182:185], v[210:213], v[72:75]
	v_mfma_f32_16x16x32_bf16 v[68:71], v[174:177], v[218:221], v[68:71]
	v_mfma_f32_16x16x32_bf16 v[64:67], v[182:185], v[218:221], v[64:67]
	s_barrier
; #define PG8_STAGE(bufoff, gbase, voff) do { _Pragma("unroll") for (int _i = 0; _i < 2; ++_i) \
;         __builtin_amdgcn_global_load_lds((const unsigned*)((const char*)(gbase) + (voff)[_i]), (LAS unsigned*)(lds + (bufoff) + ldsw + _i * 8192), 16, 0, 0); } while (0)
; #define PG8_LDA(dst, b, h) do { _Pragma("unroll") for (int m = 0; m < 4; ++m) _Pragma("unroll") for (int k = 0; k < 2; ++k) dst[m][k] = *(const LAS bf16x8*)(lds + PG8_SA(b, h) + aoff + m * 2048 + k * 1024); } while (0)
; #define PG8_MMA(ai, bj, At, Bt) do { __builtin_amdgcn_s_setprio(1); _Pragma("unroll") for (int m = 0; m < 4; ++m) _Pragma("unroll") for (int n = 0; n < 2; ++n) _Pragma("unroll") for (int k = 0; k < 2; ++k) \
;         acc[ai][bj][m][n] = __builtin_amdgcn_mfma_f32_16x16x32_bf16(Bt[n][k], At[m][k], acc[ai][bj][m][n], 0, 0, 0); __builtin_amdgcn_s_setprio(0); } while (0)
; #define PG8_WAIT_V(n) asm volatile("s_waitcnt vmcnt(" #n ")" ::: "memory")
; #define PG8_WAIT_L(n) asm volatile("s_waitcnt lgkmcnt(" #n ")" ::: "memory")
; #define PG8_BAR __builtin_amdgcn_s_barrier()
; #define PG8_SCHED __builtin_amdgcn_sched_barrier(0)
; template <class Epi, class Sched = StaticOrder, class EpiSub = NoSub, bool FAST = false>
; __device__ __forceinline__ void gemm_phase(LAS unsigned char* lds, const Gemm g, const Sched& S, const Epi& E, const EpiSub& ES = EpiSub()) {
;     ...
;             PG8_LDA(At, 1, 1); PG8_STAGE(PG8_SB(1, 0), b3, voffB); PG8_STAGE(PG8_SB(1, 1), b3 + hstepB, voffB); PG8_STAGE(PG8_SA(1, 0), a3, voffA);
;             PG8_WAIT_V(8); PG8_WAIT_L(0); PG8_BAR; PG8_MMA(1, 0, At, B0); PG8_MMA(1, 1, At, B1); PG8_BAR; PG8_SCHED;
;     ...
;         if constexpr (FAST && PG8_ALIGN) { if (wr == 0) PG8_BAR; }
	s_setprio 0
	s_add_i32 s26, s51, s30
	v_lshl_add_u64 v[144:145], v[144:145], 0, s[8:9]
	s_mov_b32 m0, s26
	ds_read_b128 v[186:189], v152 offset:49152
	ds_read_b128 v[194:197], v152 offset:50176
	ds_read_b128 v[198:201], v152 offset:51200
	ds_read_b128 v[202:205], v152 offset:52224
	ds_read_b128 v[206:209], v152 offset:53248
	ds_read_b128 v[210:213], v152 offset:54272
	ds_read_b128 v[214:217], v152 offset:55296
	ds_read_b128 v[218:221], v152 offset:56320
	global_load_lds_dwordx4 v[144:145], off
	s_add_i32 m0, s26, 0x2000
	s_add_u32 s24, s24, 0x80080
	v_lshl_add_u64 v[144:145], v[190:191], 0, s[8:9]
	s_addc_u32 s25, s25, 0
	s_add_i32 s26, s68, s30
	global_load_lds_dwordx4 v[144:145], off
	v_lshl_add_u64 v[144:145], s[24:25], 0, v[130:131]
	s_mov_b32 m0, s26
	s_nop 0
	global_load_lds_dwordx4 v[144:145], off
	v_lshl_add_u64 v[144:145], s[24:25], 0, v[134:135]
	s_add_i32 m0, s26, 0x2000
	s_nop 0
	global_load_lds_dwordx4 v[144:145], off
	v_lshl_add_u64 v[144:145], v[222:223], 0, s[8:9]
	s_mov_b32 m0, s39
	s_nop 0
	global_load_lds_dwordx4 v[144:145], off
	v_lshl_add_u64 v[144:145], v[224:225], 0, s[8:9]
	s_mov_b32 m0, s40
	s_nop 0
	global_load_lds_dwordx4 v[144:145], off
	s_waitcnt vmcnt(8)
	s_waitcnt lgkmcnt(0)
	s_setprio 1
	s_barrier
	v_mfma_f32_16x16x32_bf16 v[60:63], v[154:157], v[186:189], v[60:63]
	v_mfma_f32_16x16x32_bf16 v[56:59], v[162:165], v[186:189], v[56:59]
	v_mfma_f32_16x16x32_bf16 v[52:55], v[154:157], v[198:201], v[52:55]
	v_mfma_f32_16x16x32_bf16 v[44:47], v[162:165], v[198:201], v[44:47]
	v_mfma_f32_16x16x32_bf16 v[36:39], v[154:157], v[206:209], v[36:39]
	v_mfma_f32_16x16x32_bf16 v[28:31], v[162:165], v[206:209], v[28:31]
	v_mfma_f32_16x16x32_bf16 v[20:23], v[154:157], v[214:217], v[20:23]
	v_mfma_f32_16x16x32_bf16 v[12:15], v[162:165], v[214:217], v[12:15]
	v_mfma_f32_16x16x32_bf16 v[60:63], v[158:161], v[194:197], v[60:63]
	v_mfma_f32_16x16x32_bf16 v[56:59], v[166:169], v[194:197], v[56:59]
	v_mfma_f32_16x16x32_bf16 v[52:55], v[158:161], v[202:205], v[52:55]
	v_mfma_f32_16x16x32_bf16 v[44:47], v[166:169], v[202:205], v[44:47]
	v_mfma_f32_16x16x32_bf16 v[36:39], v[158:161], v[210:213], v[36:39]
	v_mfma_f32_16x16x32_bf16 v[28:31], v[166:169], v[210:213], v[28:31]
	v_mfma_f32_16x16x32_bf16 v[20:23], v[158:161], v[218:221], v[20:23]
	v_mfma_f32_16x16x32_bf16 v[12:15], v[166:169], v[218:221], v[12:15]
	v_mfma_f32_16x16x32_bf16 v[48:51], v[170:173], v[186:189], v[48:51]
	v_mfma_f32_16x16x32_bf16 v[40:43], v[178:181], v[186:189], v[40:43]
	v_mfma_f32_16x16x32_bf16 v[32:35], v[170:173], v[198:201], v[32:35]
	v_mfma_f32_16x16x32_bf16 v[24:27], v[178:181], v[198:201], v[24:27]
	v_mfma_f32_16x16x32_bf16 v[16:19], v[170:173], v[206:209], v[16:19]
	v_mfma_f32_16x16x32_bf16 v[8:11], v[178:181], v[206:209], v[8:11]
	v_mfma_f32_16x16x32_bf16 v[4:7], v[170:173], v[214:217], v[4:7]
	v_mfma_f32_16x16x32_bf16 v[0:3], v[178:181], v[214:217], v[0:3]
	v_mfma_f32_16x16x32_bf16 v[48:51], v[174:177], v[194:197], v[48:51]
	v_mfma_f32_16x16x32_bf16 v[40:43], v[182:185], v[194:197], v[40:43]
	v_mfma_f32_16x16x32_bf16 v[32:35], v[174:177], v[202:205], v[32:35]
	v_mfma_f32_16x16x32_bf16 v[24:27], v[182:185], v[202:205], v[24:27]
	v_mfma_f32_16x16x32_bf16 v[16:19], v[174:177], v[210:213], v[16:19]
	v_mfma_f32_16x16x32_bf16 v[8:11], v[182:185], v[210:213], v[8:11]
	v_mfma_f32_16x16x32_bf16 v[4:7], v[174:177], v[218:221], v[4:7]
	v_mfma_f32_16x16x32_bf16 v[0:3], v[182:185], v[218:221], v[0:3]
	s_barrier
	s_setprio 0
	s_add_i32 s50, s50, 2
	s_add_u32 s22, s22, 0x100
	s_addc_u32 s23, s23, 0
	s_add_u32 s48, s48, 0x100
	s_addc_u32 s49, s49, 0
	s_cmp_gt_u32 s50, 29
	s_cbranch_scc0 .LBB0_216
.Lkpeel_216_exit:
	s_and_b64 vcc, exec, s[10:11]
	s_cbranch_vccz .LBB0_219
	s_barrier

; #define PG8_STAGE(bufoff, gbase, voff) do { _Pragma("unroll") for (int _i = 0; _i < 2; ++_i) \
;         __builtin_amdgcn_global_load_lds((const unsigned*)((const char*)(gbase) + (voff)[_i]), (LAS unsigned*)(lds + (bufoff) + ldsw + _i * 8192), 16, 0, 0); } while (0)
; #define PG8_LDA(dst, b, h) do { _Pragma("unroll") for (int m = 0; m < 4; ++m) _Pragma("unroll") for (int k = 0; k < 2; ++k) dst[m][k] = *(const LAS bf16x8*)(lds + PG8_SA(b, h) + aoff + m * 2048 + k * 1024); } while (0)
; #define PG8_LDB(dst, b, h) do { _Pragma("unroll") for (int n = 0; n < 2; ++n) _Pragma("unroll") for (int k = 0; k < 2; ++k) dst[n][k] = *(const LAS bf16x8*)(lds + PG8_SB(b, h) + boff + n * 2048 + k * 1024); } while (0)
; #define PG8_WAIT_V(n) asm volatile("s_waitcnt vmcnt(" #n ")" ::: "memory")
; #define PG8_WAIT_L(n) asm volatile("s_waitcnt lgkmcnt(" #n ")" ::: "memory")
; #define PG8_BAR __builtin_amdgcn_s_barrier()
; #define PG8_SCHED __builtin_amdgcn_sched_barrier(0)
; template <class Epi, class Sched = StaticOrder, class EpiSub = NoSub, bool FAST = false>
; __device__ __forceinline__ void gemm_phase(LAS unsigned char* lds, const Gemm g, const Sched& S, const Epi& E, const EpiSub& ES = EpiSub()) {
;     ...
;         const bool has_next = S.next(ui + 1, nxt);
;         const size_t nko = (has_next && nxt.kb >= 0) ? nxt.kb * ksubB : 0;
;         const char* nA = has_next ? (const char*)g.A + (size_t)nxt.pm * tstepA + (size_t)nxt.pn * g.acs + nko : cA; const char* nB = has_next ? (const char*)g.Bt + (size_t)nxt.pn * tstepB + nko : cB;
;         const int nt = cur.kb < 0 ? ntMain : ntSub;
;         for (int t = 0; t < nt; t += 2) {
;             const bool last = (t == nt - 2);
;             const char* a1 = cA + (size_t)(t + 1) * kstep;
;             const char* a2 = last ? nA : cA + (size_t)(t + 2) * kstep; const char* b2 = last ? nB : cB + (size_t)(t + 2) * kstep;
;             const char* a3 = a2 + kstep; const char* b3 = b2 + kstep;
;             if constexpr (FAST && PG8_SP2) {
;             PG8_LDB(B0, 0, 0); PG8_LDB(B1, 0, 1); PG8_SCHED; PG8_LDA(At, 0, 0); PG8_STAGE(PG8_SA(1, 1), a1 + hstepA, voffA);
;             PG8_WAIT_V(8); PG8_WAIT_L(0); PG8_BAR; PG8_MMA(0, 0, At, B0); PG8_MMA(0, 1, At, B1); PG8_BAR; PG8_SCHED;
;             PG8_LDA(At, 0, 1); PG8_STAGE(PG8_SB(0, 0), b2, voffB); PG8_STAGE(PG8_SB(0, 1), b2 + hstepB, voffB); PG8_STAGE(PG8_SA(0, 0), a2, voffA);
.LBB0_599:
	s_cmp_gt_i32 s8, -1
	s_cselect_b64 s[30:31], -1, 0
	s_and_b64 s[30:31], s[28:29], s[30:31]
	s_lshl_b64 s[36:37], s[8:9], 9
	s_and_b64 s[30:31], s[30:31], exec
	s_cselect_b32 s7, s37, 0
	s_cselect_b32 s33, s36, 0
	s_ashr_i32 s27, s26, 31
	s_lshl_b64 s[30:31], s[26:27], 19
	s_add_u32 s1, s78, s30
	s_addc_u32 s5, s79, s31
	s_add_u32 s30, s1, s33
	s_addc_u32 s31, s5, s7
	s_and_b64 s[36:37], s[28:29], exec
	s_cselect_b32 s1, s31, s41
	s_cselect_b32 s5, s30, s40
	s_ashr_i32 s25, s24, 31
	s_lshl_b64 s[36:37], s[24:25], 19
	s_add_u32 s25, s2, s36
	s_addc_u32 s27, s3, s37
	s_add_u32 s36, s25, s33
	s_addc_u32 s37, s27, s7
	s_and_b64 s[38:39], s[28:29], exec
	s_cselect_b32 s7, s37, s43
	s_cselect_b32 s25, s36, s42
	s_cmp_gt_i32 s0, -1
	s_cselect_b64 s[38:39], -1, 0
	s_cmp_lt_i32 s0, 0
	s_cselect_b32 s27, 16, 4
	s_add_i32 s33, s27, -2
	s_add_u32 s40, s40, 0x40080
	s_addc_u32 s41, s41, 0
	s_add_u32 s48, s42, 0x100
	s_mov_b32 s50, 0
	s_addc_u32 s49, s43, 0
	ds_read_b128 v[100:103], v186
	ds_read_b128 v[112:115], v186 offset:1024
	ds_read_b128 v[124:127], v186 offset:2048
	ds_read_b128 v[136:139], v186 offset:3072
	ds_read_b128 v[144:147], v187
	ds_read_b128 v[148:151], v187 offset:1024
	ds_read_b128 v[152:155], v187 offset:2048
	ds_read_b128 v[170:173], v187 offset:3072
	s_add_i32 s51, s50, 2
	s_add_u32 s42, s40, 0xfffc0080
	s_addc_u32 s43, s41, -1
	s_cmp_eq_u32 s33, s50
	s_cselect_b32 s53, s1, s43
	s_cselect_b32 s52, s5, s42
	s_cselect_b32 s43, s7, s49
	s_cselect_b32 s42, s25, s48
	v_lshl_add_u64 v[190:191], s[40:41], 0, v[164:165]
	s_add_i32 m0, s55, 0xc000
	ds_read_b128 v[174:177], v188
	ds_read_b128 v[178:181], v188 offset:1024
	ds_read_b128 v[194:197], v188 offset:2048
	ds_read_b128 v[198:201], v188 offset:3072
	ds_read_b128 v[202:205], v188 offset:4096
	ds_read_b128 v[206:209], v188 offset:5120
	ds_read_b128 v[210:213], v188 offset:6144
	ds_read_b128 v[214:217], v188 offset:7168
	global_load_lds_dwordx4 v[190:191], off
	v_lshl_add_u64 v[190:191], s[40:41], 0, v[166:167]
	s_add_i32 m0, s55, 0xe000
	s_nop 0
	global_load_lds_dwordx4 v[190:191], off
	s_waitcnt vmcnt(8)
	s_waitcnt lgkmcnt(0)
	s_setprio 1
	s_barrier
	v_mfma_f32_16x16x32_bf16 v[140:143], v[100:103], v[174:177], 0
	v_mfma_f32_16x16x32_bf16 v[132:135], v[124:127], v[174:177], 0
	v_mfma_f32_16x16x32_bf16 v[116:119], v[100:103], v[194:197], 0
	v_mfma_f32_16x16x32_bf16 v[108:111], v[124:127], v[194:197], 0
	v_mfma_f32_16x16x32_bf16 v[92:95], v[100:103], v[202:205], 0
	v_mfma_f32_16x16x32_bf16 v[88:91], v[124:127], v[202:205], 0
	v_mfma_f32_16x16x32_bf16 v[76:79], v[100:103], v[210:213], 0
	v_mfma_f32_16x16x32_bf16 v[72:75], v[124:127], v[210:213], 0
	v_mfma_f32_16x16x32_bf16 v[140:143], v[112:115], v[178:181], v[140:143]
	v_mfma_f32_16x16x32_bf16 v[132:135], v[136:139], v[178:181], v[132:135]
	v_mfma_f32_16x16x32_bf16 v[116:119], v[112:115], v[198:201], v[116:119]
	v_mfma_f32_16x16x32_bf16 v[108:111], v[136:139], v[198:201], v[108:111]
	v_mfma_f32_16x16x32_bf16 v[92:95], v[112:115], v[206:209], v[92:95]
	v_mfma_f32_16x16x32_bf16 v[88:91], v[136:139], v[206:209], v[88:91]
	v_mfma_f32_16x16x32_bf16 v[76:79], v[112:115], v[214:217], v[76:79]
	v_mfma_f32_16x16x32_bf16 v[72:75], v[136:139], v[214:217], v[72:75]
	v_mfma_f32_16x16x32_bf16 v[128:131], v[144:147], v[174:177], 0
	v_mfma_f32_16x16x32_bf16 v[120:123], v[152:155], v[174:177], 0
	v_mfma_f32_16x16x32_bf16 v[104:107], v[144:147], v[194:197], 0
	v_mfma_f32_16x16x32_bf16 v[96:99], v[152:155], v[194:197], 0
	v_mfma_f32_16x16x32_bf16 v[84:87], v[144:147], v[202:205], 0
	v_mfma_f32_16x16x32_bf16 v[80:83], v[152:155], v[202:205], 0
	v_mfma_f32_16x16x32_bf16 v[68:71], v[144:147], v[210:213], 0
	v_mfma_f32_16x16x32_bf16 v[64:67], v[152:155], v[210:213], 0
	v_mfma_f32_16x16x32_bf16 v[128:131], v[148:151], v[178:181], v[128:131]
	v_mfma_f32_16x16x32_bf16 v[120:123], v[170:173], v[178:181], v[120:123]
	v_mfma_f32_16x16x32_bf16 v[104:107], v[148:151], v[198:201], v[104:107]
	v_mfma_f32_16x16x32_bf16 v[96:99], v[170:173], v[198:201], v[96:99]
	v_mfma_f32_16x16x32_bf16 v[84:87], v[148:151], v[206:209], v[84:87]
	v_mfma_f32_16x16x32_bf16 v[80:83], v[170:173], v[206:209], v[80:83]
	v_mfma_f32_16x16x32_bf16 v[68:71], v[148:151], v[214:217], v[68:71]
	v_mfma_f32_16x16x32_bf16 v[64:67], v[170:173], v[214:217], v[64:67]
	s_barrier
	s_setprio 0
	s_add_i32 s50, s75, s54
	v_lshl_add_u64 v[190:191], s[42:43], 0, v[158:159]
	s_mov_b32 m0, s50
	ds_read_b128 v[174:177], v188 offset:16384
	ds_read_b128 v[178:181], v188 offset:17408
	ds_read_b128 v[194:197], v188 offset:18432
	ds_read_b128 v[198:201], v188 offset:19456
	ds_read_b128 v[202:205], v188 offset:20480
	ds_read_b128 v[206:209], v188 offset:21504
	ds_read_b128 v[210:213], v188 offset:22528
	ds_read_b128 v[214:217], v188 offset:23552
	global_load_lds_dwordx4 v[190:191], off
	s_add_i32 m0, s50, 0x2000
	s_add_u32 s70, s42, 0x40000
	v_lshl_add_u64 v[218:219], s[42:43], 0, v[162:163]
	s_addc_u32 s71, s43, 0
	s_add_i32 s50, s80, s54
	global_load_lds_dwordx4 v[218:219], off
	v_lshl_add_u64 v[220:221], s[70:71], 0, v[158:159]
	s_mov_b32 m0, s50
	v_lshl_add_u64 v[222:223], s[52:53], 0, v[160:161]
	global_load_lds_dwordx4 v[220:221], off
	v_lshl_add_u64 v[220:221], s[70:71], 0, v[162:163]
	s_add_i32 m0, s50, 0x2000
	s_nop 0
	global_load_lds_dwordx4 v[220:221], off
	v_lshl_add_u64 v[220:221], s[52:53], 0, v[156:157]
	s_mov_b32 m0, s55
	s_nop 0
	global_load_lds_dwordx4 v[220:221], off
	s_mov_b32 m0, s56
	s_nop 0
	global_load_lds_dwordx4 v[222:223], off
	s_waitcnt vmcnt(8)
	s_waitcnt lgkmcnt(0)
	s_setprio 1
	s_barrier
; #define PG8_STAGE(bufoff, gbase, voff) do { _Pragma("unroll") for (int _i = 0; _i < 2; ++_i) \
;         __builtin_amdgcn_global_load_lds((const unsigned*)((const char*)(gbase) + (voff)[_i]), (LAS unsigned*)(lds + (bufoff) + ldsw + _i * 8192), 16, 0, 0); } while (0)
; #define PG8_LDA(dst, b, h) do { _Pragma("unroll") for (int m = 0; m < 4; ++m) _Pragma("unroll") for (int k = 0; k < 2; ++k) dst[m][k] = *(const LAS bf16x8*)(lds + PG8_SA(b, h) + aoff + m * 2048 + k * 1024); } while (0)
; #define PG8_LDB(dst, b, h) do { _Pragma("unroll") for (int n = 0; n < 2; ++n) _Pragma("unroll") for (int k = 0; k < 2; ++k) dst[n][k] = *(const LAS bf16x8*)(lds + PG8_SB(b, h) + boff + n * 2048 + k * 1024); } while (0)
; #define PG8_MMA(ai, bj, At, Bt) do { __builtin_amdgcn_s_setprio(1); _Pragma("unroll") for (int m = 0; m < 4; ++m) _Pragma("unroll") for (int n = 0; n < 2; ++n) _Pragma("unroll") for (int k = 0; k < 2; ++k) \
;         acc[ai][bj][m][n] = __builtin_amdgcn_mfma_f32_16x16x32_bf16(Bt[n][k], At[m][k], acc[ai][bj][m][n], 0, 0, 0); __builtin_amdgcn_s_setprio(0); } while (0)
; #define PG8_WAIT_V(n) asm volatile("s_waitcnt vmcnt(" #n ")" ::: "memory")
; #define PG8_WAIT_L(n) asm volatile("s_waitcnt lgkmcnt(" #n ")" ::: "memory")
; #define PG8_BAR __builtin_amdgcn_s_barrier()
; #define PG8_SCHED __builtin_amdgcn_sched_barrier(0)
; template <class Epi, class Sched = StaticOrder, class EpiSub = NoSub, bool FAST = false>
; __device__ __forceinline__ void gemm_phase(LAS unsigned char* lds, const Gemm g, const Sched& S, const Epi& E, const EpiSub& ES = EpiSub()) {
;     ...
;             PG8_WAIT_V(8); PG8_WAIT_L(0); PG8_BAR; PG8_MMA(1, 0, At, B0); PG8_MMA(1, 1, At, B1); PG8_BAR; PG8_SCHED;
;             PG8_LDB(B0, 1, 0); PG8_LDB(B1, 1, 1); PG8_SCHED; PG8_LDA(At, 1, 0); PG8_STAGE(PG8_SA(0, 1), a2 + hstepA, voffA);
;             PG8_WAIT_V(8); PG8_WAIT_L(0); PG8_BAR; PG8_MMA(0, 0, At, B0); PG8_MMA(0, 1, At, B1); PG8_BAR; PG8_SCHED;
	v_mfma_f32_16x16x32_bf16 v[60:63], v[100:103], v[174:177], 0
	v_mfma_f32_16x16x32_bf16 v[56:59], v[124:127], v[174:177], 0
	v_mfma_f32_16x16x32_bf16 v[44:47], v[100:103], v[194:197], 0
	v_mfma_f32_16x16x32_bf16 v[40:43], v[124:127], v[194:197], 0
	v_mfma_f32_16x16x32_bf16 v[28:31], v[100:103], v[202:205], 0
	v_mfma_f32_16x16x32_bf16 v[24:27], v[124:127], v[202:205], 0
	v_mfma_f32_16x16x32_bf16 v[12:15], v[100:103], v[210:213], 0
	v_mfma_f32_16x16x32_bf16 v[8:11], v[124:127], v[210:213], 0
	v_mfma_f32_16x16x32_bf16 v[60:63], v[112:115], v[178:181], v[60:63]
	v_mfma_f32_16x16x32_bf16 v[56:59], v[136:139], v[178:181], v[56:59]
	v_mfma_f32_16x16x32_bf16 v[44:47], v[112:115], v[198:201], v[44:47]
	v_mfma_f32_16x16x32_bf16 v[40:43], v[136:139], v[198:201], v[40:43]
	v_mfma_f32_16x16x32_bf16 v[28:31], v[112:115], v[206:209], v[28:31]
	v_mfma_f32_16x16x32_bf16 v[24:27], v[136:139], v[206:209], v[24:27]
	v_mfma_f32_16x16x32_bf16 v[12:15], v[112:115], v[214:217], v[12:15]
	v_mfma_f32_16x16x32_bf16 v[8:11], v[136:139], v[214:217], v[8:11]
	v_mfma_f32_16x16x32_bf16 v[52:55], v[144:147], v[174:177], 0
	v_mfma_f32_16x16x32_bf16 v[48:51], v[152:155], v[174:177], 0
	v_mfma_f32_16x16x32_bf16 v[36:39], v[144:147], v[194:197], 0
	v_mfma_f32_16x16x32_bf16 v[32:35], v[152:155], v[194:197], 0
	v_mfma_f32_16x16x32_bf16 v[20:23], v[144:147], v[202:205], 0
	v_mfma_f32_16x16x32_bf16 v[16:19], v[152:155], v[202:205], 0
	v_mfma_f32_16x16x32_bf16 v[4:7], v[144:147], v[210:213], 0
	v_mfma_f32_16x16x32_bf16 v[0:3], v[152:155], v[210:213], 0
	v_mfma_f32_16x16x32_bf16 v[52:55], v[148:151], v[178:181], v[52:55]
	v_mfma_f32_16x16x32_bf16 v[48:51], v[170:173], v[178:181], v[48:51]
	v_mfma_f32_16x16x32_bf16 v[36:39], v[148:151], v[198:201], v[36:39]
	v_mfma_f32_16x16x32_bf16 v[32:35], v[170:173], v[198:201], v[32:35]
	v_mfma_f32_16x16x32_bf16 v[20:23], v[148:151], v[206:209], v[20:23]
	v_mfma_f32_16x16x32_bf16 v[16:19], v[170:173], v[206:209], v[16:19]
	v_mfma_f32_16x16x32_bf16 v[4:7], v[148:151], v[214:217], v[4:7]
	v_mfma_f32_16x16x32_bf16 v[0:3], v[170:173], v[214:217], v[0:3]
	s_barrier
	s_setprio 0
	s_add_i32 s50, 0, 0x18000
	s_add_i32 s70, 0, 0x1c000
	v_add_u32_e32 v136, s50, v183
	v_add_u32_e32 v170, s70, v183
	ds_read_b128 v[100:103], v136
	ds_read_b128 v[112:115], v136 offset:1024
	ds_read_b128 v[124:127], v136 offset:2048
	ds_read_b128 v[136:139], v136 offset:3072
	ds_read_b128 v[144:147], v170
	ds_read_b128 v[148:151], v170 offset:1024
	ds_read_b128 v[152:155], v170 offset:2048
	ds_read_b128 v[170:173], v170 offset:3072
	s_add_u32 s52, s52, 0x40000
	s_addc_u32 s53, s53, 0
	s_mov_b32 m0, s57
	v_lshl_add_u64 v[224:225], s[52:53], 0, v[156:157]
	ds_read_b128 v[174:177], v188 offset:32768
	ds_read_b128 v[178:181], v188 offset:33792
	ds_read_b128 v[194:197], v188 offset:34816
	ds_read_b128 v[198:201], v188 offset:35840
	ds_read_b128 v[202:205], v188 offset:36864
	ds_read_b128 v[206:209], v188 offset:37888
	ds_read_b128 v[210:213], v188 offset:38912
	ds_read_b128 v[214:217], v188 offset:39936
	global_load_lds_dwordx4 v[224:225], off
	v_lshl_add_u64 v[224:225], s[52:53], 0, v[160:161]
	s_mov_b32 m0, s58
	s_nop 0
	global_load_lds_dwordx4 v[224:225], off
	s_waitcnt vmcnt(8)
	s_waitcnt lgkmcnt(0)
	s_setprio 1
	s_barrier
	v_mfma_f32_16x16x32_bf16 v[140:143], v[100:103], v[174:177], v[140:143]
	v_mfma_f32_16x16x32_bf16 v[132:135], v[124:127], v[174:177], v[132:135]
	v_mfma_f32_16x16x32_bf16 v[116:119], v[100:103], v[194:197], v[116:119]
	v_mfma_f32_16x16x32_bf16 v[108:111], v[124:127], v[194:197], v[108:111]
	v_mfma_f32_16x16x32_bf16 v[92:95], v[100:103], v[202:205], v[92:95]
	v_mfma_f32_16x16x32_bf16 v[88:91], v[124:127], v[202:205], v[88:91]
	v_mfma_f32_16x16x32_bf16 v[76:79], v[100:103], v[210:213], v[76:79]
	v_mfma_f32_16x16x32_bf16 v[72:75], v[124:127], v[210:213], v[72:75]
	v_mfma_f32_16x16x32_bf16 v[140:143], v[112:115], v[178:181], v[140:143]
	v_mfma_f32_16x16x32_bf16 v[132:135], v[136:139], v[178:181], v[132:135]
	v_mfma_f32_16x16x32_bf16 v[116:119], v[112:115], v[198:201], v[116:119]
	v_mfma_f32_16x16x32_bf16 v[108:111], v[136:139], v[198:201], v[108:111]
	v_mfma_f32_16x16x32_bf16 v[92:95], v[112:115], v[206:209], v[92:95]
	v_mfma_f32_16x16x32_bf16 v[88:91], v[136:139], v[206:209], v[88:91]
	v_mfma_f32_16x16x32_bf16 v[76:79], v[112:115], v[214:217], v[76:79]
	v_mfma_f32_16x16x32_bf16 v[72:75], v[136:139], v[214:217], v[72:75]
	v_mfma_f32_16x16x32_bf16 v[128:131], v[144:147], v[174:177], v[128:131]
	v_mfma_f32_16x16x32_bf16 v[120:123], v[152:155], v[174:177], v[120:123]
	v_mfma_f32_16x16x32_bf16 v[104:107], v[144:147], v[194:197], v[104:107]
	v_mfma_f32_16x16x32_bf16 v[96:99], v[152:155], v[194:197], v[96:99]
	v_mfma_f32_16x16x32_bf16 v[84:87], v[144:147], v[202:205], v[84:87]
	v_mfma_f32_16x16x32_bf16 v[80:83], v[152:155], v[202:205], v[80:83]
	v_mfma_f32_16x16x32_bf16 v[68:71], v[144:147], v[210:213], v[68:71]
	v_mfma_f32_16x16x32_bf16 v[64:67], v[152:155], v[210:213], v[64:67]
	v_mfma_f32_16x16x32_bf16 v[128:131], v[148:151], v[178:181], v[128:131]
	v_mfma_f32_16x16x32_bf16 v[120:123], v[170:173], v[178:181], v[120:123]
	v_mfma_f32_16x16x32_bf16 v[104:107], v[148:151], v[198:201], v[104:107]
	v_mfma_f32_16x16x32_bf16 v[96:99], v[170:173], v[198:201], v[96:99]
	v_mfma_f32_16x16x32_bf16 v[84:87], v[148:151], v[206:209], v[84:87]
	v_mfma_f32_16x16x32_bf16 v[80:83], v[170:173], v[206:209], v[80:83]
	v_mfma_f32_16x16x32_bf16 v[68:71], v[148:151], v[214:217], v[68:71]
	v_mfma_f32_16x16x32_bf16 v[64:67], v[170:173], v[214:217], v[64:67]
	s_barrier
; #define PG8_STAGE(bufoff, gbase, voff) do { _Pragma("unroll") for (int _i = 0; _i < 2; ++_i) \
;         __builtin_amdgcn_global_load_lds((const unsigned*)((const char*)(gbase) + (voff)[_i]), (LAS unsigned*)(lds + (bufoff) + ldsw + _i * 8192), 16, 0, 0); } while (0)
; #define PG8_LDA(dst, b, h) do { _Pragma("unroll") for (int m = 0; m < 4; ++m) _Pragma("unroll") for (int k = 0; k < 2; ++k) dst[m][k] = *(const LAS bf16x8*)(lds + PG8_SA(b, h) + aoff + m * 2048 + k * 1024); } while (0)
; #define PG8_LDB(dst, b, h) do { _Pragma("unroll") for (int n = 0; n < 2; ++n) _Pragma("unroll") for (int k = 0; k < 2; ++k) dst[n][k] = *(const LAS bf16x8*)(lds + PG8_SB(b, h) + boff + n * 2048 + k * 1024); } while (0)
; template <class Epi, class Sched = StaticOrder, class EpiSub = NoSub, bool FAST = false>
; __device__ __forceinline__ void gemm_phase(LAS unsigned char* lds, const Gemm g, const Sched& S, const Epi& E, const EpiSub& ES = EpiSub()) {
;     ...
;         for (int t = 0; t < nt; t += 2) {
;             const bool last = (t == nt - 2);
;             const char* a1 = cA + (size_t)(t + 1) * kstep;
;             const char* a2 = last ? nA : cA + (size_t)(t + 2) * kstep; const char* b2 = last ? nB : cB + (size_t)(t + 2) * kstep;
;             const char* a3 = a2 + kstep; const char* b3 = b2 + kstep;
;             if constexpr (FAST && PG8_SP2) {
;             PG8_LDB(B0, 0, 0); PG8_LDB(B1, 0, 1); PG8_SCHED; PG8_LDA(At, 0, 0); PG8_STAGE(PG8_SA(1, 1), a1 + hstepA, voffA);
;             PG8_WAIT_V(8); PG8_WAIT_L(0); PG8_BAR; PG8_MMA(0, 0, At, B0); PG8_MMA(0, 1, At, B1); PG8_BAR; PG8_SCHED;
;             PG8_LDA(At, 0, 1); PG8_STAGE(PG8_SB(0, 0), b2, voffB); PG8_STAGE(PG8_SB(0, 1), b2 + hstepB, voffB); PG8_STAGE(PG8_SA(0, 0), a2, voffA);
;             PG8_WAIT_V(8); PG8_WAIT_L(0); PG8_BAR; PG8_MMA(1, 0, At, B0); PG8_MMA(1, 1, At, B1); PG8_BAR; PG8_SCHED;
;             PG8_LDB(B0, 1, 0); PG8_LDB(B1, 1, 1); PG8_SCHED; PG8_LDA(At, 1, 0); PG8_STAGE(PG8_SA(0, 1), a2 + hstepA, voffA);
;             PG8_WAIT_V(8); PG8_WAIT_L(0); PG8_BAR; PG8_MMA(0, 0, At, B0); PG8_MMA(0, 1, At, B1); PG8_BAR; PG8_SCHED;
;             PG8_LDA(At, 1, 1); PG8_STAGE(PG8_SB(1, 0), b3, voffB); PG8_STAGE(PG8_SB(1, 1), b3 + hstepB, voffB); PG8_STAGE(PG8_SA(1, 0), a3, voffA);
;             PG8_WAIT_V(8); PG8_WAIT_L(0); PG8_BAR; PG8_MMA(1, 0, At, B0); PG8_MMA(1, 1, At, B1); PG8_BAR; PG8_SCHED;
	s_setprio 0
	s_add_i32 s50, s50, s54
	v_lshl_add_u64 v[190:191], v[190:191], 0, s[12:13]
	s_mov_b32 m0, s50
	ds_read_b128 v[174:177], v188 offset:49152
	ds_read_b128 v[178:181], v188 offset:50176
	ds_read_b128 v[194:197], v188 offset:51200
	ds_read_b128 v[198:201], v188 offset:52224
	ds_read_b128 v[202:205], v188 offset:53248
	ds_read_b128 v[206:209], v188 offset:54272
	ds_read_b128 v[210:213], v188 offset:55296
	ds_read_b128 v[214:217], v188 offset:56320
	global_load_lds_dwordx4 v[190:191], off
	s_add_i32 m0, s50, 0x2000
	s_add_u32 s42, s42, 0x40080
	v_lshl_add_u64 v[190:191], v[218:219], 0, s[12:13]
	s_addc_u32 s43, s43, 0
	s_add_i32 s50, s70, s54
	global_load_lds_dwordx4 v[190:191], off
	v_lshl_add_u64 v[190:191], s[42:43], 0, v[158:159]
	s_mov_b32 m0, s50
	s_nop 0
	global_load_lds_dwordx4 v[190:191], off
	v_lshl_add_u64 v[190:191], s[42:43], 0, v[162:163]
	s_add_i32 m0, s50, 0x2000
	s_nop 0
	global_load_lds_dwordx4 v[190:191], off
	v_lshl_add_u64 v[190:191], v[220:221], 0, s[12:13]
	s_mov_b32 m0, s69
	s_nop 0
	global_load_lds_dwordx4 v[190:191], off
	v_lshl_add_u64 v[190:191], v[222:223], 0, s[12:13]
	s_mov_b32 m0, s74
	s_nop 0
	global_load_lds_dwordx4 v[190:191], off
	s_waitcnt vmcnt(8)
	s_waitcnt lgkmcnt(0)
	s_setprio 1
	s_barrier
	v_mfma_f32_16x16x32_bf16 v[60:63], v[100:103], v[174:177], v[60:63]
	v_mfma_f32_16x16x32_bf16 v[56:59], v[124:127], v[174:177], v[56:59]
	v_mfma_f32_16x16x32_bf16 v[44:47], v[100:103], v[194:197], v[44:47]
	v_mfma_f32_16x16x32_bf16 v[40:43], v[124:127], v[194:197], v[40:43]
	v_mfma_f32_16x16x32_bf16 v[28:31], v[100:103], v[202:205], v[28:31]
	v_mfma_f32_16x16x32_bf16 v[24:27], v[124:127], v[202:205], v[24:27]
	v_mfma_f32_16x16x32_bf16 v[12:15], v[100:103], v[210:213], v[12:15]
	v_mfma_f32_16x16x32_bf16 v[8:11], v[124:127], v[210:213], v[8:11]
	v_mfma_f32_16x16x32_bf16 v[60:63], v[112:115], v[178:181], v[60:63]
	v_mfma_f32_16x16x32_bf16 v[56:59], v[136:139], v[178:181], v[56:59]
	v_mfma_f32_16x16x32_bf16 v[44:47], v[112:115], v[198:201], v[44:47]
	v_mfma_f32_16x16x32_bf16 v[40:43], v[136:139], v[198:201], v[40:43]
	v_mfma_f32_16x16x32_bf16 v[28:31], v[112:115], v[206:209], v[28:31]
	v_mfma_f32_16x16x32_bf16 v[24:27], v[136:139], v[206:209], v[24:27]
	v_mfma_f32_16x16x32_bf16 v[12:15], v[112:115], v[214:217], v[12:15]
	v_mfma_f32_16x16x32_bf16 v[8:11], v[136:139], v[214:217], v[8:11]
	v_mfma_f32_16x16x32_bf16 v[52:55], v[144:147], v[174:177], v[52:55]
	v_mfma_f32_16x16x32_bf16 v[48:51], v[152:155], v[174:177], v[48:51]
	v_mfma_f32_16x16x32_bf16 v[36:39], v[144:147], v[194:197], v[36:39]
	v_mfma_f32_16x16x32_bf16 v[32:35], v[152:155], v[194:197], v[32:35]
	v_mfma_f32_16x16x32_bf16 v[20:23], v[144:147], v[202:205], v[20:23]
	v_mfma_f32_16x16x32_bf16 v[16:19], v[152:155], v[202:205], v[16:19]
	v_mfma_f32_16x16x32_bf16 v[4:7], v[144:147], v[210:213], v[4:7]
	v_mfma_f32_16x16x32_bf16 v[0:3], v[152:155], v[210:213], v[0:3]
	v_mfma_f32_16x16x32_bf16 v[52:55], v[148:151], v[178:181], v[52:55]
	v_mfma_f32_16x16x32_bf16 v[48:51], v[170:173], v[178:181], v[48:51]
	v_mfma_f32_16x16x32_bf16 v[36:39], v[148:151], v[198:201], v[36:39]
	v_mfma_f32_16x16x32_bf16 v[32:35], v[170:173], v[198:201], v[32:35]
	v_mfma_f32_16x16x32_bf16 v[20:23], v[148:151], v[206:209], v[20:23]
	v_mfma_f32_16x16x32_bf16 v[16:19], v[170:173], v[206:209], v[16:19]
	v_mfma_f32_16x16x32_bf16 v[4:7], v[148:151], v[214:217], v[4:7]
	v_mfma_f32_16x16x32_bf16 v[0:3], v[170:173], v[214:217], v[0:3]
	s_barrier
	s_setprio 0
	s_add_u32 s40, s40, 0x100
	s_addc_u32 s41, s41, 0
	s_add_u32 s48, s48, 0x100
	s_addc_u32 s49, s49, 0
	s_cmp_ge_u32 s51, s27
	s_mov_b32 s50, s51
	s_cbranch_scc1 .Lkpeel_600_exit
.LBB0_600:
	ds_read_b128 v[100:103], v186
	ds_read_b128 v[112:115], v186 offset:1024
	ds_read_b128 v[124:127], v186 offset:2048
	ds_read_b128 v[136:139], v186 offset:3072
	ds_read_b128 v[144:147], v187
	ds_read_b128 v[148:151], v187 offset:1024
	ds_read_b128 v[152:155], v187 offset:2048
	ds_read_b128 v[170:173], v187 offset:3072
	s_add_i32 s51, s50, 2
	s_add_u32 s42, s40, 0xfffc0080
	s_addc_u32 s43, s41, -1
	s_cmp_eq_u32 s33, s50
	s_cselect_b32 s53, s1, s43
	s_cselect_b32 s52, s5, s42
	s_cselect_b32 s43, s7, s49
	s_cselect_b32 s42, s25, s48
	v_lshl_add_u64 v[190:191], s[40:41], 0, v[164:165]
	s_add_i32 m0, s55, 0xc000
	ds_read_b128 v[174:177], v188
	ds_read_b128 v[178:181], v188 offset:1024
	ds_read_b128 v[194:197], v188 offset:2048
	ds_read_b128 v[198:201], v188 offset:3072
	ds_read_b128 v[202:205], v188 offset:4096
	ds_read_b128 v[206:209], v188 offset:5120
	ds_read_b128 v[210:213], v188 offset:6144
	ds_read_b128 v[214:217], v188 offset:7168
	global_load_lds_dwordx4 v[190:191], off
	v_lshl_add_u64 v[190:191], s[40:41], 0, v[166:167]
	s_add_i32 m0, s55, 0xe000
	s_nop 0
	global_load_lds_dwordx4 v[190:191], off
	s_waitcnt vmcnt(8)
	s_waitcnt lgkmcnt(0)
	s_setprio 1
	s_barrier
; #define PG8_STAGE(bufoff, gbase, voff) do { _Pragma("unroll") for (int _i = 0; _i < 2; ++_i) \
;         __builtin_amdgcn_global_load_lds((const unsigned*)((const char*)(gbase) + (voff)[_i]), (LAS unsigned*)(lds + (bufoff) + ldsw + _i * 8192), 16, 0, 0); } while (0)
; #define PG8_LDA(dst, b, h) do { _Pragma("unroll") for (int m = 0; m < 4; ++m) _Pragma("unroll") for (int k = 0; k < 2; ++k) dst[m][k] = *(const LAS bf16x8*)(lds + PG8_SA(b, h) + aoff + m * 2048 + k * 1024); } while (0)
; #define PG8_LDB(dst, b, h) do { _Pragma("unroll") for (int n = 0; n < 2; ++n) _Pragma("unroll") for (int k = 0; k < 2; ++k) dst[n][k] = *(const LAS bf16x8*)(lds + PG8_SB(b, h) + boff + n * 2048 + k * 1024); } while (0)
; template <class Epi, class Sched = StaticOrder, class EpiSub = NoSub, bool FAST = false>
; __device__ __forceinline__ void gemm_phase(LAS unsigned char* lds, const Gemm g, const Sched& S, const Epi& E, const EpiSub& ES = EpiSub()) {
;     ...
;         for (int t = 0; t < nt; t += 2) {
;             const bool last = (t == nt - 2);
;             const char* a1 = cA + (size_t)(t + 1) * kstep;
;             const char* a2 = last ? nA : cA + (size_t)(t + 2) * kstep; const char* b2 = last ? nB : cB + (size_t)(t + 2) * kstep;
;             const char* a3 = a2 + kstep; const char* b3 = b2 + kstep;
;             if constexpr (FAST && PG8_SP2) {
;             PG8_LDB(B0, 0, 0); PG8_LDB(B1, 0, 1); PG8_SCHED; PG8_LDA(At, 0, 0); PG8_STAGE(PG8_SA(1, 1), a1 + hstepA, voffA);
;             PG8_WAIT_V(8); PG8_WAIT_L(0); PG8_BAR; PG8_MMA(0, 0, At, B0); PG8_MMA(0, 1, At, B1); PG8_BAR; PG8_SCHED;
;             PG8_LDA(At, 0, 1); PG8_STAGE(PG8_SB(0, 0), b2, voffB); PG8_STAGE(PG8_SB(0, 1), b2 + hstepB, voffB); PG8_STAGE(PG8_SA(0, 0), a2, voffA);
;             PG8_WAIT_V(8); PG8_WAIT_L(0); PG8_BAR; PG8_MMA(1, 0, At, B0); PG8_MMA(1, 1, At, B1); PG8_BAR; PG8_SCHED;
;             PG8_LDB(B0, 1, 0); PG8_LDB(B1, 1, 1); PG8_SCHED; PG8_LDA(At, 1, 0); PG8_STAGE(PG8_SA(0, 1), a2 + hstepA, voffA);
;             PG8_WAIT_V(8); PG8_WAIT_L(0); PG8_BAR; PG8_MMA(0, 0, At, B0); PG8_MMA(0, 1, At, B1); PG8_BAR; PG8_SCHED;
;             PG8_LDA(At, 1, 1); PG8_STAGE(PG8_SB(1, 0), b3, voffB); PG8_STAGE(PG8_SB(1, 1), b3 + hstepB, voffB); PG8_STAGE(PG8_SA(1, 0), a3, voffA);
;             PG8_WAIT_V(8); PG8_WAIT_L(0); PG8_BAR; PG8_MMA(1, 0, At, B0); PG8_MMA(1, 1, At, B1); PG8_BAR; PG8_SCHED;
	v_mfma_f32_16x16x32_bf16 v[140:143], v[100:103], v[174:177], v[140:143]
	v_mfma_f32_16x16x32_bf16 v[132:135], v[124:127], v[174:177], v[132:135]
	v_mfma_f32_16x16x32_bf16 v[116:119], v[100:103], v[194:197], v[116:119]
	v_mfma_f32_16x16x32_bf16 v[108:111], v[124:127], v[194:197], v[108:111]
	v_mfma_f32_16x16x32_bf16 v[92:95], v[100:103], v[202:205], v[92:95]
	v_mfma_f32_16x16x32_bf16 v[88:91], v[124:127], v[202:205], v[88:91]
	v_mfma_f32_16x16x32_bf16 v[76:79], v[100:103], v[210:213], v[76:79]
	v_mfma_f32_16x16x32_bf16 v[72:75], v[124:127], v[210:213], v[72:75]
	v_mfma_f32_16x16x32_bf16 v[140:143], v[112:115], v[178:181], v[140:143]
	v_mfma_f32_16x16x32_bf16 v[132:135], v[136:139], v[178:181], v[132:135]
	v_mfma_f32_16x16x32_bf16 v[116:119], v[112:115], v[198:201], v[116:119]
	v_mfma_f32_16x16x32_bf16 v[108:111], v[136:139], v[198:201], v[108:111]
	v_mfma_f32_16x16x32_bf16 v[92:95], v[112:115], v[206:209], v[92:95]
	v_mfma_f32_16x16x32_bf16 v[88:91], v[136:139], v[206:209], v[88:91]
	v_mfma_f32_16x16x32_bf16 v[76:79], v[112:115], v[214:217], v[76:79]
	v_mfma_f32_16x16x32_bf16 v[72:75], v[136:139], v[214:217], v[72:75]
	v_mfma_f32_16x16x32_bf16 v[128:131], v[144:147], v[174:177], v[128:131]
	v_mfma_f32_16x16x32_bf16 v[120:123], v[152:155], v[174:177], v[120:123]
	v_mfma_f32_16x16x32_bf16 v[104:107], v[144:147], v[194:197], v[104:107]
	v_mfma_f32_16x16x32_bf16 v[96:99], v[152:155], v[194:197], v[96:99]
	v_mfma_f32_16x16x32_bf16 v[84:87], v[144:147], v[202:205], v[84:87]
	v_mfma_f32_16x16x32_bf16 v[80:83], v[152:155], v[202:205], v[80:83]
	v_mfma_f32_16x16x32_bf16 v[68:71], v[144:147], v[210:213], v[68:71]
	v_mfma_f32_16x16x32_bf16 v[64:67], v[152:155], v[210:213], v[64:67]
	v_mfma_f32_16x16x32_bf16 v[128:131], v[148:151], v[178:181], v[128:131]
	v_mfma_f32_16x16x32_bf16 v[120:123], v[170:173], v[178:181], v[120:123]
	v_mfma_f32_16x16x32_bf16 v[104:107], v[148:151], v[198:201], v[104:107]
	v_mfma_f32_16x16x32_bf16 v[96:99], v[170:173], v[198:201], v[96:99]
	v_mfma_f32_16x16x32_bf16 v[84:87], v[148:151], v[206:209], v[84:87]
	v_mfma_f32_16x16x32_bf16 v[80:83], v[170:173], v[206:209], v[80:83]
	v_mfma_f32_16x16x32_bf16 v[68:71], v[148:151], v[214:217], v[68:71]
	v_mfma_f32_16x16x32_bf16 v[64:67], v[170:173], v[214:217], v[64:67]
	s_barrier
	s_setprio 0
	s_add_i32 s50, s75, s54
	v_lshl_add_u64 v[190:191], s[42:43], 0, v[158:159]
	s_mov_b32 m0, s50
	ds_read_b128 v[174:177], v188 offset:16384
	ds_read_b128 v[178:181], v188 offset:17408
	ds_read_b128 v[194:197], v188 offset:18432
	ds_read_b128 v[198:201], v188 offset:19456
	ds_read_b128 v[202:205], v188 offset:20480
	ds_read_b128 v[206:209], v188 offset:21504
	ds_read_b128 v[210:213], v188 offset:22528
	ds_read_b128 v[214:217], v188 offset:23552
	global_load_lds_dwordx4 v[190:191], off
	s_add_i32 m0, s50, 0x2000
	s_add_u32 s70, s42, 0x40000
	v_lshl_add_u64 v[218:219], s[42:43], 0, v[162:163]
	s_addc_u32 s71, s43, 0
	s_add_i32 s50, s80, s54
	global_load_lds_dwordx4 v[218:219], off
	v_lshl_add_u64 v[220:221], s[70:71], 0, v[158:159]
	s_mov_b32 m0, s50
	v_lshl_add_u64 v[222:223], s[52:53], 0, v[160:161]
	global_load_lds_dwordx4 v[220:221], off
	v_lshl_add_u64 v[220:221], s[70:71], 0, v[162:163]
	s_add_i32 m0, s50, 0x2000
	s_nop 0
	global_load_lds_dwordx4 v[220:221], off
	v_lshl_add_u64 v[220:221], s[52:53], 0, v[156:157]
	s_mov_b32 m0, s55
	s_nop 0
	global_load_lds_dwordx4 v[220:221], off
	s_mov_b32 m0, s56
	s_nop 0
	global_load_lds_dwordx4 v[222:223], off
	s_waitcnt vmcnt(8)
	s_waitcnt lgkmcnt(0)
	s_setprio 1
	s_barrier
	v_mfma_f32_16x16x32_bf16 v[60:63], v[100:103], v[174:177], v[60:63]
	v_mfma_f32_16x16x32_bf16 v[56:59], v[124:127], v[174:177], v[56:59]
	v_mfma_f32_16x16x32_bf16 v[44:47], v[100:103], v[194:197], v[44:47]
	v_mfma_f32_16x16x32_bf16 v[40:43], v[124:127], v[194:197], v[40:43]
	v_mfma_f32_16x16x32_bf16 v[28:31], v[100:103], v[202:205], v[28:31]
	v_mfma_f32_16x16x32_bf16 v[24:27], v[124:127], v[202:205], v[24:27]
	v_mfma_f32_16x16x32_bf16 v[12:15], v[100:103], v[210:213], v[12:15]
	v_mfma_f32_16x16x32_bf16 v[8:11], v[124:127], v[210:213], v[8:11]
	v_mfma_f32_16x16x32_bf16 v[60:63], v[112:115], v[178:181], v[60:63]
	v_mfma_f32_16x16x32_bf16 v[56:59], v[136:139], v[178:181], v[56:59]
	v_mfma_f32_16x16x32_bf16 v[44:47], v[112:115], v[198:201], v[44:47]
	v_mfma_f32_16x16x32_bf16 v[40:43], v[136:139], v[198:201], v[40:43]
	v_mfma_f32_16x16x32_bf16 v[28:31], v[112:115], v[206:209], v[28:31]
	v_mfma_f32_16x16x32_bf16 v[24:27], v[136:139], v[206:209], v[24:27]
	v_mfma_f32_16x16x32_bf16 v[12:15], v[112:115], v[214:217], v[12:15]
	v_mfma_f32_16x16x32_bf16 v[8:11], v[136:139], v[214:217], v[8:11]
	v_mfma_f32_16x16x32_bf16 v[52:55], v[144:147], v[174:177], v[52:55]
	v_mfma_f32_16x16x32_bf16 v[48:51], v[152:155], v[174:177], v[48:51]
	v_mfma_f32_16x16x32_bf16 v[36:39], v[144:147], v[194:197], v[36:39]
	v_mfma_f32_16x16x32_bf16 v[32:35], v[152:155], v[194:197], v[32:35]
	v_mfma_f32_16x16x32_bf16 v[20:23], v[144:147], v[202:205], v[20:23]
	v_mfma_f32_16x16x32_bf16 v[16:19], v[152:155], v[202:205], v[16:19]
	v_mfma_f32_16x16x32_bf16 v[4:7], v[144:147], v[210:213], v[4:7]
	v_mfma_f32_16x16x32_bf16 v[0:3], v[152:155], v[210:213], v[0:3]
	v_mfma_f32_16x16x32_bf16 v[52:55], v[148:151], v[178:181], v[52:55]
	v_mfma_f32_16x16x32_bf16 v[48:51], v[170:173], v[178:181], v[48:51]
	v_mfma_f32_16x16x32_bf16 v[36:39], v[148:151], v[198:201], v[36:39]
	v_mfma_f32_16x16x32_bf16 v[32:35], v[170:173], v[198:201], v[32:35]
	v_mfma_f32_16x16x32_bf16 v[20:23], v[148:151], v[206:209], v[20:23]
	v_mfma_f32_16x16x32_bf16 v[16:19], v[170:173], v[206:209], v[16:19]
	v_mfma_f32_16x16x32_bf16 v[4:7], v[148:151], v[214:217], v[4:7]
	v_mfma_f32_16x16x32_bf16 v[0:3], v[170:173], v[214:217], v[0:3]
	s_barrier
; #define PG8_STAGE(bufoff, gbase, voff) do { _Pragma("unroll") for (int _i = 0; _i < 2; ++_i) \
;         __builtin_amdgcn_global_load_lds((const unsigned*)((const char*)(gbase) + (voff)[_i]), (LAS unsigned*)(lds + (bufoff) + ldsw + _i * 8192), 16, 0, 0); } while (0)
; #define PG8_LDA(dst, b, h) do { _Pragma("unroll") for (int m = 0; m < 4; ++m) _Pragma("unroll") for (int k = 0; k < 2; ++k) dst[m][k] = *(const LAS bf16x8*)(lds + PG8_SA(b, h) + aoff + m * 2048 + k * 1024); } while (0)
; #define PG8_LDB(dst, b, h) do { _Pragma("unroll") for (int n = 0; n < 2; ++n) _Pragma("unroll") for (int k = 0; k < 2; ++k) dst[n][k] = *(const LAS bf16x8*)(lds + PG8_SB(b, h) + boff + n * 2048 + k * 1024); } while (0)
; #define PG8_MMA(ai, bj, At, Bt) do { __builtin_amdgcn_s_setprio(1); _Pragma("unroll") for (int m = 0; m < 4; ++m) _Pragma("unroll") for (int n = 0; n < 2; ++n) _Pragma("unroll") for (int k = 0; k < 2; ++k) \
;         acc[ai][bj][m][n] = __builtin_amdgcn_mfma_f32_16x16x32_bf16(Bt[n][k], At[m][k], acc[ai][bj][m][n], 0, 0, 0); __builtin_amdgcn_s_setprio(0); } while (0)
; #define PG8_WAIT_V(n) asm volatile("s_waitcnt vmcnt(" #n ")" ::: "memory")
; #define PG8_WAIT_L(n) asm volatile("s_waitcnt lgkmcnt(" #n ")" ::: "memory")
; #define PG8_BAR __builtin_amdgcn_s_barrier()
; #define PG8_SCHED __builtin_amdgcn_sched_barrier(0)
; template <class Epi, class Sched = StaticOrder, class EpiSub = NoSub, bool FAST = false>
; __device__ __forceinline__ void gemm_phase(LAS unsigned char* lds, const Gemm g, const Sched& S, const Epi& E, const EpiSub& ES = EpiSub()) {
;     ...
;             PG8_LDB(B0, 0, 0); PG8_LDB(B1, 0, 1); PG8_SCHED; PG8_LDA(At, 0, 0); PG8_STAGE(PG8_SA(1, 1), a1 + hstepA, voffA);
;             PG8_WAIT_V(8); PG8_WAIT_L(0); PG8_BAR; PG8_MMA(0, 0, At, B0); PG8_MMA(0, 1, At, B1); PG8_BAR; PG8_SCHED;
;             PG8_LDA(At, 0, 1); PG8_STAGE(PG8_SB(0, 0), b2, voffB); PG8_STAGE(PG8_SB(0, 1), b2 + hstepB, voffB); PG8_STAGE(PG8_SA(0, 0), a2, voffA);
;             PG8_WAIT_V(8); PG8_WAIT_L(0); PG8_BAR; PG8_MMA(1, 0, At, B0); PG8_MMA(1, 1, At, B1); PG8_BAR; PG8_SCHED;
;             PG8_LDB(B0, 1, 0); PG8_LDB(B1, 1, 1); PG8_SCHED; PG8_LDA(At, 1, 0); PG8_STAGE(PG8_SA(0, 1), a2 + hstepA, voffA);
;             PG8_WAIT_V(8); PG8_WAIT_L(0); PG8_BAR; PG8_MMA(0, 0, At, B0); PG8_MMA(0, 1, At, B1); PG8_BAR; PG8_SCHED;
	s_setprio 0
	s_add_i32 s50, 0, 0x18000
	s_add_i32 s70, 0, 0x1c000
	v_add_u32_e32 v136, s50, v183
	v_add_u32_e32 v170, s70, v183
	ds_read_b128 v[100:103], v136
	ds_read_b128 v[112:115], v136 offset:1024
	ds_read_b128 v[124:127], v136 offset:2048
	ds_read_b128 v[136:139], v136 offset:3072
	ds_read_b128 v[144:147], v170
	ds_read_b128 v[148:151], v170 offset:1024
	ds_read_b128 v[152:155], v170 offset:2048
	ds_read_b128 v[170:173], v170 offset:3072
	s_add_u32 s52, s52, 0x40000
	s_addc_u32 s53, s53, 0
	s_mov_b32 m0, s57
	v_lshl_add_u64 v[224:225], s[52:53], 0, v[156:157]
	ds_read_b128 v[174:177], v188 offset:32768
	ds_read_b128 v[178:181], v188 offset:33792
	ds_read_b128 v[194:197], v188 offset:34816
	ds_read_b128 v[198:201], v188 offset:35840
	ds_read_b128 v[202:205], v188 offset:36864
	ds_read_b128 v[206:209], v188 offset:37888
	ds_read_b128 v[210:213], v188 offset:38912
	ds_read_b128 v[214:217], v188 offset:39936
	global_load_lds_dwordx4 v[224:225], off
	v_lshl_add_u64 v[224:225], s[52:53], 0, v[160:161]
	s_mov_b32 m0, s58
	s_nop 0
	global_load_lds_dwordx4 v[224:225], off
	s_waitcnt vmcnt(8)
	s_waitcnt lgkmcnt(0)
	s_setprio 1
	s_barrier
	v_mfma_f32_16x16x32_bf16 v[140:143], v[100:103], v[174:177], v[140:143]
	v_mfma_f32_16x16x32_bf16 v[132:135], v[124:127], v[174:177], v[132:135]
	v_mfma_f32_16x16x32_bf16 v[116:119], v[100:103], v[194:197], v[116:119]
	v_mfma_f32_16x16x32_bf16 v[108:111], v[124:127], v[194:197], v[108:111]
	v_mfma_f32_16x16x32_bf16 v[92:95], v[100:103], v[202:205], v[92:95]
	v_mfma_f32_16x16x32_bf16 v[88:91], v[124:127], v[202:205], v[88:91]
	v_mfma_f32_16x16x32_bf16 v[76:79], v[100:103], v[210:213], v[76:79]
	v_mfma_f32_16x16x32_bf16 v[72:75], v[124:127], v[210:213], v[72:75]
	v_mfma_f32_16x16x32_bf16 v[140:143], v[112:115], v[178:181], v[140:143]
	v_mfma_f32_16x16x32_bf16 v[132:135], v[136:139], v[178:181], v[132:135]
	v_mfma_f32_16x16x32_bf16 v[116:119], v[112:115], v[198:201], v[116:119]
	v_mfma_f32_16x16x32_bf16 v[108:111], v[136:139], v[198:201], v[108:111]
	v_mfma_f32_16x16x32_bf16 v[92:95], v[112:115], v[206:209], v[92:95]
	v_mfma_f32_16x16x32_bf16 v[88:91], v[136:139], v[206:209], v[88:91]
	v_mfma_f32_16x16x32_bf16 v[76:79], v[112:115], v[214:217], v[76:79]
	v_mfma_f32_16x16x32_bf16 v[72:75], v[136:139], v[214:217], v[72:75]
	v_mfma_f32_16x16x32_bf16 v[128:131], v[144:147], v[174:177], v[128:131]
	v_mfma_f32_16x16x32_bf16 v[120:123], v[152:155], v[174:177], v[120:123]
	v_mfma_f32_16x16x32_bf16 v[104:107], v[144:147], v[194:197], v[104:107]
	v_mfma_f32_16x16x32_bf16 v[96:99], v[152:155], v[194:197], v[96:99]
	v_mfma_f32_16x16x32_bf16 v[84:87], v[144:147], v[202:205], v[84:87]
	v_mfma_f32_16x16x32_bf16 v[80:83], v[152:155], v[202:205], v[80:83]
	v_mfma_f32_16x16x32_bf16 v[68:71], v[144:147], v[210:213], v[68:71]
	v_mfma_f32_16x16x32_bf16 v[64:67], v[152:155], v[210:213], v[64:67]
	v_mfma_f32_16x16x32_bf16 v[128:131], v[148:151], v[178:181], v[128:131]
	v_mfma_f32_16x16x32_bf16 v[120:123], v[170:173], v[178:181], v[120:123]
	v_mfma_f32_16x16x32_bf16 v[104:107], v[148:151], v[198:201], v[104:107]
	v_mfma_f32_16x16x32_bf16 v[96:99], v[170:173], v[198:201], v[96:99]
	v_mfma_f32_16x16x32_bf16 v[84:87], v[148:151], v[206:209], v[84:87]
	v_mfma_f32_16x16x32_bf16 v[80:83], v[170:173], v[206:209], v[80:83]
	v_mfma_f32_16x16x32_bf16 v[68:71], v[148:151], v[214:217], v[68:71]
	v_mfma_f32_16x16x32_bf16 v[64:67], v[170:173], v[214:217], v[64:67]
	s_barrier
; #define PG8_STAGE(bufoff, gbase, voff) do { _Pragma("unroll") for (int _i = 0; _i < 2; ++_i) \
;         __builtin_amdgcn_global_load_lds((const unsigned*)((const char*)(gbase) + (voff)[_i]), (LAS unsigned*)(lds + (bufoff) + ldsw + _i * 8192), 16, 0, 0); } while (0)
; #define PG8_LDA(dst, b, h) do { _Pragma("unroll") for (int m = 0; m < 4; ++m) _Pragma("unroll") for (int k = 0; k < 2; ++k) dst[m][k] = *(const LAS bf16x8*)(lds + PG8_SA(b, h) + aoff + m * 2048 + k * 1024); } while (0)
; #define PG8_WAIT_V(n) asm volatile("s_waitcnt vmcnt(" #n ")" ::: "memory")
; #define PG8_WAIT_L(n) asm volatile("s_waitcnt lgkmcnt(" #n ")" ::: "memory")
; template <class Epi, class Sched = StaticOrder, class EpiSub = NoSub, bool FAST = false>
; __device__ __forceinline__ void gemm_phase(LAS unsigned char* lds, const Gemm g, const Sched& S, const Epi& E, const EpiSub& ES = EpiSub()) {
;     ...
;         for (int t = 0; t < nt; t += 2) {
;             const bool last = (t == nt - 2);
;             const char* a1 = cA + (size_t)(t + 1) * kstep;
;             const char* a2 = last ? nA : cA + (size_t)(t + 2) * kstep; const char* b2 = last ? nB : cB + (size_t)(t + 2) * kstep;
;             const char* a3 = a2 + kstep; const char* b3 = b2 + kstep;
;             if constexpr (FAST && PG8_SP2) {
;             PG8_LDB(B0, 0, 0); PG8_LDB(B1, 0, 1); PG8_SCHED; PG8_LDA(At, 0, 0); PG8_STAGE(PG8_SA(1, 1), a1 + hstepA, voffA);
;             PG8_WAIT_V(8); PG8_WAIT_L(0); PG8_BAR; PG8_MMA(0, 0, At, B0); PG8_MMA(0, 1, At, B1); PG8_BAR; PG8_SCHED;
;             PG8_LDA(At, 0, 1); PG8_STAGE(PG8_SB(0, 0), b2, voffB); PG8_STAGE(PG8_SB(0, 1), b2 + hstepB, voffB); PG8_STAGE(PG8_SA(0, 0), a2, voffA);
;             PG8_WAIT_V(8); PG8_WAIT_L(0); PG8_BAR; PG8_MMA(1, 0, At, B0); PG8_MMA(1, 1, At, B1); PG8_BAR; PG8_SCHED;
;             PG8_LDB(B0, 1, 0); PG8_LDB(B1, 1, 1); PG8_SCHED; PG8_LDA(At, 1, 0); PG8_STAGE(PG8_SA(0, 1), a2 + hstepA, voffA);
;             PG8_WAIT_V(8); PG8_WAIT_L(0); PG8_BAR; PG8_MMA(0, 0, At, B0); PG8_MMA(0, 1, At, B1); PG8_BAR; PG8_SCHED;
;             PG8_LDA(At, 1, 1); PG8_STAGE(PG8_SB(1, 0), b3, voffB); PG8_STAGE(PG8_SB(1, 1), b3 + hstepB, voffB); PG8_STAGE(PG8_SA(1, 0), a3, voffA);
;             PG8_WAIT_V(8); PG8_WAIT_L(0); PG8_BAR; PG8_MMA(1, 0, At, B0); PG8_MMA(1, 1, At, B1); PG8_BAR; PG8_SCHED;
;     ...
;         if constexpr (FAST && PG8_ALIGN) { if (wr == 0) PG8_BAR; }
	s_setprio 0
	s_add_i32 s50, s50, s54
	v_lshl_add_u64 v[190:191], v[190:191], 0, s[12:13]
	s_mov_b32 m0, s50
	ds_read_b128 v[174:177], v188 offset:49152
	ds_read_b128 v[178:181], v188 offset:50176
	ds_read_b128 v[194:197], v188 offset:51200
	ds_read_b128 v[198:201], v188 offset:52224
	ds_read_b128 v[202:205], v188 offset:53248
	ds_read_b128 v[206:209], v188 offset:54272
	ds_read_b128 v[210:213], v188 offset:55296
	ds_read_b128 v[214:217], v188 offset:56320
	global_load_lds_dwordx4 v[190:191], off
	s_add_i32 m0, s50, 0x2000
	s_add_u32 s42, s42, 0x40080
	v_lshl_add_u64 v[190:191], v[218:219], 0, s[12:13]
	s_addc_u32 s43, s43, 0
	s_add_i32 s50, s70, s54
	global_load_lds_dwordx4 v[190:191], off
	v_lshl_add_u64 v[190:191], s[42:43], 0, v[158:159]
	s_mov_b32 m0, s50
	s_nop 0
	global_load_lds_dwordx4 v[190:191], off
	v_lshl_add_u64 v[190:191], s[42:43], 0, v[162:163]
	s_add_i32 m0, s50, 0x2000
	s_nop 0
	global_load_lds_dwordx4 v[190:191], off
	v_lshl_add_u64 v[190:191], v[220:221], 0, s[12:13]
	s_mov_b32 m0, s69
	s_nop 0
	global_load_lds_dwordx4 v[190:191], off
	v_lshl_add_u64 v[190:191], v[222:223], 0, s[12:13]
	s_mov_b32 m0, s74
	s_nop 0
	global_load_lds_dwordx4 v[190:191], off
	s_waitcnt vmcnt(8)
	s_waitcnt lgkmcnt(0)
	s_setprio 1
	s_barrier
	v_mfma_f32_16x16x32_bf16 v[60:63], v[100:103], v[174:177], v[60:63]
	v_mfma_f32_16x16x32_bf16 v[56:59], v[124:127], v[174:177], v[56:59]
	v_mfma_f32_16x16x32_bf16 v[44:47], v[100:103], v[194:197], v[44:47]
	v_mfma_f32_16x16x32_bf16 v[40:43], v[124:127], v[194:197], v[40:43]
	v_mfma_f32_16x16x32_bf16 v[28:31], v[100:103], v[202:205], v[28:31]
	v_mfma_f32_16x16x32_bf16 v[24:27], v[124:127], v[202:205], v[24:27]
	v_mfma_f32_16x16x32_bf16 v[12:15], v[100:103], v[210:213], v[12:15]
	v_mfma_f32_16x16x32_bf16 v[8:11], v[124:127], v[210:213], v[8:11]
	v_mfma_f32_16x16x32_bf16 v[60:63], v[112:115], v[178:181], v[60:63]
	v_mfma_f32_16x16x32_bf16 v[56:59], v[136:139], v[178:181], v[56:59]
	v_mfma_f32_16x16x32_bf16 v[44:47], v[112:115], v[198:201], v[44:47]
	v_mfma_f32_16x16x32_bf16 v[40:43], v[136:139], v[198:201], v[40:43]
	v_mfma_f32_16x16x32_bf16 v[28:31], v[112:115], v[206:209], v[28:31]
	v_mfma_f32_16x16x32_bf16 v[24:27], v[136:139], v[206:209], v[24:27]
	v_mfma_f32_16x16x32_bf16 v[12:15], v[112:115], v[214:217], v[12:15]
	v_mfma_f32_16x16x32_bf16 v[8:11], v[136:139], v[214:217], v[8:11]
	v_mfma_f32_16x16x32_bf16 v[52:55], v[144:147], v[174:177], v[52:55]
	v_mfma_f32_16x16x32_bf16 v[48:51], v[152:155], v[174:177], v[48:51]
	v_mfma_f32_16x16x32_bf16 v[36:39], v[144:147], v[194:197], v[36:39]
	v_mfma_f32_16x16x32_bf16 v[32:35], v[152:155], v[194:197], v[32:35]
	v_mfma_f32_16x16x32_bf16 v[20:23], v[144:147], v[202:205], v[20:23]
	v_mfma_f32_16x16x32_bf16 v[16:19], v[152:155], v[202:205], v[16:19]
	v_mfma_f32_16x16x32_bf16 v[4:7], v[144:147], v[210:213], v[4:7]
	v_mfma_f32_16x16x32_bf16 v[0:3], v[152:155], v[210:213], v[0:3]
	v_mfma_f32_16x16x32_bf16 v[52:55], v[148:151], v[178:181], v[52:55]
	v_mfma_f32_16x16x32_bf16 v[48:51], v[170:173], v[178:181], v[48:51]
	v_mfma_f32_16x16x32_bf16 v[36:39], v[148:151], v[198:201], v[36:39]
	v_mfma_f32_16x16x32_bf16 v[32:35], v[170:173], v[198:201], v[32:35]
	v_mfma_f32_16x16x32_bf16 v[20:23], v[148:151], v[206:209], v[20:23]
	v_mfma_f32_16x16x32_bf16 v[16:19], v[170:173], v[206:209], v[16:19]
	v_mfma_f32_16x16x32_bf16 v[4:7], v[148:151], v[214:217], v[4:7]
	v_mfma_f32_16x16x32_bf16 v[0:3], v[170:173], v[214:217], v[0:3]
	s_barrier
	s_setprio 0
	s_add_u32 s40, s40, 0x100
	s_addc_u32 s41, s41, 0
	s_add_u32 s48, s48, 0x100
	s_addc_u32 s49, s49, 0
	s_cmp_ge_u32 s51, s27
	s_mov_b32 s50, s51
	s_cbranch_scc0 .LBB0_600
.Lkpeel_600_exit:
	s_and_b64 vcc, exec, s[14:15]
	s_cbranch_vccz .LBB0_603
	s_barrier

; #define PG8_STAGE(bufoff, gbase, voff) do { _Pragma("unroll") for (int _i = 0; _i < 2; ++_i) \
;         __builtin_amdgcn_global_load_lds((const unsigned*)((const char*)(gbase) + (voff)[_i]), (LAS unsigned*)(lds + (bufoff) + ldsw + _i * 8192), 16, 0, 0); } while (0)
; #define PG8_LDA(dst, b, h) do { _Pragma("unroll") for (int m = 0; m < 4; ++m) _Pragma("unroll") for (int k = 0; k < 2; ++k) dst[m][k] = *(const LAS bf16x8*)(lds + PG8_SA(b, h) + aoff + m * 2048 + k * 1024); } while (0)
; #define PG8_LDB(dst, b, h) do { _Pragma("unroll") for (int n = 0; n < 2; ++n) _Pragma("unroll") for (int k = 0; k < 2; ++k) dst[n][k] = *(const LAS bf16x8*)(lds + PG8_SB(b, h) + boff + n * 2048 + k * 1024); } while (0)
; #define PG8_WAIT_V(n) asm volatile("s_waitcnt vmcnt(" #n ")" ::: "memory")
; #define PG8_BAR __builtin_amdgcn_s_barrier()
; template <class Epi, class Sched = StaticOrder, class EpiSub = NoSub, bool FAST = false>
; __device__ __forceinline__ void gemm_phase(LAS unsigned char* lds, const Gemm g, const Sched& S, const Epi& E, const EpiSub& ES = EpiSub()) {
;     ...
;         const bool has_next = S.next(ui + 1, nxt);
;         const size_t nko = (has_next && nxt.kb >= 0) ? nxt.kb * ksubB : 0;
;         const char* nA = has_next ? (const char*)g.A + (size_t)nxt.pm * tstepA + (size_t)nxt.pn * g.acs + nko : cA; const char* nB = has_next ? (const char*)g.Bt + (size_t)nxt.pn * tstepB + nko : cB;
;         const int nt = cur.kb < 0 ? ntMain : ntSub;
;         for (int t = 0; t < nt; t += 2) {
;             const bool last = (t == nt - 2);
;             const char* a1 = cA + (size_t)(t + 1) * kstep;
;             const char* a2 = last ? nA : cA + (size_t)(t + 2) * kstep; const char* b2 = last ? nB : cB + (size_t)(t + 2) * kstep;
;             const char* a3 = a2 + kstep; const char* b3 = b2 + kstep;
;             if constexpr (FAST && PG8_SP2) {
;             PG8_LDB(B0, 0, 0); PG8_LDB(B1, 0, 1); PG8_SCHED; PG8_LDA(At, 0, 0); PG8_STAGE(PG8_SA(1, 1), a1 + hstepA, voffA);
;             PG8_WAIT_V(8); PG8_WAIT_L(0); PG8_BAR; PG8_MMA(0, 0, At, B0); PG8_MMA(0, 1, At, B1); PG8_BAR; PG8_SCHED;
;             PG8_LDA(At, 0, 1); PG8_STAGE(PG8_SB(0, 0), b2, voffB); PG8_STAGE(PG8_SB(0, 1), b2 + hstepB, voffB); PG8_STAGE(PG8_SA(0, 0), a2, voffA);
;             PG8_WAIT_V(8); PG8_WAIT_L(0); PG8_BAR; PG8_MMA(1, 0, At, B0); PG8_MMA(1, 1, At, B1); PG8_BAR; PG8_SCHED;
.LBB0_631:
	s_cmp_gt_i32 s8, -1
	s_cselect_b64 s[26:27], -1, 0
	s_and_b64 s[26:27], s[24:25], s[26:27]
	s_lshl_b64 s[28:29], s[8:9], 10
	s_and_b64 s[26:27], s[26:27], exec
	s_cselect_b32 s31, s29, 0
	s_cselect_b32 s33, s28, 0
	s_ashr_i32 s23, s22, 31
	s_lshl_b64 s[26:27], s[22:23], 20
	v_readlane_b32 s28, v254, 36
	v_readlane_b32 s29, v254, 37
	s_add_u32 s1, s28, s26
	s_addc_u32 s5, s29, s27
	s_add_u32 s26, s1, s33
	s_addc_u32 s27, s5, s31
	s_and_b64 s[28:29], s[24:25], exec
	s_cselect_b32 s1, s27, s39
	s_cselect_b32 s5, s26, s38
	s_ashr_i32 s21, s20, 31
	s_lshl_b64 s[28:29], s[20:21], 20
	s_add_u32 s21, s2, s28
	s_addc_u32 s23, s3, s29
	s_add_u32 s28, s21, s33
	s_addc_u32 s29, s23, s31
	s_and_b64 s[36:37], s[24:25], exec
	s_cselect_b32 s21, s29, s41
	s_cselect_b32 s23, s28, s40
	s_cmp_gt_i32 s0, -1
	s_cselect_b64 s[36:37], -1, 0
	s_cmp_lt_i32 s0, 0
	s_cselect_b32 s31, 32, 8
	s_add_i32 s33, s31, -2
	s_add_u32 s38, s38, 0x80080
	s_addc_u32 s39, s39, 0
	s_add_u32 s48, s40, 0x100
	s_mov_b32 s42, 0
	s_addc_u32 s49, s41, 0
	ds_read_b128 v[104:107], v224
	ds_read_b128 v[108:111], v224 offset:1024
	ds_read_b128 v[120:123], v224 offset:2048
	ds_read_b128 v[124:127], v224 offset:3072
	ds_read_b128 v[136:139], v225
	ds_read_b128 v[140:143], v225 offset:1024
	ds_read_b128 v[152:155], v225 offset:2048
	ds_read_b128 v[156:159], v225 offset:3072
	s_add_i32 s50, s42, 2
	s_add_u32 s40, s38, 0xfff80080
	s_addc_u32 s41, s39, -1
	s_cmp_eq_u32 s33, s42
	s_cselect_b32 s42, s5, s40
	s_cselect_b32 s43, s1, s41
	s_cselect_b32 s41, s21, s49
	s_cselect_b32 s40, s23, s48
	v_lshl_add_u64 v[208:209], s[38:39], 0, v[202:203]
	s_add_i32 m0, s53, 0xc000
	ds_read_b128 v[160:163], v226
	ds_read_b128 v[164:167], v226 offset:1024
	ds_read_b128 v[168:171], v226 offset:2048
	ds_read_b128 v[172:175], v226 offset:3072
	ds_read_b128 v[176:179], v226 offset:4096
	ds_read_b128 v[180:183], v226 offset:5120
	ds_read_b128 v[184:187], v226 offset:6144
	ds_read_b128 v[188:191], v226 offset:7168
	global_load_lds_dwordx4 v[208:209], off
	v_lshl_add_u64 v[208:209], s[38:39], 0, v[204:205]
	s_add_i32 m0, s53, 0xe000
	s_nop 0
	global_load_lds_dwordx4 v[208:209], off
	s_waitcnt vmcnt(8)
	s_waitcnt lgkmcnt(0)
	s_setprio 1
	s_barrier
	v_mfma_f32_16x16x32_bf16 v[148:151], v[104:107], v[160:163], 0
	v_mfma_f32_16x16x32_bf16 v[144:147], v[120:123], v[160:163], 0
	v_mfma_f32_16x16x32_bf16 v[116:119], v[104:107], v[168:171], 0
	v_mfma_f32_16x16x32_bf16 v[112:115], v[120:123], v[168:171], 0
	v_mfma_f32_16x16x32_bf16 v[92:95], v[104:107], v[176:179], 0
	v_mfma_f32_16x16x32_bf16 v[88:91], v[120:123], v[176:179], 0
	v_mfma_f32_16x16x32_bf16 v[76:79], v[104:107], v[184:187], 0
	v_mfma_f32_16x16x32_bf16 v[72:75], v[120:123], v[184:187], 0
	v_mfma_f32_16x16x32_bf16 v[148:151], v[108:111], v[164:167], v[148:151]
	v_mfma_f32_16x16x32_bf16 v[144:147], v[124:127], v[164:167], v[144:147]
	v_mfma_f32_16x16x32_bf16 v[116:119], v[108:111], v[172:175], v[116:119]
	v_mfma_f32_16x16x32_bf16 v[112:115], v[124:127], v[172:175], v[112:115]
	v_mfma_f32_16x16x32_bf16 v[92:95], v[108:111], v[180:183], v[92:95]
	v_mfma_f32_16x16x32_bf16 v[88:91], v[124:127], v[180:183], v[88:91]
	v_mfma_f32_16x16x32_bf16 v[76:79], v[108:111], v[188:191], v[76:79]
	v_mfma_f32_16x16x32_bf16 v[72:75], v[124:127], v[188:191], v[72:75]
	v_mfma_f32_16x16x32_bf16 v[132:135], v[136:139], v[160:163], 0
	v_mfma_f32_16x16x32_bf16 v[128:131], v[152:155], v[160:163], 0
	v_mfma_f32_16x16x32_bf16 v[100:103], v[136:139], v[168:171], 0
	v_mfma_f32_16x16x32_bf16 v[96:99], v[152:155], v[168:171], 0
	v_mfma_f32_16x16x32_bf16 v[84:87], v[136:139], v[176:179], 0
	v_mfma_f32_16x16x32_bf16 v[80:83], v[152:155], v[176:179], 0
	v_mfma_f32_16x16x32_bf16 v[68:71], v[136:139], v[184:187], 0
	v_mfma_f32_16x16x32_bf16 v[64:67], v[152:155], v[184:187], 0
	v_mfma_f32_16x16x32_bf16 v[132:135], v[140:143], v[164:167], v[132:135]
	v_mfma_f32_16x16x32_bf16 v[128:131], v[156:159], v[164:167], v[128:131]
	v_mfma_f32_16x16x32_bf16 v[100:103], v[140:143], v[172:175], v[100:103]
	v_mfma_f32_16x16x32_bf16 v[96:99], v[156:159], v[172:175], v[96:99]
	v_mfma_f32_16x16x32_bf16 v[84:87], v[140:143], v[180:183], v[84:87]
	v_mfma_f32_16x16x32_bf16 v[80:83], v[156:159], v[180:183], v[80:83]
	v_mfma_f32_16x16x32_bf16 v[68:71], v[140:143], v[188:191], v[68:71]
	v_mfma_f32_16x16x32_bf16 v[64:67], v[156:159], v[188:191], v[64:67]
	s_barrier
	s_setprio 0
	s_add_i32 s51, s75, s52
	v_lshl_add_u64 v[208:209], s[40:41], 0, v[196:197]
	s_mov_b32 m0, s51
	ds_read_b128 v[160:163], v226 offset:16384
	ds_read_b128 v[164:167], v226 offset:17408
	ds_read_b128 v[168:171], v226 offset:18432
	ds_read_b128 v[172:175], v226 offset:19456
	ds_read_b128 v[176:179], v226 offset:20480
	ds_read_b128 v[180:183], v226 offset:21504
	ds_read_b128 v[184:187], v226 offset:22528
	ds_read_b128 v[188:191], v226 offset:23552
	global_load_lds_dwordx4 v[208:209], off
	s_add_i32 m0, s51, 0x2000
	s_add_u32 s70, s40, 0x80000
	v_lshl_add_u64 v[210:211], s[40:41], 0, v[200:201]
	s_addc_u32 s71, s41, 0
	s_add_i32 s51, s78, s52
	global_load_lds_dwordx4 v[210:211], off
	v_lshl_add_u64 v[212:213], s[70:71], 0, v[196:197]
	s_mov_b32 m0, s51
	v_lshl_add_u64 v[214:215], s[42:43], 0, v[198:199]
	global_load_lds_dwordx4 v[212:213], off
	v_lshl_add_u64 v[212:213], s[70:71], 0, v[200:201]
	s_add_i32 m0, s51, 0x2000
	s_nop 0
	global_load_lds_dwordx4 v[212:213], off
	v_lshl_add_u64 v[212:213], s[42:43], 0, v[194:195]
	s_mov_b32 m0, s53
	s_nop 0
	global_load_lds_dwordx4 v[212:213], off
	s_mov_b32 m0, s54
	s_nop 0
	global_load_lds_dwordx4 v[214:215], off
	s_waitcnt vmcnt(8)
	s_waitcnt lgkmcnt(0)
	s_setprio 1
	s_barrier
; #define PG8_STAGE(bufoff, gbase, voff) do { _Pragma("unroll") for (int _i = 0; _i < 2; ++_i) \
;         __builtin_amdgcn_global_load_lds((const unsigned*)((const char*)(gbase) + (voff)[_i]), (LAS unsigned*)(lds + (bufoff) + ldsw + _i * 8192), 16, 0, 0); } while (0)
; #define PG8_LDA(dst, b, h) do { _Pragma("unroll") for (int m = 0; m < 4; ++m) _Pragma("unroll") for (int k = 0; k < 2; ++k) dst[m][k] = *(const LAS bf16x8*)(lds + PG8_SA(b, h) + aoff + m * 2048 + k * 1024); } while (0)
; #define PG8_LDB(dst, b, h) do { _Pragma("unroll") for (int n = 0; n < 2; ++n) _Pragma("unroll") for (int k = 0; k < 2; ++k) dst[n][k] = *(const LAS bf16x8*)(lds + PG8_SB(b, h) + boff + n * 2048 + k * 1024); } while (0)
; #define PG8_MMA(ai, bj, At, Bt) do { __builtin_amdgcn_s_setprio(1); _Pragma("unroll") for (int m = 0; m < 4; ++m) _Pragma("unroll") for (int n = 0; n < 2; ++n) _Pragma("unroll") for (int k = 0; k < 2; ++k) \
;         acc[ai][bj][m][n] = __builtin_amdgcn_mfma_f32_16x16x32_bf16(Bt[n][k], At[m][k], acc[ai][bj][m][n], 0, 0, 0); __builtin_amdgcn_s_setprio(0); } while (0)
; #define PG8_WAIT_V(n) asm volatile("s_waitcnt vmcnt(" #n ")" ::: "memory")
; #define PG8_WAIT_L(n) asm volatile("s_waitcnt lgkmcnt(" #n ")" ::: "memory")
; #define PG8_BAR __builtin_amdgcn_s_barrier()
; #define PG8_SCHED __builtin_amdgcn_sched_barrier(0)
; template <class Epi, class Sched = StaticOrder, class EpiSub = NoSub, bool FAST = false>
; __device__ __forceinline__ void gemm_phase(LAS unsigned char* lds, const Gemm g, const Sched& S, const Epi& E, const EpiSub& ES = EpiSub()) {
;     ...
;             PG8_WAIT_V(8); PG8_WAIT_L(0); PG8_BAR; PG8_MMA(1, 0, At, B0); PG8_MMA(1, 1, At, B1); PG8_BAR; PG8_SCHED;
;             PG8_LDB(B0, 1, 0); PG8_LDB(B1, 1, 1); PG8_SCHED; PG8_LDA(At, 1, 0); PG8_STAGE(PG8_SA(0, 1), a2 + hstepA, voffA);
;             PG8_WAIT_V(8); PG8_WAIT_L(0); PG8_BAR; PG8_MMA(0, 0, At, B0); PG8_MMA(0, 1, At, B1); PG8_BAR; PG8_SCHED;
	v_mfma_f32_16x16x32_bf16 v[60:63], v[104:107], v[160:163], 0
	v_mfma_f32_16x16x32_bf16 v[56:59], v[120:123], v[160:163], 0
	v_mfma_f32_16x16x32_bf16 v[44:47], v[104:107], v[168:171], 0
	v_mfma_f32_16x16x32_bf16 v[40:43], v[120:123], v[168:171], 0
	v_mfma_f32_16x16x32_bf16 v[28:31], v[104:107], v[176:179], 0
	v_mfma_f32_16x16x32_bf16 v[24:27], v[120:123], v[176:179], 0
	v_mfma_f32_16x16x32_bf16 v[12:15], v[104:107], v[184:187], 0
	v_mfma_f32_16x16x32_bf16 v[8:11], v[120:123], v[184:187], 0
	v_mfma_f32_16x16x32_bf16 v[60:63], v[108:111], v[164:167], v[60:63]
	v_mfma_f32_16x16x32_bf16 v[56:59], v[124:127], v[164:167], v[56:59]
	v_mfma_f32_16x16x32_bf16 v[44:47], v[108:111], v[172:175], v[44:47]
	v_mfma_f32_16x16x32_bf16 v[40:43], v[124:127], v[172:175], v[40:43]
	v_mfma_f32_16x16x32_bf16 v[28:31], v[108:111], v[180:183], v[28:31]
	v_mfma_f32_16x16x32_bf16 v[24:27], v[124:127], v[180:183], v[24:27]
	v_mfma_f32_16x16x32_bf16 v[12:15], v[108:111], v[188:191], v[12:15]
	v_mfma_f32_16x16x32_bf16 v[8:11], v[124:127], v[188:191], v[8:11]
	v_mfma_f32_16x16x32_bf16 v[52:55], v[136:139], v[160:163], 0
	v_mfma_f32_16x16x32_bf16 v[48:51], v[152:155], v[160:163], 0
	v_mfma_f32_16x16x32_bf16 v[36:39], v[136:139], v[168:171], 0
	v_mfma_f32_16x16x32_bf16 v[32:35], v[152:155], v[168:171], 0
	v_mfma_f32_16x16x32_bf16 v[20:23], v[136:139], v[176:179], 0
	v_mfma_f32_16x16x32_bf16 v[16:19], v[152:155], v[176:179], 0
	v_mfma_f32_16x16x32_bf16 v[4:7], v[136:139], v[184:187], 0
	v_mfma_f32_16x16x32_bf16 v[0:3], v[152:155], v[184:187], 0
	v_mfma_f32_16x16x32_bf16 v[52:55], v[140:143], v[164:167], v[52:55]
	v_mfma_f32_16x16x32_bf16 v[48:51], v[156:159], v[164:167], v[48:51]
	v_mfma_f32_16x16x32_bf16 v[36:39], v[140:143], v[172:175], v[36:39]
	v_mfma_f32_16x16x32_bf16 v[32:35], v[156:159], v[172:175], v[32:35]
	v_mfma_f32_16x16x32_bf16 v[20:23], v[140:143], v[180:183], v[20:23]
	v_mfma_f32_16x16x32_bf16 v[16:19], v[156:159], v[180:183], v[16:19]
	v_mfma_f32_16x16x32_bf16 v[4:7], v[140:143], v[188:191], v[4:7]
	v_mfma_f32_16x16x32_bf16 v[0:3], v[156:159], v[188:191], v[0:3]
	s_barrier
	s_setprio 0
	s_add_i32 s51, 0, 0x18000
	s_add_i32 s70, 0, 0x1c000
	v_add_u32_e32 v124, s51, v221
	v_add_u32_e32 v156, s70, v221
	ds_read_b128 v[104:107], v124
	ds_read_b128 v[108:111], v124 offset:1024
	ds_read_b128 v[120:123], v124 offset:2048
	ds_read_b128 v[124:127], v124 offset:3072
	ds_read_b128 v[136:139], v156
	ds_read_b128 v[140:143], v156 offset:1024
	ds_read_b128 v[152:155], v156 offset:2048
	ds_read_b128 v[156:159], v156 offset:3072
	s_add_u32 s42, s42, 0x80000
	s_addc_u32 s43, s43, 0
	s_mov_b32 m0, s55
	v_lshl_add_u64 v[216:217], s[42:43], 0, v[194:195]
	ds_read_b128 v[160:163], v226 offset:32768
	ds_read_b128 v[164:167], v226 offset:33792
	ds_read_b128 v[168:171], v226 offset:34816
	ds_read_b128 v[172:175], v226 offset:35840
	ds_read_b128 v[176:179], v226 offset:36864
	ds_read_b128 v[180:183], v226 offset:37888
	ds_read_b128 v[184:187], v226 offset:38912
	ds_read_b128 v[188:191], v226 offset:39936
	global_load_lds_dwordx4 v[216:217], off
	v_lshl_add_u64 v[216:217], s[42:43], 0, v[198:199]
	s_mov_b32 m0, s56
	s_nop 0
	global_load_lds_dwordx4 v[216:217], off
	s_waitcnt vmcnt(8)
	s_waitcnt lgkmcnt(0)
	s_setprio 1
	s_barrier
	v_mfma_f32_16x16x32_bf16 v[148:151], v[104:107], v[160:163], v[148:151]
	v_mfma_f32_16x16x32_bf16 v[144:147], v[120:123], v[160:163], v[144:147]
	v_mfma_f32_16x16x32_bf16 v[116:119], v[104:107], v[168:171], v[116:119]
	v_mfma_f32_16x16x32_bf16 v[112:115], v[120:123], v[168:171], v[112:115]
	v_mfma_f32_16x16x32_bf16 v[92:95], v[104:107], v[176:179], v[92:95]
	v_mfma_f32_16x16x32_bf16 v[88:91], v[120:123], v[176:179], v[88:91]
	v_mfma_f32_16x16x32_bf16 v[76:79], v[104:107], v[184:187], v[76:79]
	v_mfma_f32_16x16x32_bf16 v[72:75], v[120:123], v[184:187], v[72:75]
	v_mfma_f32_16x16x32_bf16 v[148:151], v[108:111], v[164:167], v[148:151]
	v_mfma_f32_16x16x32_bf16 v[144:147], v[124:127], v[164:167], v[144:147]
	v_mfma_f32_16x16x32_bf16 v[116:119], v[108:111], v[172:175], v[116:119]
	v_mfma_f32_16x16x32_bf16 v[112:115], v[124:127], v[172:175], v[112:115]
	v_mfma_f32_16x16x32_bf16 v[92:95], v[108:111], v[180:183], v[92:95]
	v_mfma_f32_16x16x32_bf16 v[88:91], v[124:127], v[180:183], v[88:91]
	v_mfma_f32_16x16x32_bf16 v[76:79], v[108:111], v[188:191], v[76:79]
	v_mfma_f32_16x16x32_bf16 v[72:75], v[124:127], v[188:191], v[72:75]
	v_mfma_f32_16x16x32_bf16 v[132:135], v[136:139], v[160:163], v[132:135]
	v_mfma_f32_16x16x32_bf16 v[128:131], v[152:155], v[160:163], v[128:131]
	v_mfma_f32_16x16x32_bf16 v[100:103], v[136:139], v[168:171], v[100:103]
	v_mfma_f32_16x16x32_bf16 v[96:99], v[152:155], v[168:171], v[96:99]
	v_mfma_f32_16x16x32_bf16 v[84:87], v[136:139], v[176:179], v[84:87]
	v_mfma_f32_16x16x32_bf16 v[80:83], v[152:155], v[176:179], v[80:83]
	v_mfma_f32_16x16x32_bf16 v[68:71], v[136:139], v[184:187], v[68:71]
	v_mfma_f32_16x16x32_bf16 v[64:67], v[152:155], v[184:187], v[64:67]
	v_mfma_f32_16x16x32_bf16 v[132:135], v[140:143], v[164:167], v[132:135]
	v_mfma_f32_16x16x32_bf16 v[128:131], v[156:159], v[164:167], v[128:131]
	v_mfma_f32_16x16x32_bf16 v[100:103], v[140:143], v[172:175], v[100:103]
	v_mfma_f32_16x16x32_bf16 v[96:99], v[156:159], v[172:175], v[96:99]
	v_mfma_f32_16x16x32_bf16 v[84:87], v[140:143], v[180:183], v[84:87]
	v_mfma_f32_16x16x32_bf16 v[80:83], v[156:159], v[180:183], v[80:83]
	v_mfma_f32_16x16x32_bf16 v[68:71], v[140:143], v[188:191], v[68:71]
	v_mfma_f32_16x16x32_bf16 v[64:67], v[156:159], v[188:191], v[64:67]
	s_barrier
; #define PG8_STAGE(bufoff, gbase, voff) do { _Pragma("unroll") for (int _i = 0; _i < 2; ++_i) \
;         __builtin_amdgcn_global_load_lds((const unsigned*)((const char*)(gbase) + (voff)[_i]), (LAS unsigned*)(lds + (bufoff) + ldsw + _i * 8192), 16, 0, 0); } while (0)
; #define PG8_LDA(dst, b, h) do { _Pragma("unroll") for (int m = 0; m < 4; ++m) _Pragma("unroll") for (int k = 0; k < 2; ++k) dst[m][k] = *(const LAS bf16x8*)(lds + PG8_SA(b, h) + aoff + m * 2048 + k * 1024); } while (0)
; #define PG8_LDB(dst, b, h) do { _Pragma("unroll") for (int n = 0; n < 2; ++n) _Pragma("unroll") for (int k = 0; k < 2; ++k) dst[n][k] = *(const LAS bf16x8*)(lds + PG8_SB(b, h) + boff + n * 2048 + k * 1024); } while (0)
; template <class Epi, class Sched = StaticOrder, class EpiSub = NoSub, bool FAST = false>
; __device__ __forceinline__ void gemm_phase(LAS unsigned char* lds, const Gemm g, const Sched& S, const Epi& E, const EpiSub& ES = EpiSub()) {
;     ...
;         for (int t = 0; t < nt; t += 2) {
;             const bool last = (t == nt - 2);
;             const char* a1 = cA + (size_t)(t + 1) * kstep;
;             const char* a2 = last ? nA : cA + (size_t)(t + 2) * kstep; const char* b2 = last ? nB : cB + (size_t)(t + 2) * kstep;
;             const char* a3 = a2 + kstep; const char* b3 = b2 + kstep;
;             if constexpr (FAST && PG8_SP2) {
;             PG8_LDB(B0, 0, 0); PG8_LDB(B1, 0, 1); PG8_SCHED; PG8_LDA(At, 0, 0); PG8_STAGE(PG8_SA(1, 1), a1 + hstepA, voffA);
;             PG8_WAIT_V(8); PG8_WAIT_L(0); PG8_BAR; PG8_MMA(0, 0, At, B0); PG8_MMA(0, 1, At, B1); PG8_BAR; PG8_SCHED;
;             PG8_LDA(At, 0, 1); PG8_STAGE(PG8_SB(0, 0), b2, voffB); PG8_STAGE(PG8_SB(0, 1), b2 + hstepB, voffB); PG8_STAGE(PG8_SA(0, 0), a2, voffA);
;             PG8_WAIT_V(8); PG8_WAIT_L(0); PG8_BAR; PG8_MMA(1, 0, At, B0); PG8_MMA(1, 1, At, B1); PG8_BAR; PG8_SCHED;
;             PG8_LDB(B0, 1, 0); PG8_LDB(B1, 1, 1); PG8_SCHED; PG8_LDA(At, 1, 0); PG8_STAGE(PG8_SA(0, 1), a2 + hstepA, voffA);
;             PG8_WAIT_V(8); PG8_WAIT_L(0); PG8_BAR; PG8_MMA(0, 0, At, B0); PG8_MMA(0, 1, At, B1); PG8_BAR; PG8_SCHED;
;             PG8_LDA(At, 1, 1); PG8_STAGE(PG8_SB(1, 0), b3, voffB); PG8_STAGE(PG8_SB(1, 1), b3 + hstepB, voffB); PG8_STAGE(PG8_SA(1, 0), a3, voffA);
;             PG8_WAIT_V(8); PG8_WAIT_L(0); PG8_BAR; PG8_MMA(1, 0, At, B0); PG8_MMA(1, 1, At, B1); PG8_BAR; PG8_SCHED;
	s_setprio 0
	s_add_i32 s42, s51, s52
	v_lshl_add_u64 v[208:209], v[208:209], 0, s[12:13]
	s_mov_b32 m0, s42
	ds_read_b128 v[160:163], v226 offset:49152
	ds_read_b128 v[164:167], v226 offset:50176
	ds_read_b128 v[168:171], v226 offset:51200
	ds_read_b128 v[172:175], v226 offset:52224
	ds_read_b128 v[176:179], v226 offset:53248
	ds_read_b128 v[180:183], v226 offset:54272
	ds_read_b128 v[184:187], v226 offset:55296
	ds_read_b128 v[188:191], v226 offset:56320
	global_load_lds_dwordx4 v[208:209], off
	s_add_i32 m0, s42, 0x2000
	s_add_u32 s40, s40, 0x80080
	v_lshl_add_u64 v[208:209], v[210:211], 0, s[12:13]
	s_addc_u32 s41, s41, 0
	s_add_i32 s42, s70, s52
	global_load_lds_dwordx4 v[208:209], off
	v_lshl_add_u64 v[208:209], s[40:41], 0, v[196:197]
	s_mov_b32 m0, s42
	s_nop 0
	global_load_lds_dwordx4 v[208:209], off
	v_lshl_add_u64 v[208:209], s[40:41], 0, v[200:201]
	s_add_i32 m0, s42, 0x2000
	s_nop 0
	global_load_lds_dwordx4 v[208:209], off
	v_lshl_add_u64 v[208:209], v[212:213], 0, s[12:13]
	s_mov_b32 m0, s69
	s_nop 0
	global_load_lds_dwordx4 v[208:209], off
	v_lshl_add_u64 v[208:209], v[214:215], 0, s[12:13]
	s_mov_b32 m0, s74
	s_nop 0
	global_load_lds_dwordx4 v[208:209], off
	s_waitcnt vmcnt(8)
	s_waitcnt lgkmcnt(0)
	s_setprio 1
	s_barrier
	v_mfma_f32_16x16x32_bf16 v[60:63], v[104:107], v[160:163], v[60:63]
	v_mfma_f32_16x16x32_bf16 v[56:59], v[120:123], v[160:163], v[56:59]
	v_mfma_f32_16x16x32_bf16 v[44:47], v[104:107], v[168:171], v[44:47]
	v_mfma_f32_16x16x32_bf16 v[40:43], v[120:123], v[168:171], v[40:43]
	v_mfma_f32_16x16x32_bf16 v[28:31], v[104:107], v[176:179], v[28:31]
	v_mfma_f32_16x16x32_bf16 v[24:27], v[120:123], v[176:179], v[24:27]
	v_mfma_f32_16x16x32_bf16 v[12:15], v[104:107], v[184:187], v[12:15]
	v_mfma_f32_16x16x32_bf16 v[8:11], v[120:123], v[184:187], v[8:11]
	v_mfma_f32_16x16x32_bf16 v[60:63], v[108:111], v[164:167], v[60:63]
	v_mfma_f32_16x16x32_bf16 v[56:59], v[124:127], v[164:167], v[56:59]
	v_mfma_f32_16x16x32_bf16 v[44:47], v[108:111], v[172:175], v[44:47]
	v_mfma_f32_16x16x32_bf16 v[40:43], v[124:127], v[172:175], v[40:43]
	v_mfma_f32_16x16x32_bf16 v[28:31], v[108:111], v[180:183], v[28:31]
	v_mfma_f32_16x16x32_bf16 v[24:27], v[124:127], v[180:183], v[24:27]
	v_mfma_f32_16x16x32_bf16 v[12:15], v[108:111], v[188:191], v[12:15]
	v_mfma_f32_16x16x32_bf16 v[8:11], v[124:127], v[188:191], v[8:11]
	v_mfma_f32_16x16x32_bf16 v[52:55], v[136:139], v[160:163], v[52:55]
	v_mfma_f32_16x16x32_bf16 v[48:51], v[152:155], v[160:163], v[48:51]
	v_mfma_f32_16x16x32_bf16 v[36:39], v[136:139], v[168:171], v[36:39]
	v_mfma_f32_16x16x32_bf16 v[32:35], v[152:155], v[168:171], v[32:35]
	v_mfma_f32_16x16x32_bf16 v[20:23], v[136:139], v[176:179], v[20:23]
	v_mfma_f32_16x16x32_bf16 v[16:19], v[152:155], v[176:179], v[16:19]
	v_mfma_f32_16x16x32_bf16 v[4:7], v[136:139], v[184:187], v[4:7]
	v_mfma_f32_16x16x32_bf16 v[0:3], v[152:155], v[184:187], v[0:3]
	v_mfma_f32_16x16x32_bf16 v[52:55], v[140:143], v[164:167], v[52:55]
	v_mfma_f32_16x16x32_bf16 v[48:51], v[156:159], v[164:167], v[48:51]
	v_mfma_f32_16x16x32_bf16 v[36:39], v[140:143], v[172:175], v[36:39]
	v_mfma_f32_16x16x32_bf16 v[32:35], v[156:159], v[172:175], v[32:35]
	v_mfma_f32_16x16x32_bf16 v[20:23], v[140:143], v[180:183], v[20:23]
	v_mfma_f32_16x16x32_bf16 v[16:19], v[156:159], v[180:183], v[16:19]
	v_mfma_f32_16x16x32_bf16 v[4:7], v[140:143], v[188:191], v[4:7]
	v_mfma_f32_16x16x32_bf16 v[0:3], v[156:159], v[188:191], v[0:3]
	s_barrier
	s_setprio 0
	s_add_u32 s38, s38, 0x100
	s_addc_u32 s39, s39, 0
	s_add_u32 s48, s48, 0x100
	s_addc_u32 s49, s49, 0
	s_cmp_ge_u32 s50, s31
	s_mov_b32 s42, s50
	s_cbranch_scc1 .Lkpeel_632_exit
.LBB0_632:
	ds_read_b128 v[104:107], v224
	ds_read_b128 v[108:111], v224 offset:1024
	ds_read_b128 v[120:123], v224 offset:2048
	ds_read_b128 v[124:127], v224 offset:3072
	ds_read_b128 v[136:139], v225
	ds_read_b128 v[140:143], v225 offset:1024
	ds_read_b128 v[152:155], v225 offset:2048
	ds_read_b128 v[156:159], v225 offset:3072
	s_add_i32 s50, s42, 2
	s_add_u32 s40, s38, 0xfff80080
	s_addc_u32 s41, s39, -1
	s_cmp_eq_u32 s33, s42
	s_cselect_b32 s42, s5, s40
	s_cselect_b32 s43, s1, s41
	s_cselect_b32 s41, s21, s49
	s_cselect_b32 s40, s23, s48
	v_lshl_add_u64 v[208:209], s[38:39], 0, v[202:203]
	s_add_i32 m0, s53, 0xc000
	ds_read_b128 v[160:163], v226
	ds_read_b128 v[164:167], v226 offset:1024
	ds_read_b128 v[168:171], v226 offset:2048
	ds_read_b128 v[172:175], v226 offset:3072
	ds_read_b128 v[176:179], v226 offset:4096
	ds_read_b128 v[180:183], v226 offset:5120
	ds_read_b128 v[184:187], v226 offset:6144
	ds_read_b128 v[188:191], v226 offset:7168
	global_load_lds_dwordx4 v[208:209], off
	v_lshl_add_u64 v[208:209], s[38:39], 0, v[204:205]
	s_add_i32 m0, s53, 0xe000
	s_nop 0
	global_load_lds_dwordx4 v[208:209], off
	s_waitcnt vmcnt(8)
	s_waitcnt lgkmcnt(0)
	s_setprio 1
	s_barrier
; #define PG8_STAGE(bufoff, gbase, voff) do { _Pragma("unroll") for (int _i = 0; _i < 2; ++_i) \
;         __builtin_amdgcn_global_load_lds((const unsigned*)((const char*)(gbase) + (voff)[_i]), (LAS unsigned*)(lds + (bufoff) + ldsw + _i * 8192), 16, 0, 0); } while (0)
; #define PG8_LDA(dst, b, h) do { _Pragma("unroll") for (int m = 0; m < 4; ++m) _Pragma("unroll") for (int k = 0; k < 2; ++k) dst[m][k] = *(const LAS bf16x8*)(lds + PG8_SA(b, h) + aoff + m * 2048 + k * 1024); } while (0)
; #define PG8_LDB(dst, b, h) do { _Pragma("unroll") for (int n = 0; n < 2; ++n) _Pragma("unroll") for (int k = 0; k < 2; ++k) dst[n][k] = *(const LAS bf16x8*)(lds + PG8_SB(b, h) + boff + n * 2048 + k * 1024); } while (0)
; #define PG8_MMA(ai, bj, At, Bt) do { __builtin_amdgcn_s_setprio(1); _Pragma("unroll") for (int m = 0; m < 4; ++m) _Pragma("unroll") for (int n = 0; n < 2; ++n) _Pragma("unroll") for (int k = 0; k < 2; ++k) \
;         acc[ai][bj][m][n] = __builtin_amdgcn_mfma_f32_16x16x32_bf16(Bt[n][k], At[m][k], acc[ai][bj][m][n], 0, 0, 0); __builtin_amdgcn_s_setprio(0); } while (0)
; #define PG8_WAIT_V(n) asm volatile("s_waitcnt vmcnt(" #n ")" ::: "memory")
; #define PG8_WAIT_L(n) asm volatile("s_waitcnt lgkmcnt(" #n ")" ::: "memory")
; #define PG8_BAR __builtin_amdgcn_s_barrier()
; #define PG8_SCHED __builtin_amdgcn_sched_barrier(0)
; template <class Epi, class Sched = StaticOrder, class EpiSub = NoSub, bool FAST = false>
; __device__ __forceinline__ void gemm_phase(LAS unsigned char* lds, const Gemm g, const Sched& S, const Epi& E, const EpiSub& ES = EpiSub()) {
;     ...
;             PG8_LDB(B0, 0, 0); PG8_LDB(B1, 0, 1); PG8_SCHED; PG8_LDA(At, 0, 0); PG8_STAGE(PG8_SA(1, 1), a1 + hstepA, voffA);
;             PG8_WAIT_V(8); PG8_WAIT_L(0); PG8_BAR; PG8_MMA(0, 0, At, B0); PG8_MMA(0, 1, At, B1); PG8_BAR; PG8_SCHED;
;             PG8_LDA(At, 0, 1); PG8_STAGE(PG8_SB(0, 0), b2, voffB); PG8_STAGE(PG8_SB(0, 1), b2 + hstepB, voffB); PG8_STAGE(PG8_SA(0, 0), a2, voffA);
;             PG8_WAIT_V(8); PG8_WAIT_L(0); PG8_BAR; PG8_MMA(1, 0, At, B0); PG8_MMA(1, 1, At, B1); PG8_BAR; PG8_SCHED;
	v_mfma_f32_16x16x32_bf16 v[148:151], v[104:107], v[160:163], v[148:151]
	v_mfma_f32_16x16x32_bf16 v[144:147], v[120:123], v[160:163], v[144:147]
	v_mfma_f32_16x16x32_bf16 v[116:119], v[104:107], v[168:171], v[116:119]
	v_mfma_f32_16x16x32_bf16 v[112:115], v[120:123], v[168:171], v[112:115]
	v_mfma_f32_16x16x32_bf16 v[92:95], v[104:107], v[176:179], v[92:95]
	v_mfma_f32_16x16x32_bf16 v[88:91], v[120:123], v[176:179], v[88:91]
	v_mfma_f32_16x16x32_bf16 v[76:79], v[104:107], v[184:187], v[76:79]
	v_mfma_f32_16x16x32_bf16 v[72:75], v[120:123], v[184:187], v[72:75]
	v_mfma_f32_16x16x32_bf16 v[148:151], v[108:111], v[164:167], v[148:151]
	v_mfma_f32_16x16x32_bf16 v[144:147], v[124:127], v[164:167], v[144:147]
	v_mfma_f32_16x16x32_bf16 v[116:119], v[108:111], v[172:175], v[116:119]
	v_mfma_f32_16x16x32_bf16 v[112:115], v[124:127], v[172:175], v[112:115]
	v_mfma_f32_16x16x32_bf16 v[92:95], v[108:111], v[180:183], v[92:95]
	v_mfma_f32_16x16x32_bf16 v[88:91], v[124:127], v[180:183], v[88:91]
	v_mfma_f32_16x16x32_bf16 v[76:79], v[108:111], v[188:191], v[76:79]
	v_mfma_f32_16x16x32_bf16 v[72:75], v[124:127], v[188:191], v[72:75]
	v_mfma_f32_16x16x32_bf16 v[132:135], v[136:139], v[160:163], v[132:135]
	v_mfma_f32_16x16x32_bf16 v[128:131], v[152:155], v[160:163], v[128:131]
	v_mfma_f32_16x16x32_bf16 v[100:103], v[136:139], v[168:171], v[100:103]
	v_mfma_f32_16x16x32_bf16 v[96:99], v[152:155], v[168:171], v[96:99]
	v_mfma_f32_16x16x32_bf16 v[84:87], v[136:139], v[176:179], v[84:87]
	v_mfma_f32_16x16x32_bf16 v[80:83], v[152:155], v[176:179], v[80:83]
	v_mfma_f32_16x16x32_bf16 v[68:71], v[136:139], v[184:187], v[68:71]
	v_mfma_f32_16x16x32_bf16 v[64:67], v[152:155], v[184:187], v[64:67]
	v_mfma_f32_16x16x32_bf16 v[132:135], v[140:143], v[164:167], v[132:135]
	v_mfma_f32_16x16x32_bf16 v[128:131], v[156:159], v[164:167], v[128:131]
	v_mfma_f32_16x16x32_bf16 v[100:103], v[140:143], v[172:175], v[100:103]
	v_mfma_f32_16x16x32_bf16 v[96:99], v[156:159], v[172:175], v[96:99]
	v_mfma_f32_16x16x32_bf16 v[84:87], v[140:143], v[180:183], v[84:87]
	v_mfma_f32_16x16x32_bf16 v[80:83], v[156:159], v[180:183], v[80:83]
	v_mfma_f32_16x16x32_bf16 v[68:71], v[140:143], v[188:191], v[68:71]
	v_mfma_f32_16x16x32_bf16 v[64:67], v[156:159], v[188:191], v[64:67]
	s_barrier
	s_setprio 0
	s_add_i32 s51, s75, s52
	v_lshl_add_u64 v[208:209], s[40:41], 0, v[196:197]
	s_mov_b32 m0, s51
	ds_read_b128 v[160:163], v226 offset:16384
	ds_read_b128 v[164:167], v226 offset:17408
	ds_read_b128 v[168:171], v226 offset:18432
	ds_read_b128 v[172:175], v226 offset:19456
	ds_read_b128 v[176:179], v226 offset:20480
	ds_read_b128 v[180:183], v226 offset:21504
	ds_read_b128 v[184:187], v226 offset:22528
	ds_read_b128 v[188:191], v226 offset:23552
	global_load_lds_dwordx4 v[208:209], off
	s_add_i32 m0, s51, 0x2000
	s_add_u32 s70, s40, 0x80000
	v_lshl_add_u64 v[210:211], s[40:41], 0, v[200:201]
	s_addc_u32 s71, s41, 0
	s_add_i32 s51, s78, s52
	global_load_lds_dwordx4 v[210:211], off
	v_lshl_add_u64 v[212:213], s[70:71], 0, v[196:197]
	s_mov_b32 m0, s51
	v_lshl_add_u64 v[214:215], s[42:43], 0, v[198:199]
	global_load_lds_dwordx4 v[212:213], off
	v_lshl_add_u64 v[212:213], s[70:71], 0, v[200:201]
	s_add_i32 m0, s51, 0x2000
	s_nop 0
	global_load_lds_dwordx4 v[212:213], off
	v_lshl_add_u64 v[212:213], s[42:43], 0, v[194:195]
	s_mov_b32 m0, s53
	s_nop 0
	global_load_lds_dwordx4 v[212:213], off
	s_mov_b32 m0, s54
	s_nop 0
	global_load_lds_dwordx4 v[214:215], off
	s_waitcnt vmcnt(8)
	s_waitcnt lgkmcnt(0)
	s_setprio 1
	s_barrier
	v_mfma_f32_16x16x32_bf16 v[60:63], v[104:107], v[160:163], v[60:63]
	v_mfma_f32_16x16x32_bf16 v[56:59], v[120:123], v[160:163], v[56:59]
	v_mfma_f32_16x16x32_bf16 v[44:47], v[104:107], v[168:171], v[44:47]
	v_mfma_f32_16x16x32_bf16 v[40:43], v[120:123], v[168:171], v[40:43]
	v_mfma_f32_16x16x32_bf16 v[28:31], v[104:107], v[176:179], v[28:31]
	v_mfma_f32_16x16x32_bf16 v[24:27], v[120:123], v[176:179], v[24:27]
	v_mfma_f32_16x16x32_bf16 v[12:15], v[104:107], v[184:187], v[12:15]
	v_mfma_f32_16x16x32_bf16 v[8:11], v[120:123], v[184:187], v[8:11]
	v_mfma_f32_16x16x32_bf16 v[60:63], v[108:111], v[164:167], v[60:63]
	v_mfma_f32_16x16x32_bf16 v[56:59], v[124:127], v[164:167], v[56:59]
	v_mfma_f32_16x16x32_bf16 v[44:47], v[108:111], v[172:175], v[44:47]
	v_mfma_f32_16x16x32_bf16 v[40:43], v[124:127], v[172:175], v[40:43]
	v_mfma_f32_16x16x32_bf16 v[28:31], v[108:111], v[180:183], v[28:31]
	v_mfma_f32_16x16x32_bf16 v[24:27], v[124:127], v[180:183], v[24:27]
	v_mfma_f32_16x16x32_bf16 v[12:15], v[108:111], v[188:191], v[12:15]
	v_mfma_f32_16x16x32_bf16 v[8:11], v[124:127], v[188:191], v[8:11]
	v_mfma_f32_16x16x32_bf16 v[52:55], v[136:139], v[160:163], v[52:55]
	v_mfma_f32_16x16x32_bf16 v[48:51], v[152:155], v[160:163], v[48:51]
	v_mfma_f32_16x16x32_bf16 v[36:39], v[136:139], v[168:171], v[36:39]
	v_mfma_f32_16x16x32_bf16 v[32:35], v[152:155], v[168:171], v[32:35]
	v_mfma_f32_16x16x32_bf16 v[20:23], v[136:139], v[176:179], v[20:23]
	v_mfma_f32_16x16x32_bf16 v[16:19], v[152:155], v[176:179], v[16:19]
	v_mfma_f32_16x16x32_bf16 v[4:7], v[136:139], v[184:187], v[4:7]
	v_mfma_f32_16x16x32_bf16 v[0:3], v[152:155], v[184:187], v[0:3]
	v_mfma_f32_16x16x32_bf16 v[52:55], v[140:143], v[164:167], v[52:55]
	v_mfma_f32_16x16x32_bf16 v[48:51], v[156:159], v[164:167], v[48:51]
	v_mfma_f32_16x16x32_bf16 v[36:39], v[140:143], v[172:175], v[36:39]
	v_mfma_f32_16x16x32_bf16 v[32:35], v[156:159], v[172:175], v[32:35]
	v_mfma_f32_16x16x32_bf16 v[20:23], v[140:143], v[180:183], v[20:23]
	v_mfma_f32_16x16x32_bf16 v[16:19], v[156:159], v[180:183], v[16:19]
	v_mfma_f32_16x16x32_bf16 v[4:7], v[140:143], v[188:191], v[4:7]
	v_mfma_f32_16x16x32_bf16 v[0:3], v[156:159], v[188:191], v[0:3]
	s_barrier
; #define PG8_STAGE(bufoff, gbase, voff) do { _Pragma("unroll") for (int _i = 0; _i < 2; ++_i) \
;         __builtin_amdgcn_global_load_lds((const unsigned*)((const char*)(gbase) + (voff)[_i]), (LAS unsigned*)(lds + (bufoff) + ldsw + _i * 8192), 16, 0, 0); } while (0)
; #define PG8_LDA(dst, b, h) do { _Pragma("unroll") for (int m = 0; m < 4; ++m) _Pragma("unroll") for (int k = 0; k < 2; ++k) dst[m][k] = *(const LAS bf16x8*)(lds + PG8_SA(b, h) + aoff + m * 2048 + k * 1024); } while (0)
; #define PG8_LDB(dst, b, h) do { _Pragma("unroll") for (int n = 0; n < 2; ++n) _Pragma("unroll") for (int k = 0; k < 2; ++k) dst[n][k] = *(const LAS bf16x8*)(lds + PG8_SB(b, h) + boff + n * 2048 + k * 1024); } while (0)
; #define PG8_MMA(ai, bj, At, Bt) do { __builtin_amdgcn_s_setprio(1); _Pragma("unroll") for (int m = 0; m < 4; ++m) _Pragma("unroll") for (int n = 0; n < 2; ++n) _Pragma("unroll") for (int k = 0; k < 2; ++k) \
;         acc[ai][bj][m][n] = __builtin_amdgcn_mfma_f32_16x16x32_bf16(Bt[n][k], At[m][k], acc[ai][bj][m][n], 0, 0, 0); __builtin_amdgcn_s_setprio(0); } while (0)
; #define PG8_WAIT_V(n) asm volatile("s_waitcnt vmcnt(" #n ")" ::: "memory")
; #define PG8_WAIT_L(n) asm volatile("s_waitcnt lgkmcnt(" #n ")" ::: "memory")
; #define PG8_BAR __builtin_amdgcn_s_barrier()
; #define PG8_SCHED __builtin_amdgcn_sched_barrier(0)
; template <class Epi, class Sched = StaticOrder, class EpiSub = NoSub, bool FAST = false>
; __device__ __forceinline__ void gemm_phase(LAS unsigned char* lds, const Gemm g, const Sched& S, const Epi& E, const EpiSub& ES = EpiSub()) {
;     ...
;             PG8_LDB(B0, 1, 0); PG8_LDB(B1, 1, 1); PG8_SCHED; PG8_LDA(At, 1, 0); PG8_STAGE(PG8_SA(0, 1), a2 + hstepA, voffA);
;             PG8_WAIT_V(8); PG8_WAIT_L(0); PG8_BAR; PG8_MMA(0, 0, At, B0); PG8_MMA(0, 1, At, B1); PG8_BAR; PG8_SCHED;
	s_setprio 0
	s_add_i32 s51, 0, 0x18000
	s_add_i32 s70, 0, 0x1c000
	v_add_u32_e32 v124, s51, v221
	v_add_u32_e32 v156, s70, v221
	ds_read_b128 v[104:107], v124
	ds_read_b128 v[108:111], v124 offset:1024
	ds_read_b128 v[120:123], v124 offset:2048
	ds_read_b128 v[124:127], v124 offset:3072
	ds_read_b128 v[136:139], v156
	ds_read_b128 v[140:143], v156 offset:1024
	ds_read_b128 v[152:155], v156 offset:2048
	ds_read_b128 v[156:159], v156 offset:3072
	s_add_u32 s42, s42, 0x80000
	s_addc_u32 s43, s43, 0
	s_mov_b32 m0, s55
	v_lshl_add_u64 v[216:217], s[42:43], 0, v[194:195]
	ds_read_b128 v[160:163], v226 offset:32768
	ds_read_b128 v[164:167], v226 offset:33792
	ds_read_b128 v[168:171], v226 offset:34816
	ds_read_b128 v[172:175], v226 offset:35840
	ds_read_b128 v[176:179], v226 offset:36864
	ds_read_b128 v[180:183], v226 offset:37888
	ds_read_b128 v[184:187], v226 offset:38912
	ds_read_b128 v[188:191], v226 offset:39936
	global_load_lds_dwordx4 v[216:217], off
	v_lshl_add_u64 v[216:217], s[42:43], 0, v[198:199]
	s_mov_b32 m0, s56
	s_nop 0
	global_load_lds_dwordx4 v[216:217], off
	s_waitcnt vmcnt(8)
	s_waitcnt lgkmcnt(0)
	s_setprio 1
	s_barrier
	v_mfma_f32_16x16x32_bf16 v[148:151], v[104:107], v[160:163], v[148:151]
	v_mfma_f32_16x16x32_bf16 v[144:147], v[120:123], v[160:163], v[144:147]
	v_mfma_f32_16x16x32_bf16 v[116:119], v[104:107], v[168:171], v[116:119]
	v_mfma_f32_16x16x32_bf16 v[112:115], v[120:123], v[168:171], v[112:115]
	v_mfma_f32_16x16x32_bf16 v[92:95], v[104:107], v[176:179], v[92:95]
	v_mfma_f32_16x16x32_bf16 v[88:91], v[120:123], v[176:179], v[88:91]
	v_mfma_f32_16x16x32_bf16 v[76:79], v[104:107], v[184:187], v[76:79]
	v_mfma_f32_16x16x32_bf16 v[72:75], v[120:123], v[184:187], v[72:75]
	v_mfma_f32_16x16x32_bf16 v[148:151], v[108:111], v[164:167], v[148:151]
	v_mfma_f32_16x16x32_bf16 v[144:147], v[124:127], v[164:167], v[144:147]
	v_mfma_f32_16x16x32_bf16 v[116:119], v[108:111], v[172:175], v[116:119]
	v_mfma_f32_16x16x32_bf16 v[112:115], v[124:127], v[172:175], v[112:115]
	v_mfma_f32_16x16x32_bf16 v[92:95], v[108:111], v[180:183], v[92:95]
	v_mfma_f32_16x16x32_bf16 v[88:91], v[124:127], v[180:183], v[88:91]
	v_mfma_f32_16x16x32_bf16 v[76:79], v[108:111], v[188:191], v[76:79]
	v_mfma_f32_16x16x32_bf16 v[72:75], v[124:127], v[188:191], v[72:75]
	v_mfma_f32_16x16x32_bf16 v[132:135], v[136:139], v[160:163], v[132:135]
	v_mfma_f32_16x16x32_bf16 v[128:131], v[152:155], v[160:163], v[128:131]
	v_mfma_f32_16x16x32_bf16 v[100:103], v[136:139], v[168:171], v[100:103]
	v_mfma_f32_16x16x32_bf16 v[96:99], v[152:155], v[168:171], v[96:99]
	v_mfma_f32_16x16x32_bf16 v[84:87], v[136:139], v[176:179], v[84:87]
	v_mfma_f32_16x16x32_bf16 v[80:83], v[152:155], v[176:179], v[80:83]
	v_mfma_f32_16x16x32_bf16 v[68:71], v[136:139], v[184:187], v[68:71]
	v_mfma_f32_16x16x32_bf16 v[64:67], v[152:155], v[184:187], v[64:67]
	v_mfma_f32_16x16x32_bf16 v[132:135], v[140:143], v[164:167], v[132:135]
	v_mfma_f32_16x16x32_bf16 v[128:131], v[156:159], v[164:167], v[128:131]
	v_mfma_f32_16x16x32_bf16 v[100:103], v[140:143], v[172:175], v[100:103]
	v_mfma_f32_16x16x32_bf16 v[96:99], v[156:159], v[172:175], v[96:99]
	v_mfma_f32_16x16x32_bf16 v[84:87], v[140:143], v[180:183], v[84:87]
	v_mfma_f32_16x16x32_bf16 v[80:83], v[156:159], v[180:183], v[80:83]
	v_mfma_f32_16x16x32_bf16 v[68:71], v[140:143], v[188:191], v[68:71]
	v_mfma_f32_16x16x32_bf16 v[64:67], v[156:159], v[188:191], v[64:67]
	s_barrier
; #define PG8_STAGE(bufoff, gbase, voff) do { _Pragma("unroll") for (int _i = 0; _i < 2; ++_i) \
;         __builtin_amdgcn_global_load_lds((const unsigned*)((const char*)(gbase) + (voff)[_i]), (LAS unsigned*)(lds + (bufoff) + ldsw + _i * 8192), 16, 0, 0); } while (0)
; #define PG8_LDA(dst, b, h) do { _Pragma("unroll") for (int m = 0; m < 4; ++m) _Pragma("unroll") for (int k = 0; k < 2; ++k) dst[m][k] = *(const LAS bf16x8*)(lds + PG8_SA(b, h) + aoff + m * 2048 + k * 1024); } while (0)
; #define PG8_MMA(ai, bj, At, Bt) do { __builtin_amdgcn_s_setprio(1); _Pragma("unroll") for (int m = 0; m < 4; ++m) _Pragma("unroll") for (int n = 0; n < 2; ++n) _Pragma("unroll") for (int k = 0; k < 2; ++k) \
;         acc[ai][bj][m][n] = __builtin_amdgcn_mfma_f32_16x16x32_bf16(Bt[n][k], At[m][k], acc[ai][bj][m][n], 0, 0, 0); __builtin_amdgcn_s_setprio(0); } while (0)
; #define PG8_WAIT_V(n) asm volatile("s_waitcnt vmcnt(" #n ")" ::: "memory")
; #define PG8_WAIT_L(n) asm volatile("s_waitcnt lgkmcnt(" #n ")" ::: "memory")
; #define PG8_BAR __builtin_amdgcn_s_barrier()
; #define PG8_SCHED __builtin_amdgcn_sched_barrier(0)
; template <class Epi, class Sched = StaticOrder, class EpiSub = NoSub, bool FAST = false>
; __device__ __forceinline__ void gemm_phase(LAS unsigned char* lds, const Gemm g, const Sched& S, const Epi& E, const EpiSub& ES = EpiSub()) {
;     ...
;         for (int t = 0; t < nt; t += 2) {
;     ...
;             PG8_LDA(At, 1, 1); PG8_STAGE(PG8_SB(1, 0), b3, voffB); PG8_STAGE(PG8_SB(1, 1), b3 + hstepB, voffB); PG8_STAGE(PG8_SA(1, 0), a3, voffA);
;             PG8_WAIT_V(8); PG8_WAIT_L(0); PG8_BAR; PG8_MMA(1, 0, At, B0); PG8_MMA(1, 1, At, B1); PG8_BAR; PG8_SCHED;
	s_setprio 0
	s_add_i32 s42, s51, s52
	v_lshl_add_u64 v[208:209], v[208:209], 0, s[12:13]
	s_mov_b32 m0, s42
	ds_read_b128 v[160:163], v226 offset:49152
	ds_read_b128 v[164:167], v226 offset:50176
	ds_read_b128 v[168:171], v226 offset:51200
	ds_read_b128 v[172:175], v226 offset:52224
	ds_read_b128 v[176:179], v226 offset:53248
	ds_read_b128 v[180:183], v226 offset:54272
	ds_read_b128 v[184:187], v226 offset:55296
	ds_read_b128 v[188:191], v226 offset:56320
	global_load_lds_dwordx4 v[208:209], off
	s_add_i32 m0, s42, 0x2000
	s_add_u32 s40, s40, 0x80080
	v_lshl_add_u64 v[208:209], v[210:211], 0, s[12:13]
	s_addc_u32 s41, s41, 0
	s_add_i32 s42, s70, s52
	global_load_lds_dwordx4 v[208:209], off
	v_lshl_add_u64 v[208:209], s[40:41], 0, v[196:197]
	s_mov_b32 m0, s42
	s_nop 0
	global_load_lds_dwordx4 v[208:209], off
	v_lshl_add_u64 v[208:209], s[40:41], 0, v[200:201]
	s_add_i32 m0, s42, 0x2000
	s_nop 0
	global_load_lds_dwordx4 v[208:209], off
	v_lshl_add_u64 v[208:209], v[212:213], 0, s[12:13]
	s_mov_b32 m0, s69
	s_nop 0
	global_load_lds_dwordx4 v[208:209], off
	v_lshl_add_u64 v[208:209], v[214:215], 0, s[12:13]
	s_mov_b32 m0, s74
	s_nop 0
	global_load_lds_dwordx4 v[208:209], off
	s_waitcnt vmcnt(8)
	s_waitcnt lgkmcnt(0)
	s_setprio 1
	s_barrier
	v_mfma_f32_16x16x32_bf16 v[60:63], v[104:107], v[160:163], v[60:63]
	v_mfma_f32_16x16x32_bf16 v[56:59], v[120:123], v[160:163], v[56:59]
	v_mfma_f32_16x16x32_bf16 v[44:47], v[104:107], v[168:171], v[44:47]
	v_mfma_f32_16x16x32_bf16 v[40:43], v[120:123], v[168:171], v[40:43]
	v_mfma_f32_16x16x32_bf16 v[28:31], v[104:107], v[176:179], v[28:31]
	v_mfma_f32_16x16x32_bf16 v[24:27], v[120:123], v[176:179], v[24:27]
	v_mfma_f32_16x16x32_bf16 v[12:15], v[104:107], v[184:187], v[12:15]
	v_mfma_f32_16x16x32_bf16 v[8:11], v[120:123], v[184:187], v[8:11]
	v_mfma_f32_16x16x32_bf16 v[60:63], v[108:111], v[164:167], v[60:63]
	v_mfma_f32_16x16x32_bf16 v[56:59], v[124:127], v[164:167], v[56:59]
	v_mfma_f32_16x16x32_bf16 v[44:47], v[108:111], v[172:175], v[44:47]
	v_mfma_f32_16x16x32_bf16 v[40:43], v[124:127], v[172:175], v[40:43]
	v_mfma_f32_16x16x32_bf16 v[28:31], v[108:111], v[180:183], v[28:31]
	v_mfma_f32_16x16x32_bf16 v[24:27], v[124:127], v[180:183], v[24:27]
	v_mfma_f32_16x16x32_bf16 v[12:15], v[108:111], v[188:191], v[12:15]
	v_mfma_f32_16x16x32_bf16 v[8:11], v[124:127], v[188:191], v[8:11]
	v_mfma_f32_16x16x32_bf16 v[52:55], v[136:139], v[160:163], v[52:55]
	v_mfma_f32_16x16x32_bf16 v[48:51], v[152:155], v[160:163], v[48:51]
	v_mfma_f32_16x16x32_bf16 v[36:39], v[136:139], v[168:171], v[36:39]
	v_mfma_f32_16x16x32_bf16 v[32:35], v[152:155], v[168:171], v[32:35]
	v_mfma_f32_16x16x32_bf16 v[20:23], v[136:139], v[176:179], v[20:23]
	v_mfma_f32_16x16x32_bf16 v[16:19], v[152:155], v[176:179], v[16:19]
	v_mfma_f32_16x16x32_bf16 v[4:7], v[136:139], v[184:187], v[4:7]
	v_mfma_f32_16x16x32_bf16 v[0:3], v[152:155], v[184:187], v[0:3]
	v_mfma_f32_16x16x32_bf16 v[52:55], v[140:143], v[164:167], v[52:55]
	v_mfma_f32_16x16x32_bf16 v[48:51], v[156:159], v[164:167], v[48:51]
	v_mfma_f32_16x16x32_bf16 v[36:39], v[140:143], v[172:175], v[36:39]
	v_mfma_f32_16x16x32_bf16 v[32:35], v[156:159], v[172:175], v[32:35]
	v_mfma_f32_16x16x32_bf16 v[20:23], v[140:143], v[180:183], v[20:23]
	v_mfma_f32_16x16x32_bf16 v[16:19], v[156:159], v[180:183], v[16:19]
	v_mfma_f32_16x16x32_bf16 v[4:7], v[140:143], v[188:191], v[4:7]
	v_mfma_f32_16x16x32_bf16 v[0:3], v[156:159], v[188:191], v[0:3]
	s_barrier
	s_setprio 0
	s_add_u32 s38, s38, 0x100
	s_addc_u32 s39, s39, 0
	s_add_u32 s48, s48, 0x100
	s_addc_u32 s49, s49, 0
	s_cmp_ge_u32 s50, s31
	s_mov_b32 s42, s50
	s_cbranch_scc0 .LBB0_632

; #define PG8_STAGE(bufoff, gbase, voff) do { _Pragma("unroll") for (int _i = 0; _i < 2; ++_i) \
;         __builtin_amdgcn_global_load_lds((const unsigned*)((const char*)(gbase) + (voff)[_i]), (LAS unsigned*)(lds + (bufoff) + ldsw + _i * 8192), 16, 0, 0); } while (0)
; #define PG8_LDA(dst, b, h) do { _Pragma("unroll") for (int m = 0; m < 4; ++m) _Pragma("unroll") for (int k = 0; k < 2; ++k) dst[m][k] = *(const LAS bf16x8*)(lds + PG8_SA(b, h) + aoff + m * 2048 + k * 1024); } while (0)
; #define PG8_LDB(dst, b, h) do { _Pragma("unroll") for (int n = 0; n < 2; ++n) _Pragma("unroll") for (int k = 0; k < 2; ++k) dst[n][k] = *(const LAS bf16x8*)(lds + PG8_SB(b, h) + boff + n * 2048 + k * 1024); } while (0)
; #define PG8_WAIT_V(n) asm volatile("s_waitcnt vmcnt(" #n ")" ::: "memory")
; #define PG8_BAR __builtin_amdgcn_s_barrier()
; template <class Epi, class Sched = StaticOrder, class EpiSub = NoSub, bool FAST = false>
; __device__ __forceinline__ void gemm_phase(LAS unsigned char* lds, const Gemm g, const Sched& S, const Epi& E, const EpiSub& ES = EpiSub()) {
;     ...
;         const bool has_next = S.next(ui + 1, nxt);
;         const size_t nko = (has_next && nxt.kb >= 0) ? nxt.kb * ksubB : 0;
;         const char* nA = has_next ? (const char*)g.A + (size_t)nxt.pm * tstepA + (size_t)nxt.pn * g.acs + nko : cA; const char* nB = has_next ? (const char*)g.Bt + (size_t)nxt.pn * tstepB + nko : cB;
;         const int nt = cur.kb < 0 ? ntMain : ntSub;
;         for (int t = 0; t < nt; t += 2) {
;             const bool last = (t == nt - 2);
;             const char* a1 = cA + (size_t)(t + 1) * kstep;
;             const char* a2 = last ? nA : cA + (size_t)(t + 2) * kstep; const char* b2 = last ? nB : cB + (size_t)(t + 2) * kstep;
;             const char* a3 = a2 + kstep; const char* b3 = b2 + kstep;
;             if constexpr (FAST && PG8_SP2) {
;             PG8_LDB(B0, 0, 0); PG8_LDB(B1, 0, 1); PG8_SCHED; PG8_LDA(At, 0, 0); PG8_STAGE(PG8_SA(1, 1), a1 + hstepA, voffA);
;             PG8_WAIT_V(8); PG8_WAIT_L(0); PG8_BAR; PG8_MMA(0, 0, At, B0); PG8_MMA(0, 1, At, B1); PG8_BAR; PG8_SCHED;
;             PG8_LDA(At, 0, 1); PG8_STAGE(PG8_SB(0, 0), b2, voffB); PG8_STAGE(PG8_SB(0, 1), b2 + hstepB, voffB); PG8_STAGE(PG8_SA(0, 0), a2, voffA);
;             PG8_WAIT_V(8); PG8_WAIT_L(0); PG8_BAR; PG8_MMA(1, 0, At, B0); PG8_MMA(1, 1, At, B1); PG8_BAR; PG8_SCHED;
.LBB0_768:
	s_cmp_gt_i32 s6, -1
	s_cselect_b64 s[24:25], -1, 0
	s_and_b64 s[24:25], s[22:23], s[24:25]
	s_lshl_b64 s[26:27], s[6:7], 9
	s_and_b64 s[24:25], s[24:25], exec
	s_cselect_b32 s29, s27, 0
	s_cselect_b32 s30, s26, 0
	s_ashr_i32 s21, s20, 31
	s_lshl_b64 s[24:25], s[20:21], 20
	s_add_u32 s1, s84, s24
	s_addc_u32 s5, s85, s25
	s_add_u32 s24, s1, s30
	s_addc_u32 s25, s5, s29
	s_and_b64 s[26:27], s[22:23], exec
	s_cselect_b32 s1, s25, s39
	s_cselect_b32 s5, s24, s38
	s_ashr_i32 s19, s18, 31
	s_lshl_b64 s[26:27], s[18:19], 20
	s_add_u32 s19, s2, s26
	s_addc_u32 s21, s3, s27
	s_add_u32 s26, s19, s30
	s_addc_u32 s27, s21, s29
	s_and_b64 s[30:31], s[22:23], exec
	s_cselect_b32 s19, s27, s41
	s_cselect_b32 s21, s26, s40
	s_cmp_gt_i32 s4, -1
	s_cselect_b64 s[30:31], -1, 0
	s_cmp_lt_i32 s4, 0
	s_cselect_b32 s29, 32, 4
	s_add_i32 s33, s29, -2
	s_add_u32 s38, s38, 0x80080
	s_addc_u32 s39, s39, 0
	s_add_u32 s70, s40, 0x100
	s_mov_b32 s42, 0
	s_addc_u32 s71, s41, 0
	ds_read_b128 v[96:99], v215
	ds_read_b128 v[100:103], v215 offset:1024
	ds_read_b128 v[112:115], v215 offset:2048
	ds_read_b128 v[116:119], v215 offset:3072
	ds_read_b128 v[144:147], v216
	ds_read_b128 v[148:151], v216 offset:1024
	ds_read_b128 v[152:155], v216 offset:2048
	ds_read_b128 v[156:159], v216 offset:3072
	s_add_i32 s72, s42, 2
	s_add_u32 s40, s38, 0xfff80080
	s_addc_u32 s41, s39, -1
	s_cmp_eq_u32 s33, s42
	s_cselect_b32 s42, s5, s40
	s_cselect_b32 s43, s1, s41
	s_cselect_b32 s41, s19, s71
	s_cselect_b32 s40, s21, s70
	v_lshl_add_u64 v[208:209], s[38:39], 0, v[194:195]
	s_add_i32 m0, s48, 0xc000
	ds_read_b128 v[160:163], v217
	ds_read_b128 v[164:167], v217 offset:1024
	ds_read_b128 v[168:171], v217 offset:2048
	ds_read_b128 v[172:175], v217 offset:3072
	ds_read_b128 v[176:179], v217 offset:4096
	ds_read_b128 v[180:183], v217 offset:5120
	ds_read_b128 v[200:203], v217 offset:6144
	ds_read_b128 v[204:207], v217 offset:7168
	global_load_lds_dwordx4 v[208:209], off
	v_lshl_add_u64 v[208:209], s[38:39], 0, v[196:197]
	s_add_i32 m0, s48, 0xe000
	s_nop 0
	global_load_lds_dwordx4 v[208:209], off
	s_waitcnt vmcnt(8)
	s_waitcnt lgkmcnt(0)
	s_setprio 1
	s_barrier
	v_mfma_f32_16x16x32_bf16 v[140:143], v[96:99], v[160:163], 0
	v_mfma_f32_16x16x32_bf16 v[136:139], v[112:115], v[160:163], 0
	v_mfma_f32_16x16x32_bf16 v[124:127], v[96:99], v[168:171], 0
	v_mfma_f32_16x16x32_bf16 v[120:123], v[112:115], v[168:171], 0
	v_mfma_f32_16x16x32_bf16 v[92:95], v[96:99], v[176:179], 0
	v_mfma_f32_16x16x32_bf16 v[88:91], v[112:115], v[176:179], 0
	v_mfma_f32_16x16x32_bf16 v[76:79], v[96:99], v[200:203], 0
	v_mfma_f32_16x16x32_bf16 v[72:75], v[112:115], v[200:203], 0
	v_mfma_f32_16x16x32_bf16 v[140:143], v[100:103], v[164:167], v[140:143]
	v_mfma_f32_16x16x32_bf16 v[136:139], v[116:119], v[164:167], v[136:139]
	v_mfma_f32_16x16x32_bf16 v[124:127], v[100:103], v[172:175], v[124:127]
	v_mfma_f32_16x16x32_bf16 v[120:123], v[116:119], v[172:175], v[120:123]
	v_mfma_f32_16x16x32_bf16 v[92:95], v[100:103], v[180:183], v[92:95]
	v_mfma_f32_16x16x32_bf16 v[88:91], v[116:119], v[180:183], v[88:91]
	v_mfma_f32_16x16x32_bf16 v[76:79], v[100:103], v[204:207], v[76:79]
	v_mfma_f32_16x16x32_bf16 v[72:75], v[116:119], v[204:207], v[72:75]
	v_mfma_f32_16x16x32_bf16 v[132:135], v[144:147], v[160:163], 0
	v_mfma_f32_16x16x32_bf16 v[128:131], v[152:155], v[160:163], 0
	v_mfma_f32_16x16x32_bf16 v[108:111], v[144:147], v[168:171], 0
	v_mfma_f32_16x16x32_bf16 v[104:107], v[152:155], v[168:171], 0
	v_mfma_f32_16x16x32_bf16 v[84:87], v[144:147], v[176:179], 0
	v_mfma_f32_16x16x32_bf16 v[80:83], v[152:155], v[176:179], 0
	v_mfma_f32_16x16x32_bf16 v[68:71], v[144:147], v[200:203], 0
	v_mfma_f32_16x16x32_bf16 v[64:67], v[152:155], v[200:203], 0
	v_mfma_f32_16x16x32_bf16 v[132:135], v[148:151], v[164:167], v[132:135]
	v_mfma_f32_16x16x32_bf16 v[128:131], v[156:159], v[164:167], v[128:131]
	v_mfma_f32_16x16x32_bf16 v[108:111], v[148:151], v[172:175], v[108:111]
	v_mfma_f32_16x16x32_bf16 v[104:107], v[156:159], v[172:175], v[104:107]
	v_mfma_f32_16x16x32_bf16 v[84:87], v[148:151], v[180:183], v[84:87]
	v_mfma_f32_16x16x32_bf16 v[80:83], v[156:159], v[180:183], v[80:83]
	v_mfma_f32_16x16x32_bf16 v[68:71], v[148:151], v[204:207], v[68:71]
	v_mfma_f32_16x16x32_bf16 v[64:67], v[156:159], v[204:207], v[64:67]
	s_barrier
	s_setprio 0
	s_add_i32 s73, s58, s17
	v_lshl_add_u64 v[208:209], s[40:41], 0, v[186:187]
	s_mov_b32 m0, s73
	ds_read_b128 v[160:163], v217 offset:16384
	ds_read_b128 v[164:167], v217 offset:17408
	ds_read_b128 v[168:171], v217 offset:18432
	ds_read_b128 v[172:175], v217 offset:19456
	ds_read_b128 v[176:179], v217 offset:20480
	ds_read_b128 v[180:183], v217 offset:21504
	ds_read_b128 v[200:203], v217 offset:22528
	ds_read_b128 v[204:207], v217 offset:23552
	global_load_lds_dwordx4 v[208:209], off
	s_add_i32 m0, s73, 0x2000
	s_add_u32 s76, s40, 0x80000
	v_lshl_add_u64 v[210:211], s[40:41], 0, v[190:191]
	s_addc_u32 s77, s41, 0
	s_add_i32 s73, s59, s17
	global_load_lds_dwordx4 v[210:211], off
	v_lshl_add_u64 v[218:219], s[76:77], 0, v[186:187]
	s_mov_b32 m0, s73
	v_lshl_add_u64 v[220:221], s[42:43], 0, v[188:189]
	global_load_lds_dwordx4 v[218:219], off
	v_lshl_add_u64 v[218:219], s[76:77], 0, v[190:191]
	s_add_i32 m0, s73, 0x2000
	s_nop 0
	global_load_lds_dwordx4 v[218:219], off
	v_lshl_add_u64 v[218:219], s[42:43], 0, v[184:185]
	s_mov_b32 m0, s48
	s_nop 0
	global_load_lds_dwordx4 v[218:219], off
	s_mov_b32 m0, s49
	s_nop 0
	global_load_lds_dwordx4 v[220:221], off
	s_waitcnt vmcnt(8)
	s_waitcnt lgkmcnt(0)
	s_setprio 1
	s_barrier
; #define PG8_STAGE(bufoff, gbase, voff) do { _Pragma("unroll") for (int _i = 0; _i < 2; ++_i) \
;         __builtin_amdgcn_global_load_lds((const unsigned*)((const char*)(gbase) + (voff)[_i]), (LAS unsigned*)(lds + (bufoff) + ldsw + _i * 8192), 16, 0, 0); } while (0)
; #define PG8_LDA(dst, b, h) do { _Pragma("unroll") for (int m = 0; m < 4; ++m) _Pragma("unroll") for (int k = 0; k < 2; ++k) dst[m][k] = *(const LAS bf16x8*)(lds + PG8_SA(b, h) + aoff + m * 2048 + k * 1024); } while (0)
; #define PG8_LDB(dst, b, h) do { _Pragma("unroll") for (int n = 0; n < 2; ++n) _Pragma("unroll") for (int k = 0; k < 2; ++k) dst[n][k] = *(const LAS bf16x8*)(lds + PG8_SB(b, h) + boff + n * 2048 + k * 1024); } while (0)
; #define PG8_MMA(ai, bj, At, Bt) do { __builtin_amdgcn_s_setprio(1); _Pragma("unroll") for (int m = 0; m < 4; ++m) _Pragma("unroll") for (int n = 0; n < 2; ++n) _Pragma("unroll") for (int k = 0; k < 2; ++k) \
;         acc[ai][bj][m][n] = __builtin_amdgcn_mfma_f32_16x16x32_bf16(Bt[n][k], At[m][k], acc[ai][bj][m][n], 0, 0, 0); __builtin_amdgcn_s_setprio(0); } while (0)
; #define PG8_WAIT_V(n) asm volatile("s_waitcnt vmcnt(" #n ")" ::: "memory")
; #define PG8_WAIT_L(n) asm volatile("s_waitcnt lgkmcnt(" #n ")" ::: "memory")
; #define PG8_BAR __builtin_amdgcn_s_barrier()
; #define PG8_SCHED __builtin_amdgcn_sched_barrier(0)
; template <class Epi, class Sched = StaticOrder, class EpiSub = NoSub, bool FAST = false>
; __device__ __forceinline__ void gemm_phase(LAS unsigned char* lds, const Gemm g, const Sched& S, const Epi& E, const EpiSub& ES = EpiSub()) {
;     ...
;             PG8_WAIT_V(8); PG8_WAIT_L(0); PG8_BAR; PG8_MMA(1, 0, At, B0); PG8_MMA(1, 1, At, B1); PG8_BAR; PG8_SCHED;
;             PG8_LDB(B0, 1, 0); PG8_LDB(B1, 1, 1); PG8_SCHED; PG8_LDA(At, 1, 0); PG8_STAGE(PG8_SA(0, 1), a2 + hstepA, voffA);
;             PG8_WAIT_V(8); PG8_WAIT_L(0); PG8_BAR; PG8_MMA(0, 0, At, B0); PG8_MMA(0, 1, At, B1); PG8_BAR; PG8_SCHED;
	v_mfma_f32_16x16x32_bf16 v[60:63], v[96:99], v[160:163], 0
	v_mfma_f32_16x16x32_bf16 v[56:59], v[112:115], v[160:163], 0
	v_mfma_f32_16x16x32_bf16 v[44:47], v[96:99], v[168:171], 0
	v_mfma_f32_16x16x32_bf16 v[40:43], v[112:115], v[168:171], 0
	v_mfma_f32_16x16x32_bf16 v[28:31], v[96:99], v[176:179], 0
	v_mfma_f32_16x16x32_bf16 v[24:27], v[112:115], v[176:179], 0
	v_mfma_f32_16x16x32_bf16 v[12:15], v[96:99], v[200:203], 0
	v_mfma_f32_16x16x32_bf16 v[8:11], v[112:115], v[200:203], 0
	v_mfma_f32_16x16x32_bf16 v[60:63], v[100:103], v[164:167], v[60:63]
	v_mfma_f32_16x16x32_bf16 v[56:59], v[116:119], v[164:167], v[56:59]
	v_mfma_f32_16x16x32_bf16 v[44:47], v[100:103], v[172:175], v[44:47]
	v_mfma_f32_16x16x32_bf16 v[40:43], v[116:119], v[172:175], v[40:43]
	v_mfma_f32_16x16x32_bf16 v[28:31], v[100:103], v[180:183], v[28:31]
	v_mfma_f32_16x16x32_bf16 v[24:27], v[116:119], v[180:183], v[24:27]
	v_mfma_f32_16x16x32_bf16 v[12:15], v[100:103], v[204:207], v[12:15]
	v_mfma_f32_16x16x32_bf16 v[8:11], v[116:119], v[204:207], v[8:11]
	v_mfma_f32_16x16x32_bf16 v[52:55], v[144:147], v[160:163], 0
	v_mfma_f32_16x16x32_bf16 v[48:51], v[152:155], v[160:163], 0
	v_mfma_f32_16x16x32_bf16 v[36:39], v[144:147], v[168:171], 0
	v_mfma_f32_16x16x32_bf16 v[32:35], v[152:155], v[168:171], 0
	v_mfma_f32_16x16x32_bf16 v[20:23], v[144:147], v[176:179], 0
	v_mfma_f32_16x16x32_bf16 v[16:19], v[152:155], v[176:179], 0
	v_mfma_f32_16x16x32_bf16 v[4:7], v[144:147], v[200:203], 0
	v_mfma_f32_16x16x32_bf16 v[0:3], v[152:155], v[200:203], 0
	v_mfma_f32_16x16x32_bf16 v[52:55], v[148:151], v[164:167], v[52:55]
	v_mfma_f32_16x16x32_bf16 v[48:51], v[156:159], v[164:167], v[48:51]
	v_mfma_f32_16x16x32_bf16 v[36:39], v[148:151], v[172:175], v[36:39]
	v_mfma_f32_16x16x32_bf16 v[32:35], v[156:159], v[172:175], v[32:35]
	v_mfma_f32_16x16x32_bf16 v[20:23], v[148:151], v[180:183], v[20:23]
	v_mfma_f32_16x16x32_bf16 v[16:19], v[156:159], v[180:183], v[16:19]
	v_mfma_f32_16x16x32_bf16 v[4:7], v[148:151], v[204:207], v[4:7]
	v_mfma_f32_16x16x32_bf16 v[0:3], v[156:159], v[204:207], v[0:3]
	s_barrier
	s_setprio 0
	s_add_i32 s73, 0, 0x18000
	s_add_i32 s76, 0, 0x1c000
	v_add_u32_e32 v116, s73, v212
	v_add_u32_e32 v156, s76, v212
	ds_read_b128 v[96:99], v116
	ds_read_b128 v[100:103], v116 offset:1024
	ds_read_b128 v[112:115], v116 offset:2048
	ds_read_b128 v[116:119], v116 offset:3072
	ds_read_b128 v[144:147], v156
	ds_read_b128 v[148:151], v156 offset:1024
	ds_read_b128 v[152:155], v156 offset:2048
	ds_read_b128 v[156:159], v156 offset:3072
	s_add_u32 s42, s42, 0x80000
	s_addc_u32 s43, s43, 0
	s_mov_b32 m0, s50
	v_lshl_add_u64 v[222:223], s[42:43], 0, v[184:185]
	ds_read_b128 v[160:163], v217 offset:32768
	ds_read_b128 v[164:167], v217 offset:33792
	ds_read_b128 v[168:171], v217 offset:34816
	ds_read_b128 v[172:175], v217 offset:35840
	ds_read_b128 v[176:179], v217 offset:36864
	ds_read_b128 v[180:183], v217 offset:37888
	ds_read_b128 v[200:203], v217 offset:38912
	ds_read_b128 v[204:207], v217 offset:39936
	global_load_lds_dwordx4 v[222:223], off
	v_lshl_add_u64 v[222:223], s[42:43], 0, v[188:189]
	s_mov_b32 m0, s51
	s_nop 0
	global_load_lds_dwordx4 v[222:223], off
	s_waitcnt vmcnt(8)
	s_waitcnt lgkmcnt(0)
	s_setprio 1
	s_barrier
	v_mfma_f32_16x16x32_bf16 v[140:143], v[96:99], v[160:163], v[140:143]
	v_mfma_f32_16x16x32_bf16 v[136:139], v[112:115], v[160:163], v[136:139]
	v_mfma_f32_16x16x32_bf16 v[124:127], v[96:99], v[168:171], v[124:127]
	v_mfma_f32_16x16x32_bf16 v[120:123], v[112:115], v[168:171], v[120:123]
	v_mfma_f32_16x16x32_bf16 v[92:95], v[96:99], v[176:179], v[92:95]
	v_mfma_f32_16x16x32_bf16 v[88:91], v[112:115], v[176:179], v[88:91]
	v_mfma_f32_16x16x32_bf16 v[76:79], v[96:99], v[200:203], v[76:79]
	v_mfma_f32_16x16x32_bf16 v[72:75], v[112:115], v[200:203], v[72:75]
	v_mfma_f32_16x16x32_bf16 v[140:143], v[100:103], v[164:167], v[140:143]
	v_mfma_f32_16x16x32_bf16 v[136:139], v[116:119], v[164:167], v[136:139]
	v_mfma_f32_16x16x32_bf16 v[124:127], v[100:103], v[172:175], v[124:127]
	v_mfma_f32_16x16x32_bf16 v[120:123], v[116:119], v[172:175], v[120:123]
	v_mfma_f32_16x16x32_bf16 v[92:95], v[100:103], v[180:183], v[92:95]
	v_mfma_f32_16x16x32_bf16 v[88:91], v[116:119], v[180:183], v[88:91]
	v_mfma_f32_16x16x32_bf16 v[76:79], v[100:103], v[204:207], v[76:79]
	v_mfma_f32_16x16x32_bf16 v[72:75], v[116:119], v[204:207], v[72:75]
	v_mfma_f32_16x16x32_bf16 v[132:135], v[144:147], v[160:163], v[132:135]
	v_mfma_f32_16x16x32_bf16 v[128:131], v[152:155], v[160:163], v[128:131]
	v_mfma_f32_16x16x32_bf16 v[108:111], v[144:147], v[168:171], v[108:111]
	v_mfma_f32_16x16x32_bf16 v[104:107], v[152:155], v[168:171], v[104:107]
	v_mfma_f32_16x16x32_bf16 v[84:87], v[144:147], v[176:179], v[84:87]
	v_mfma_f32_16x16x32_bf16 v[80:83], v[152:155], v[176:179], v[80:83]
	v_mfma_f32_16x16x32_bf16 v[68:71], v[144:147], v[200:203], v[68:71]
	v_mfma_f32_16x16x32_bf16 v[64:67], v[152:155], v[200:203], v[64:67]
	v_mfma_f32_16x16x32_bf16 v[132:135], v[148:151], v[164:167], v[132:135]
	v_mfma_f32_16x16x32_bf16 v[128:131], v[156:159], v[164:167], v[128:131]
	v_mfma_f32_16x16x32_bf16 v[108:111], v[148:151], v[172:175], v[108:111]
	v_mfma_f32_16x16x32_bf16 v[104:107], v[156:159], v[172:175], v[104:107]
	v_mfma_f32_16x16x32_bf16 v[84:87], v[148:151], v[180:183], v[84:87]
	v_mfma_f32_16x16x32_bf16 v[80:83], v[156:159], v[180:183], v[80:83]
	v_mfma_f32_16x16x32_bf16 v[68:71], v[148:151], v[204:207], v[68:71]
	v_mfma_f32_16x16x32_bf16 v[64:67], v[156:159], v[204:207], v[64:67]
	s_barrier
; #define PG8_STAGE(bufoff, gbase, voff) do { _Pragma("unroll") for (int _i = 0; _i < 2; ++_i) \
;         __builtin_amdgcn_global_load_lds((const unsigned*)((const char*)(gbase) + (voff)[_i]), (LAS unsigned*)(lds + (bufoff) + ldsw + _i * 8192), 16, 0, 0); } while (0)
; #define PG8_LDA(dst, b, h) do { _Pragma("unroll") for (int m = 0; m < 4; ++m) _Pragma("unroll") for (int k = 0; k < 2; ++k) dst[m][k] = *(const LAS bf16x8*)(lds + PG8_SA(b, h) + aoff + m * 2048 + k * 1024); } while (0)
; #define PG8_LDB(dst, b, h) do { _Pragma("unroll") for (int n = 0; n < 2; ++n) _Pragma("unroll") for (int k = 0; k < 2; ++k) dst[n][k] = *(const LAS bf16x8*)(lds + PG8_SB(b, h) + boff + n * 2048 + k * 1024); } while (0)
; template <class Epi, class Sched = StaticOrder, class EpiSub = NoSub, bool FAST = false>
; __device__ __forceinline__ void gemm_phase(LAS unsigned char* lds, const Gemm g, const Sched& S, const Epi& E, const EpiSub& ES = EpiSub()) {
;     ...
;         for (int t = 0; t < nt; t += 2) {
;             const bool last = (t == nt - 2);
;             const char* a1 = cA + (size_t)(t + 1) * kstep;
;             const char* a2 = last ? nA : cA + (size_t)(t + 2) * kstep; const char* b2 = last ? nB : cB + (size_t)(t + 2) * kstep;
;             const char* a3 = a2 + kstep; const char* b3 = b2 + kstep;
;             if constexpr (FAST && PG8_SP2) {
;             PG8_LDB(B0, 0, 0); PG8_LDB(B1, 0, 1); PG8_SCHED; PG8_LDA(At, 0, 0); PG8_STAGE(PG8_SA(1, 1), a1 + hstepA, voffA);
;             PG8_WAIT_V(8); PG8_WAIT_L(0); PG8_BAR; PG8_MMA(0, 0, At, B0); PG8_MMA(0, 1, At, B1); PG8_BAR; PG8_SCHED;
;             PG8_LDA(At, 0, 1); PG8_STAGE(PG8_SB(0, 0), b2, voffB); PG8_STAGE(PG8_SB(0, 1), b2 + hstepB, voffB); PG8_STAGE(PG8_SA(0, 0), a2, voffA);
;             PG8_WAIT_V(8); PG8_WAIT_L(0); PG8_BAR; PG8_MMA(1, 0, At, B0); PG8_MMA(1, 1, At, B1); PG8_BAR; PG8_SCHED;
;             PG8_LDB(B0, 1, 0); PG8_LDB(B1, 1, 1); PG8_SCHED; PG8_LDA(At, 1, 0); PG8_STAGE(PG8_SA(0, 1), a2 + hstepA, voffA);
;             PG8_WAIT_V(8); PG8_WAIT_L(0); PG8_BAR; PG8_MMA(0, 0, At, B0); PG8_MMA(0, 1, At, B1); PG8_BAR; PG8_SCHED;
;             PG8_LDA(At, 1, 1); PG8_STAGE(PG8_SB(1, 0), b3, voffB); PG8_STAGE(PG8_SB(1, 1), b3 + hstepB, voffB); PG8_STAGE(PG8_SA(1, 0), a3, voffA);
;             PG8_WAIT_V(8); PG8_WAIT_L(0); PG8_BAR; PG8_MMA(1, 0, At, B0); PG8_MMA(1, 1, At, B1); PG8_BAR; PG8_SCHED;
	s_setprio 0
	s_add_i32 s42, s73, s17
	v_lshl_add_u64 v[208:209], v[208:209], 0, s[12:13]
	s_mov_b32 m0, s42
	ds_read_b128 v[160:163], v217 offset:49152
	ds_read_b128 v[164:167], v217 offset:50176
	ds_read_b128 v[168:171], v217 offset:51200
	ds_read_b128 v[172:175], v217 offset:52224
	ds_read_b128 v[176:179], v217 offset:53248
	ds_read_b128 v[180:183], v217 offset:54272
	ds_read_b128 v[200:203], v217 offset:55296
	ds_read_b128 v[204:207], v217 offset:56320
	global_load_lds_dwordx4 v[208:209], off
	s_add_i32 m0, s42, 0x2000
	s_add_u32 s40, s40, 0x80080
	v_lshl_add_u64 v[208:209], v[210:211], 0, s[12:13]
	s_addc_u32 s41, s41, 0
	s_add_i32 s42, s76, s17
	global_load_lds_dwordx4 v[208:209], off
	v_lshl_add_u64 v[208:209], s[40:41], 0, v[186:187]
	s_mov_b32 m0, s42
	s_nop 0
	global_load_lds_dwordx4 v[208:209], off
	v_lshl_add_u64 v[208:209], s[40:41], 0, v[190:191]
	s_add_i32 m0, s42, 0x2000
	s_nop 0
	global_load_lds_dwordx4 v[208:209], off
	v_lshl_add_u64 v[208:209], v[218:219], 0, s[12:13]
	s_mov_b32 m0, s55
	s_nop 0
	global_load_lds_dwordx4 v[208:209], off
	v_lshl_add_u64 v[208:209], v[220:221], 0, s[12:13]
	s_mov_b32 m0, s56
	s_nop 0
	global_load_lds_dwordx4 v[208:209], off
	s_waitcnt vmcnt(8)
	s_waitcnt lgkmcnt(0)
	s_setprio 1
	s_barrier
	v_mfma_f32_16x16x32_bf16 v[60:63], v[96:99], v[160:163], v[60:63]
	v_mfma_f32_16x16x32_bf16 v[56:59], v[112:115], v[160:163], v[56:59]
	v_mfma_f32_16x16x32_bf16 v[44:47], v[96:99], v[168:171], v[44:47]
	v_mfma_f32_16x16x32_bf16 v[40:43], v[112:115], v[168:171], v[40:43]
	v_mfma_f32_16x16x32_bf16 v[28:31], v[96:99], v[176:179], v[28:31]
	v_mfma_f32_16x16x32_bf16 v[24:27], v[112:115], v[176:179], v[24:27]
	v_mfma_f32_16x16x32_bf16 v[12:15], v[96:99], v[200:203], v[12:15]
	v_mfma_f32_16x16x32_bf16 v[8:11], v[112:115], v[200:203], v[8:11]
	v_mfma_f32_16x16x32_bf16 v[60:63], v[100:103], v[164:167], v[60:63]
	v_mfma_f32_16x16x32_bf16 v[56:59], v[116:119], v[164:167], v[56:59]
	v_mfma_f32_16x16x32_bf16 v[44:47], v[100:103], v[172:175], v[44:47]
	v_mfma_f32_16x16x32_bf16 v[40:43], v[116:119], v[172:175], v[40:43]
	v_mfma_f32_16x16x32_bf16 v[28:31], v[100:103], v[180:183], v[28:31]
	v_mfma_f32_16x16x32_bf16 v[24:27], v[116:119], v[180:183], v[24:27]
	v_mfma_f32_16x16x32_bf16 v[12:15], v[100:103], v[204:207], v[12:15]
	v_mfma_f32_16x16x32_bf16 v[8:11], v[116:119], v[204:207], v[8:11]
	v_mfma_f32_16x16x32_bf16 v[52:55], v[144:147], v[160:163], v[52:55]
	v_mfma_f32_16x16x32_bf16 v[48:51], v[152:155], v[160:163], v[48:51]
	v_mfma_f32_16x16x32_bf16 v[36:39], v[144:147], v[168:171], v[36:39]
	v_mfma_f32_16x16x32_bf16 v[32:35], v[152:155], v[168:171], v[32:35]
	v_mfma_f32_16x16x32_bf16 v[20:23], v[144:147], v[176:179], v[20:23]
	v_mfma_f32_16x16x32_bf16 v[16:19], v[152:155], v[176:179], v[16:19]
	v_mfma_f32_16x16x32_bf16 v[4:7], v[144:147], v[200:203], v[4:7]
	v_mfma_f32_16x16x32_bf16 v[0:3], v[152:155], v[200:203], v[0:3]
	v_mfma_f32_16x16x32_bf16 v[52:55], v[148:151], v[164:167], v[52:55]
	v_mfma_f32_16x16x32_bf16 v[48:51], v[156:159], v[164:167], v[48:51]
	v_mfma_f32_16x16x32_bf16 v[36:39], v[148:151], v[172:175], v[36:39]
	v_mfma_f32_16x16x32_bf16 v[32:35], v[156:159], v[172:175], v[32:35]
	v_mfma_f32_16x16x32_bf16 v[20:23], v[148:151], v[180:183], v[20:23]
	v_mfma_f32_16x16x32_bf16 v[16:19], v[156:159], v[180:183], v[16:19]
	v_mfma_f32_16x16x32_bf16 v[4:7], v[148:151], v[204:207], v[4:7]
	v_mfma_f32_16x16x32_bf16 v[0:3], v[156:159], v[204:207], v[0:3]
	s_barrier
	s_setprio 0
	s_add_u32 s38, s38, 0x100
	s_addc_u32 s39, s39, 0
	s_add_u32 s70, s70, 0x100
	s_addc_u32 s71, s71, 0
	s_cmp_ge_u32 s72, s29
	s_mov_b32 s42, s72
	s_cbranch_scc1 .Lkpeel_769_exit
.LBB0_769:
	ds_read_b128 v[96:99], v215
	ds_read_b128 v[100:103], v215 offset:1024
	ds_read_b128 v[112:115], v215 offset:2048
	ds_read_b128 v[116:119], v215 offset:3072
	ds_read_b128 v[144:147], v216
	ds_read_b128 v[148:151], v216 offset:1024
	ds_read_b128 v[152:155], v216 offset:2048
	ds_read_b128 v[156:159], v216 offset:3072
	s_add_i32 s72, s42, 2
	s_add_u32 s40, s38, 0xfff80080
	s_addc_u32 s41, s39, -1
	s_cmp_eq_u32 s33, s42
	s_cselect_b32 s42, s5, s40
	s_cselect_b32 s43, s1, s41
	s_cselect_b32 s41, s19, s71
	s_cselect_b32 s40, s21, s70
	v_lshl_add_u64 v[208:209], s[38:39], 0, v[194:195]
	s_add_i32 m0, s48, 0xc000
	ds_read_b128 v[160:163], v217
	ds_read_b128 v[164:167], v217 offset:1024
	ds_read_b128 v[168:171], v217 offset:2048
	ds_read_b128 v[172:175], v217 offset:3072
	ds_read_b128 v[176:179], v217 offset:4096
	ds_read_b128 v[180:183], v217 offset:5120
	ds_read_b128 v[200:203], v217 offset:6144
	ds_read_b128 v[204:207], v217 offset:7168
	global_load_lds_dwordx4 v[208:209], off
	v_lshl_add_u64 v[208:209], s[38:39], 0, v[196:197]
	s_add_i32 m0, s48, 0xe000
	s_nop 0
	global_load_lds_dwordx4 v[208:209], off
	s_waitcnt vmcnt(8)
	s_waitcnt lgkmcnt(0)
	s_setprio 1
	s_barrier
; #define PG8_STAGE(bufoff, gbase, voff) do { _Pragma("unroll") for (int _i = 0; _i < 2; ++_i) \
;         __builtin_amdgcn_global_load_lds((const unsigned*)((const char*)(gbase) + (voff)[_i]), (LAS unsigned*)(lds + (bufoff) + ldsw + _i * 8192), 16, 0, 0); } while (0)
; #define PG8_LDA(dst, b, h) do { _Pragma("unroll") for (int m = 0; m < 4; ++m) _Pragma("unroll") for (int k = 0; k < 2; ++k) dst[m][k] = *(const LAS bf16x8*)(lds + PG8_SA(b, h) + aoff + m * 2048 + k * 1024); } while (0)
; #define PG8_LDB(dst, b, h) do { _Pragma("unroll") for (int n = 0; n < 2; ++n) _Pragma("unroll") for (int k = 0; k < 2; ++k) dst[n][k] = *(const LAS bf16x8*)(lds + PG8_SB(b, h) + boff + n * 2048 + k * 1024); } while (0)
; #define PG8_MMA(ai, bj, At, Bt) do { __builtin_amdgcn_s_setprio(1); _Pragma("unroll") for (int m = 0; m < 4; ++m) _Pragma("unroll") for (int n = 0; n < 2; ++n) _Pragma("unroll") for (int k = 0; k < 2; ++k) \
;         acc[ai][bj][m][n] = __builtin_amdgcn_mfma_f32_16x16x32_bf16(Bt[n][k], At[m][k], acc[ai][bj][m][n], 0, 0, 0); __builtin_amdgcn_s_setprio(0); } while (0)
; #define PG8_WAIT_V(n) asm volatile("s_waitcnt vmcnt(" #n ")" ::: "memory")
; #define PG8_WAIT_L(n) asm volatile("s_waitcnt lgkmcnt(" #n ")" ::: "memory")
; #define PG8_BAR __builtin_amdgcn_s_barrier()
; #define PG8_SCHED __builtin_amdgcn_sched_barrier(0)
; template <class Epi, class Sched = StaticOrder, class EpiSub = NoSub, bool FAST = false>
; __device__ __forceinline__ void gemm_phase(LAS unsigned char* lds, const Gemm g, const Sched& S, const Epi& E, const EpiSub& ES = EpiSub()) {
;     ...
;             PG8_LDB(B0, 0, 0); PG8_LDB(B1, 0, 1); PG8_SCHED; PG8_LDA(At, 0, 0); PG8_STAGE(PG8_SA(1, 1), a1 + hstepA, voffA);
;             PG8_WAIT_V(8); PG8_WAIT_L(0); PG8_BAR; PG8_MMA(0, 0, At, B0); PG8_MMA(0, 1, At, B1); PG8_BAR; PG8_SCHED;
;             PG8_LDA(At, 0, 1); PG8_STAGE(PG8_SB(0, 0), b2, voffB); PG8_STAGE(PG8_SB(0, 1), b2 + hstepB, voffB); PG8_STAGE(PG8_SA(0, 0), a2, voffA);
;             PG8_WAIT_V(8); PG8_WAIT_L(0); PG8_BAR; PG8_MMA(1, 0, At, B0); PG8_MMA(1, 1, At, B1); PG8_BAR; PG8_SCHED;
	v_mfma_f32_16x16x32_bf16 v[140:143], v[96:99], v[160:163], v[140:143]
	v_mfma_f32_16x16x32_bf16 v[136:139], v[112:115], v[160:163], v[136:139]
	v_mfma_f32_16x16x32_bf16 v[124:127], v[96:99], v[168:171], v[124:127]
	v_mfma_f32_16x16x32_bf16 v[120:123], v[112:115], v[168:171], v[120:123]
	v_mfma_f32_16x16x32_bf16 v[92:95], v[96:99], v[176:179], v[92:95]
	v_mfma_f32_16x16x32_bf16 v[88:91], v[112:115], v[176:179], v[88:91]
	v_mfma_f32_16x16x32_bf16 v[76:79], v[96:99], v[200:203], v[76:79]
	v_mfma_f32_16x16x32_bf16 v[72:75], v[112:115], v[200:203], v[72:75]
	v_mfma_f32_16x16x32_bf16 v[140:143], v[100:103], v[164:167], v[140:143]
	v_mfma_f32_16x16x32_bf16 v[136:139], v[116:119], v[164:167], v[136:139]
	v_mfma_f32_16x16x32_bf16 v[124:127], v[100:103], v[172:175], v[124:127]
	v_mfma_f32_16x16x32_bf16 v[120:123], v[116:119], v[172:175], v[120:123]
	v_mfma_f32_16x16x32_bf16 v[92:95], v[100:103], v[180:183], v[92:95]
	v_mfma_f32_16x16x32_bf16 v[88:91], v[116:119], v[180:183], v[88:91]
	v_mfma_f32_16x16x32_bf16 v[76:79], v[100:103], v[204:207], v[76:79]
	v_mfma_f32_16x16x32_bf16 v[72:75], v[116:119], v[204:207], v[72:75]
	v_mfma_f32_16x16x32_bf16 v[132:135], v[144:147], v[160:163], v[132:135]
	v_mfma_f32_16x16x32_bf16 v[128:131], v[152:155], v[160:163], v[128:131]
	v_mfma_f32_16x16x32_bf16 v[108:111], v[144:147], v[168:171], v[108:111]
	v_mfma_f32_16x16x32_bf16 v[104:107], v[152:155], v[168:171], v[104:107]
	v_mfma_f32_16x16x32_bf16 v[84:87], v[144:147], v[176:179], v[84:87]
	v_mfma_f32_16x16x32_bf16 v[80:83], v[152:155], v[176:179], v[80:83]
	v_mfma_f32_16x16x32_bf16 v[68:71], v[144:147], v[200:203], v[68:71]
	v_mfma_f32_16x16x32_bf16 v[64:67], v[152:155], v[200:203], v[64:67]
	v_mfma_f32_16x16x32_bf16 v[132:135], v[148:151], v[164:167], v[132:135]
	v_mfma_f32_16x16x32_bf16 v[128:131], v[156:159], v[164:167], v[128:131]
	v_mfma_f32_16x16x32_bf16 v[108:111], v[148:151], v[172:175], v[108:111]
	v_mfma_f32_16x16x32_bf16 v[104:107], v[156:159], v[172:175], v[104:107]
	v_mfma_f32_16x16x32_bf16 v[84:87], v[148:151], v[180:183], v[84:87]
	v_mfma_f32_16x16x32_bf16 v[80:83], v[156:159], v[180:183], v[80:83]
	v_mfma_f32_16x16x32_bf16 v[68:71], v[148:151], v[204:207], v[68:71]
	v_mfma_f32_16x16x32_bf16 v[64:67], v[156:159], v[204:207], v[64:67]
	s_barrier
	s_setprio 0
	s_add_i32 s73, s58, s17
	v_lshl_add_u64 v[208:209], s[40:41], 0, v[186:187]
	s_mov_b32 m0, s73
	ds_read_b128 v[160:163], v217 offset:16384
	ds_read_b128 v[164:167], v217 offset:17408
	ds_read_b128 v[168:171], v217 offset:18432
	ds_read_b128 v[172:175], v217 offset:19456
	ds_read_b128 v[176:179], v217 offset:20480
	ds_read_b128 v[180:183], v217 offset:21504
	ds_read_b128 v[200:203], v217 offset:22528
	ds_read_b128 v[204:207], v217 offset:23552
	global_load_lds_dwordx4 v[208:209], off
	s_add_i32 m0, s73, 0x2000
	s_add_u32 s76, s40, 0x80000
	v_lshl_add_u64 v[210:211], s[40:41], 0, v[190:191]
	s_addc_u32 s77, s41, 0
	s_add_i32 s73, s59, s17
	global_load_lds_dwordx4 v[210:211], off
	v_lshl_add_u64 v[218:219], s[76:77], 0, v[186:187]
	s_mov_b32 m0, s73
	v_lshl_add_u64 v[220:221], s[42:43], 0, v[188:189]
	global_load_lds_dwordx4 v[218:219], off
	v_lshl_add_u64 v[218:219], s[76:77], 0, v[190:191]
	s_add_i32 m0, s73, 0x2000
	s_nop 0
	global_load_lds_dwordx4 v[218:219], off
	v_lshl_add_u64 v[218:219], s[42:43], 0, v[184:185]
	s_mov_b32 m0, s48
	s_nop 0
	global_load_lds_dwordx4 v[218:219], off
	s_mov_b32 m0, s49
	s_nop 0
	global_load_lds_dwordx4 v[220:221], off
	s_waitcnt vmcnt(8)
	s_waitcnt lgkmcnt(0)
	s_setprio 1
	s_barrier
	v_mfma_f32_16x16x32_bf16 v[60:63], v[96:99], v[160:163], v[60:63]
	v_mfma_f32_16x16x32_bf16 v[56:59], v[112:115], v[160:163], v[56:59]
	v_mfma_f32_16x16x32_bf16 v[44:47], v[96:99], v[168:171], v[44:47]
	v_mfma_f32_16x16x32_bf16 v[40:43], v[112:115], v[168:171], v[40:43]
	v_mfma_f32_16x16x32_bf16 v[28:31], v[96:99], v[176:179], v[28:31]
	v_mfma_f32_16x16x32_bf16 v[24:27], v[112:115], v[176:179], v[24:27]
	v_mfma_f32_16x16x32_bf16 v[12:15], v[96:99], v[200:203], v[12:15]
	v_mfma_f32_16x16x32_bf16 v[8:11], v[112:115], v[200:203], v[8:11]
	v_mfma_f32_16x16x32_bf16 v[60:63], v[100:103], v[164:167], v[60:63]
	v_mfma_f32_16x16x32_bf16 v[56:59], v[116:119], v[164:167], v[56:59]
	v_mfma_f32_16x16x32_bf16 v[44:47], v[100:103], v[172:175], v[44:47]
	v_mfma_f32_16x16x32_bf16 v[40:43], v[116:119], v[172:175], v[40:43]
	v_mfma_f32_16x16x32_bf16 v[28:31], v[100:103], v[180:183], v[28:31]
	v_mfma_f32_16x16x32_bf16 v[24:27], v[116:119], v[180:183], v[24:27]
	v_mfma_f32_16x16x32_bf16 v[12:15], v[100:103], v[204:207], v[12:15]
	v_mfma_f32_16x16x32_bf16 v[8:11], v[116:119], v[204:207], v[8:11]
	v_mfma_f32_16x16x32_bf16 v[52:55], v[144:147], v[160:163], v[52:55]
	v_mfma_f32_16x16x32_bf16 v[48:51], v[152:155], v[160:163], v[48:51]
	v_mfma_f32_16x16x32_bf16 v[36:39], v[144:147], v[168:171], v[36:39]
	v_mfma_f32_16x16x32_bf16 v[32:35], v[152:155], v[168:171], v[32:35]
	v_mfma_f32_16x16x32_bf16 v[20:23], v[144:147], v[176:179], v[20:23]
	v_mfma_f32_16x16x32_bf16 v[16:19], v[152:155], v[176:179], v[16:19]
	v_mfma_f32_16x16x32_bf16 v[4:7], v[144:147], v[200:203], v[4:7]
	v_mfma_f32_16x16x32_bf16 v[0:3], v[152:155], v[200:203], v[0:3]
	v_mfma_f32_16x16x32_bf16 v[52:55], v[148:151], v[164:167], v[52:55]
	v_mfma_f32_16x16x32_bf16 v[48:51], v[156:159], v[164:167], v[48:51]
	v_mfma_f32_16x16x32_bf16 v[36:39], v[148:151], v[172:175], v[36:39]
	v_mfma_f32_16x16x32_bf16 v[32:35], v[156:159], v[172:175], v[32:35]
	v_mfma_f32_16x16x32_bf16 v[20:23], v[148:151], v[180:183], v[20:23]
	v_mfma_f32_16x16x32_bf16 v[16:19], v[156:159], v[180:183], v[16:19]
	v_mfma_f32_16x16x32_bf16 v[4:7], v[148:151], v[204:207], v[4:7]
	v_mfma_f32_16x16x32_bf16 v[0:3], v[156:159], v[204:207], v[0:3]
	s_barrier
; #define PG8_STAGE(bufoff, gbase, voff) do { _Pragma("unroll") for (int _i = 0; _i < 2; ++_i) \
;         __builtin_amdgcn_global_load_lds((const unsigned*)((const char*)(gbase) + (voff)[_i]), (LAS unsigned*)(lds + (bufoff) + ldsw + _i * 8192), 16, 0, 0); } while (0)
; #define PG8_LDA(dst, b, h) do { _Pragma("unroll") for (int m = 0; m < 4; ++m) _Pragma("unroll") for (int k = 0; k < 2; ++k) dst[m][k] = *(const LAS bf16x8*)(lds + PG8_SA(b, h) + aoff + m * 2048 + k * 1024); } while (0)
; #define PG8_LDB(dst, b, h) do { _Pragma("unroll") for (int n = 0; n < 2; ++n) _Pragma("unroll") for (int k = 0; k < 2; ++k) dst[n][k] = *(const LAS bf16x8*)(lds + PG8_SB(b, h) + boff + n * 2048 + k * 1024); } while (0)
; #define PG8_MMA(ai, bj, At, Bt) do { __builtin_amdgcn_s_setprio(1); _Pragma("unroll") for (int m = 0; m < 4; ++m) _Pragma("unroll") for (int n = 0; n < 2; ++n) _Pragma("unroll") for (int k = 0; k < 2; ++k) \
;         acc[ai][bj][m][n] = __builtin_amdgcn_mfma_f32_16x16x32_bf16(Bt[n][k], At[m][k], acc[ai][bj][m][n], 0, 0, 0); __builtin_amdgcn_s_setprio(0); } while (0)
; #define PG8_WAIT_V(n) asm volatile("s_waitcnt vmcnt(" #n ")" ::: "memory")
; #define PG8_WAIT_L(n) asm volatile("s_waitcnt lgkmcnt(" #n ")" ::: "memory")
; #define PG8_BAR __builtin_amdgcn_s_barrier()
; #define PG8_SCHED __builtin_amdgcn_sched_barrier(0)
; template <class Epi, class Sched = StaticOrder, class EpiSub = NoSub, bool FAST = false>
; __device__ __forceinline__ void gemm_phase(LAS unsigned char* lds, const Gemm g, const Sched& S, const Epi& E, const EpiSub& ES = EpiSub()) {
;     ...
;             PG8_LDB(B0, 1, 0); PG8_LDB(B1, 1, 1); PG8_SCHED; PG8_LDA(At, 1, 0); PG8_STAGE(PG8_SA(0, 1), a2 + hstepA, voffA);
;             PG8_WAIT_V(8); PG8_WAIT_L(0); PG8_BAR; PG8_MMA(0, 0, At, B0); PG8_MMA(0, 1, At, B1); PG8_BAR; PG8_SCHED;
	s_setprio 0
	s_add_i32 s73, 0, 0x18000
	s_add_i32 s76, 0, 0x1c000
	v_add_u32_e32 v116, s73, v212
	v_add_u32_e32 v156, s76, v212
	ds_read_b128 v[96:99], v116
	ds_read_b128 v[100:103], v116 offset:1024
	ds_read_b128 v[112:115], v116 offset:2048
	ds_read_b128 v[116:119], v116 offset:3072
	ds_read_b128 v[144:147], v156
	ds_read_b128 v[148:151], v156 offset:1024
	ds_read_b128 v[152:155], v156 offset:2048
	ds_read_b128 v[156:159], v156 offset:3072
	s_add_u32 s42, s42, 0x80000
	s_addc_u32 s43, s43, 0
	s_mov_b32 m0, s50
	v_lshl_add_u64 v[222:223], s[42:43], 0, v[184:185]
	ds_read_b128 v[160:163], v217 offset:32768
	ds_read_b128 v[164:167], v217 offset:33792
	ds_read_b128 v[168:171], v217 offset:34816
	ds_read_b128 v[172:175], v217 offset:35840
	ds_read_b128 v[176:179], v217 offset:36864
	ds_read_b128 v[180:183], v217 offset:37888
	ds_read_b128 v[200:203], v217 offset:38912
	ds_read_b128 v[204:207], v217 offset:39936
	global_load_lds_dwordx4 v[222:223], off
	v_lshl_add_u64 v[222:223], s[42:43], 0, v[188:189]
	s_mov_b32 m0, s51
	s_nop 0
	global_load_lds_dwordx4 v[222:223], off
	s_waitcnt vmcnt(8)
	s_waitcnt lgkmcnt(0)
	s_setprio 1
	s_barrier
	v_mfma_f32_16x16x32_bf16 v[140:143], v[96:99], v[160:163], v[140:143]
	v_mfma_f32_16x16x32_bf16 v[136:139], v[112:115], v[160:163], v[136:139]
	v_mfma_f32_16x16x32_bf16 v[124:127], v[96:99], v[168:171], v[124:127]
	v_mfma_f32_16x16x32_bf16 v[120:123], v[112:115], v[168:171], v[120:123]
	v_mfma_f32_16x16x32_bf16 v[92:95], v[96:99], v[176:179], v[92:95]
	v_mfma_f32_16x16x32_bf16 v[88:91], v[112:115], v[176:179], v[88:91]
	v_mfma_f32_16x16x32_bf16 v[76:79], v[96:99], v[200:203], v[76:79]
	v_mfma_f32_16x16x32_bf16 v[72:75], v[112:115], v[200:203], v[72:75]
	v_mfma_f32_16x16x32_bf16 v[140:143], v[100:103], v[164:167], v[140:143]
	v_mfma_f32_16x16x32_bf16 v[136:139], v[116:119], v[164:167], v[136:139]
	v_mfma_f32_16x16x32_bf16 v[124:127], v[100:103], v[172:175], v[124:127]
	v_mfma_f32_16x16x32_bf16 v[120:123], v[116:119], v[172:175], v[120:123]
	v_mfma_f32_16x16x32_bf16 v[92:95], v[100:103], v[180:183], v[92:95]
	v_mfma_f32_16x16x32_bf16 v[88:91], v[116:119], v[180:183], v[88:91]
	v_mfma_f32_16x16x32_bf16 v[76:79], v[100:103], v[204:207], v[76:79]
	v_mfma_f32_16x16x32_bf16 v[72:75], v[116:119], v[204:207], v[72:75]
	v_mfma_f32_16x16x32_bf16 v[132:135], v[144:147], v[160:163], v[132:135]
	v_mfma_f32_16x16x32_bf16 v[128:131], v[152:155], v[160:163], v[128:131]
	v_mfma_f32_16x16x32_bf16 v[108:111], v[144:147], v[168:171], v[108:111]
	v_mfma_f32_16x16x32_bf16 v[104:107], v[152:155], v[168:171], v[104:107]
	v_mfma_f32_16x16x32_bf16 v[84:87], v[144:147], v[176:179], v[84:87]
	v_mfma_f32_16x16x32_bf16 v[80:83], v[152:155], v[176:179], v[80:83]
	v_mfma_f32_16x16x32_bf16 v[68:71], v[144:147], v[200:203], v[68:71]
	v_mfma_f32_16x16x32_bf16 v[64:67], v[152:155], v[200:203], v[64:67]
	v_mfma_f32_16x16x32_bf16 v[132:135], v[148:151], v[164:167], v[132:135]
	v_mfma_f32_16x16x32_bf16 v[128:131], v[156:159], v[164:167], v[128:131]
	v_mfma_f32_16x16x32_bf16 v[108:111], v[148:151], v[172:175], v[108:111]
	v_mfma_f32_16x16x32_bf16 v[104:107], v[156:159], v[172:175], v[104:107]
	v_mfma_f32_16x16x32_bf16 v[84:87], v[148:151], v[180:183], v[84:87]
	v_mfma_f32_16x16x32_bf16 v[80:83], v[156:159], v[180:183], v[80:83]
	v_mfma_f32_16x16x32_bf16 v[68:71], v[148:151], v[204:207], v[68:71]
	v_mfma_f32_16x16x32_bf16 v[64:67], v[156:159], v[204:207], v[64:67]
	s_barrier
; #define PG8_STAGE(bufoff, gbase, voff) do { _Pragma("unroll") for (int _i = 0; _i < 2; ++_i) \
;         __builtin_amdgcn_global_load_lds((const unsigned*)((const char*)(gbase) + (voff)[_i]), (LAS unsigned*)(lds + (bufoff) + ldsw + _i * 8192), 16, 0, 0); } while (0)
; #define PG8_LDA(dst, b, h) do { _Pragma("unroll") for (int m = 0; m < 4; ++m) _Pragma("unroll") for (int k = 0; k < 2; ++k) dst[m][k] = *(const LAS bf16x8*)(lds + PG8_SA(b, h) + aoff + m * 2048 + k * 1024); } while (0)
; #define PG8_MMA(ai, bj, At, Bt) do { __builtin_amdgcn_s_setprio(1); _Pragma("unroll") for (int m = 0; m < 4; ++m) _Pragma("unroll") for (int n = 0; n < 2; ++n) _Pragma("unroll") for (int k = 0; k < 2; ++k) \
;         acc[ai][bj][m][n] = __builtin_amdgcn_mfma_f32_16x16x32_bf16(Bt[n][k], At[m][k], acc[ai][bj][m][n], 0, 0, 0); __builtin_amdgcn_s_setprio(0); } while (0)
; #define PG8_WAIT_V(n) asm volatile("s_waitcnt vmcnt(" #n ")" ::: "memory")
; #define PG8_WAIT_L(n) asm volatile("s_waitcnt lgkmcnt(" #n ")" ::: "memory")
; #define PG8_BAR __builtin_amdgcn_s_barrier()
; #define PG8_SCHED __builtin_amdgcn_sched_barrier(0)
; template <class Epi, class Sched = StaticOrder, class EpiSub = NoSub, bool FAST = false>
; __device__ __forceinline__ void gemm_phase(LAS unsigned char* lds, const Gemm g, const Sched& S, const Epi& E, const EpiSub& ES = EpiSub()) {
;     ...
;         for (int t = 0; t < nt; t += 2) {
;     ...
;             PG8_LDA(At, 1, 1); PG8_STAGE(PG8_SB(1, 0), b3, voffB); PG8_STAGE(PG8_SB(1, 1), b3 + hstepB, voffB); PG8_STAGE(PG8_SA(1, 0), a3, voffA);
;             PG8_WAIT_V(8); PG8_WAIT_L(0); PG8_BAR; PG8_MMA(1, 0, At, B0); PG8_MMA(1, 1, At, B1); PG8_BAR; PG8_SCHED;
	s_setprio 0
	s_add_i32 s42, s73, s17
	v_lshl_add_u64 v[208:209], v[208:209], 0, s[12:13]
	s_mov_b32 m0, s42
	ds_read_b128 v[160:163], v217 offset:49152
	ds_read_b128 v[164:167], v217 offset:50176
	ds_read_b128 v[168:171], v217 offset:51200
	ds_read_b128 v[172:175], v217 offset:52224
	ds_read_b128 v[176:179], v217 offset:53248
	ds_read_b128 v[180:183], v217 offset:54272
	ds_read_b128 v[200:203], v217 offset:55296
	ds_read_b128 v[204:207], v217 offset:56320
	global_load_lds_dwordx4 v[208:209], off
	s_add_i32 m0, s42, 0x2000
	s_add_u32 s40, s40, 0x80080
	v_lshl_add_u64 v[208:209], v[210:211], 0, s[12:13]
	s_addc_u32 s41, s41, 0
	s_add_i32 s42, s76, s17
	global_load_lds_dwordx4 v[208:209], off
	v_lshl_add_u64 v[208:209], s[40:41], 0, v[186:187]
	s_mov_b32 m0, s42
	s_nop 0
	global_load_lds_dwordx4 v[208:209], off
	v_lshl_add_u64 v[208:209], s[40:41], 0, v[190:191]
	s_add_i32 m0, s42, 0x2000
	s_nop 0
	global_load_lds_dwordx4 v[208:209], off
	v_lshl_add_u64 v[208:209], v[218:219], 0, s[12:13]
	s_mov_b32 m0, s55
	s_nop 0
	global_load_lds_dwordx4 v[208:209], off
	v_lshl_add_u64 v[208:209], v[220:221], 0, s[12:13]
	s_mov_b32 m0, s56
	s_nop 0
	global_load_lds_dwordx4 v[208:209], off
	s_waitcnt vmcnt(8)
	s_waitcnt lgkmcnt(0)
	s_setprio 1
	s_barrier
	v_mfma_f32_16x16x32_bf16 v[60:63], v[96:99], v[160:163], v[60:63]
	v_mfma_f32_16x16x32_bf16 v[56:59], v[112:115], v[160:163], v[56:59]
	v_mfma_f32_16x16x32_bf16 v[44:47], v[96:99], v[168:171], v[44:47]
	v_mfma_f32_16x16x32_bf16 v[40:43], v[112:115], v[168:171], v[40:43]
	v_mfma_f32_16x16x32_bf16 v[28:31], v[96:99], v[176:179], v[28:31]
	v_mfma_f32_16x16x32_bf16 v[24:27], v[112:115], v[176:179], v[24:27]
	v_mfma_f32_16x16x32_bf16 v[12:15], v[96:99], v[200:203], v[12:15]
	v_mfma_f32_16x16x32_bf16 v[8:11], v[112:115], v[200:203], v[8:11]
	v_mfma_f32_16x16x32_bf16 v[60:63], v[100:103], v[164:167], v[60:63]
	v_mfma_f32_16x16x32_bf16 v[56:59], v[116:119], v[164:167], v[56:59]
	v_mfma_f32_16x16x32_bf16 v[44:47], v[100:103], v[172:175], v[44:47]
	v_mfma_f32_16x16x32_bf16 v[40:43], v[116:119], v[172:175], v[40:43]
	v_mfma_f32_16x16x32_bf16 v[28:31], v[100:103], v[180:183], v[28:31]
	v_mfma_f32_16x16x32_bf16 v[24:27], v[116:119], v[180:183], v[24:27]
	v_mfma_f32_16x16x32_bf16 v[12:15], v[100:103], v[204:207], v[12:15]
	v_mfma_f32_16x16x32_bf16 v[8:11], v[116:119], v[204:207], v[8:11]
	v_mfma_f32_16x16x32_bf16 v[52:55], v[144:147], v[160:163], v[52:55]
	v_mfma_f32_16x16x32_bf16 v[48:51], v[152:155], v[160:163], v[48:51]
	v_mfma_f32_16x16x32_bf16 v[36:39], v[144:147], v[168:171], v[36:39]
	v_mfma_f32_16x16x32_bf16 v[32:35], v[152:155], v[168:171], v[32:35]
	v_mfma_f32_16x16x32_bf16 v[20:23], v[144:147], v[176:179], v[20:23]
	v_mfma_f32_16x16x32_bf16 v[16:19], v[152:155], v[176:179], v[16:19]
	v_mfma_f32_16x16x32_bf16 v[4:7], v[144:147], v[200:203], v[4:7]
	v_mfma_f32_16x16x32_bf16 v[0:3], v[152:155], v[200:203], v[0:3]
	v_mfma_f32_16x16x32_bf16 v[52:55], v[148:151], v[164:167], v[52:55]
	v_mfma_f32_16x16x32_bf16 v[48:51], v[156:159], v[164:167], v[48:51]
	v_mfma_f32_16x16x32_bf16 v[36:39], v[148:151], v[172:175], v[36:39]
	v_mfma_f32_16x16x32_bf16 v[32:35], v[156:159], v[172:175], v[32:35]
	v_mfma_f32_16x16x32_bf16 v[20:23], v[148:151], v[180:183], v[20:23]
	v_mfma_f32_16x16x32_bf16 v[16:19], v[156:159], v[180:183], v[16:19]
	v_mfma_f32_16x16x32_bf16 v[4:7], v[148:151], v[204:207], v[4:7]
	v_mfma_f32_16x16x32_bf16 v[0:3], v[156:159], v[204:207], v[0:3]
	s_barrier
	s_setprio 0
	s_add_u32 s38, s38, 0x100
	s_addc_u32 s39, s39, 0
	s_add_u32 s70, s70, 0x100
	s_addc_u32 s71, s71, 0
	s_cmp_ge_u32 s72, s29
	s_mov_b32 s42, s72
	s_cbranch_scc0 .LBB0_769

; #define PG8_STAGE(bufoff, gbase, voff) do { _Pragma("unroll") for (int _i = 0; _i < 2; ++_i) \
;         __builtin_amdgcn_global_load_lds((const unsigned*)((const char*)(gbase) + (voff)[_i]), (LAS unsigned*)(lds + (bufoff) + ldsw + _i * 8192), 16, 0, 0); } while (0)
; #define PG8_LDA(dst, b, h) do { _Pragma("unroll") for (int m = 0; m < 4; ++m) _Pragma("unroll") for (int k = 0; k < 2; ++k) dst[m][k] = *(const LAS bf16x8*)(lds + PG8_SA(b, h) + aoff + m * 2048 + k * 1024); } while (0)
; #define PG8_LDB(dst, b, h) do { _Pragma("unroll") for (int n = 0; n < 2; ++n) _Pragma("unroll") for (int k = 0; k < 2; ++k) dst[n][k] = *(const LAS bf16x8*)(lds + PG8_SB(b, h) + boff + n * 2048 + k * 1024); } while (0)
; #define PG8_WAIT_V(n) asm volatile("s_waitcnt vmcnt(" #n ")" ::: "memory")
; #define PG8_BAR __builtin_amdgcn_s_barrier()
; template <class Epi, class Sched = StaticOrder, class EpiSub = NoSub, bool FAST = false>
; __device__ __forceinline__ void gemm_phase(LAS unsigned char* lds, const Gemm g, const Sched& S, const Epi& E, const EpiSub& ES = EpiSub()) {
;     ...
;         const bool has_next = S.next(ui + 1, nxt);
;         const size_t nko = (has_next && nxt.kb >= 0) ? nxt.kb * ksubB : 0;
;         const char* nA = has_next ? (const char*)g.A + (size_t)nxt.pm * tstepA + (size_t)nxt.pn * g.acs + nko : cA; const char* nB = has_next ? (const char*)g.Bt + (size_t)nxt.pn * tstepB + nko : cB;
;         const int nt = cur.kb < 0 ? ntMain : ntSub;
;         for (int t = 0; t < nt; t += 2) {
;             const bool last = (t == nt - 2);
;             const char* a1 = cA + (size_t)(t + 1) * kstep;
;             const char* a2 = last ? nA : cA + (size_t)(t + 2) * kstep; const char* b2 = last ? nB : cB + (size_t)(t + 2) * kstep;
;             const char* a3 = a2 + kstep; const char* b3 = b2 + kstep;
;             if constexpr (FAST && PG8_SP2) {
;             PG8_LDB(B0, 0, 0); PG8_LDB(B1, 0, 1); PG8_SCHED; PG8_LDA(At, 0, 0); PG8_STAGE(PG8_SA(1, 1), a1 + hstepA, voffA);
;             PG8_WAIT_V(8); PG8_WAIT_L(0); PG8_BAR; PG8_MMA(0, 0, At, B0); PG8_MMA(0, 1, At, B1); PG8_BAR; PG8_SCHED;
;             PG8_LDA(At, 0, 1); PG8_STAGE(PG8_SB(0, 0), b2, voffB); PG8_STAGE(PG8_SB(0, 1), b2 + hstepB, voffB); PG8_STAGE(PG8_SA(0, 0), a2, voffA);
;             PG8_WAIT_V(8); PG8_WAIT_L(0); PG8_BAR; PG8_MMA(1, 0, At, B0); PG8_MMA(1, 1, At, B1); PG8_BAR; PG8_SCHED;
.LBB0_984:
	s_ashr_i32 s15, s14, 31
	s_lshl_b64 s[16:17], s[14:15], 20
	v_readlane_b32 s18, v254, 36
	v_readlane_b32 s19, v254, 37
	s_add_u32 s16, s18, s16
	s_addc_u32 s17, s19, s17
	s_and_b64 s[18:19], s[0:1], exec
	s_cselect_b32 s15, s17, s23
	s_cselect_b32 s45, s16, s22
	s_ashr_i32 s13, s12, 31
	s_lshl_b64 s[18:19], s[12:13], 20
	s_add_u32 s18, s2, s18
	s_addc_u32 s19, s3, s19
	s_and_b64 s[26:27], s[0:1], exec
	s_cselect_b32 s13, s19, s25
	s_cselect_b32 s46, s18, s24
	s_add_u32 s22, s22, 0x80080
	s_addc_u32 s23, s23, 0
	s_add_u32 s47, s24, 0x100
	s_addc_u32 s48, s25, 0
	s_mov_b32 s49, -2
	ds_read_b128 v[150:153], v147
	ds_read_b128 v[154:157], v147 offset:1024
	ds_read_b128 v[158:161], v147 offset:2048
	ds_read_b128 v[162:165], v147 offset:3072
	ds_read_b128 v[166:169], v148
	ds_read_b128 v[170:173], v148 offset:1024
	ds_read_b128 v[174:177], v148 offset:2048
	ds_read_b128 v[178:181], v148 offset:3072
	s_add_u32 s24, s22, 0xfff80080
	s_addc_u32 s25, s23, -1
	s_cmp_eq_u32 s49, 28
	s_cselect_b32 s27, s15, s25
	s_cselect_b32 s26, s45, s24
	s_cselect_b32 s25, s13, s48
	s_cselect_b32 s24, s46, s47
	v_lshl_add_u64 v[190:191], s[22:23], 0, v[136:137]
	s_add_i32 m0, s21, 0xc000
	ds_read_b128 v[182:185], v149
	ds_read_b128 v[186:189], v149 offset:1024
	ds_read_b128 v[194:197], v149 offset:2048
	ds_read_b128 v[198:201], v149 offset:3072
	ds_read_b128 v[202:205], v149 offset:4096
	ds_read_b128 v[206:209], v149 offset:5120
	ds_read_b128 v[210:213], v149 offset:6144
	ds_read_b128 v[214:217], v149 offset:7168
	global_load_lds_dwordx4 v[190:191], off
	v_lshl_add_u64 v[190:191], s[22:23], 0, v[138:139]
	s_add_i32 m0, s21, 0xe000
	s_nop 0
	global_load_lds_dwordx4 v[190:191], off
	s_waitcnt vmcnt(8)
	s_waitcnt lgkmcnt(0)
	s_setprio 1
	s_barrier
	v_mfma_f32_16x16x32_bf16 v[124:127], v[150:153], v[182:185], 0
	v_mfma_f32_16x16x32_bf16 v[116:119], v[158:161], v[182:185], 0
	v_mfma_f32_16x16x32_bf16 v[108:111], v[150:153], v[194:197], 0
	v_mfma_f32_16x16x32_bf16 v[100:103], v[158:161], v[194:197], 0
	v_mfma_f32_16x16x32_bf16 v[92:95], v[150:153], v[202:205], 0
	v_mfma_f32_16x16x32_bf16 v[84:87], v[158:161], v[202:205], 0
	v_mfma_f32_16x16x32_bf16 v[76:79], v[150:153], v[210:213], 0
	v_mfma_f32_16x16x32_bf16 v[68:71], v[158:161], v[210:213], 0
	v_mfma_f32_16x16x32_bf16 v[124:127], v[154:157], v[186:189], v[124:127]
	v_mfma_f32_16x16x32_bf16 v[116:119], v[162:165], v[186:189], v[116:119]
	v_mfma_f32_16x16x32_bf16 v[108:111], v[154:157], v[198:201], v[108:111]
	v_mfma_f32_16x16x32_bf16 v[100:103], v[162:165], v[198:201], v[100:103]
	v_mfma_f32_16x16x32_bf16 v[92:95], v[154:157], v[206:209], v[92:95]
	v_mfma_f32_16x16x32_bf16 v[84:87], v[162:165], v[206:209], v[84:87]
	v_mfma_f32_16x16x32_bf16 v[76:79], v[154:157], v[214:217], v[76:79]
	v_mfma_f32_16x16x32_bf16 v[68:71], v[162:165], v[214:217], v[68:71]
	v_mfma_f32_16x16x32_bf16 v[120:123], v[166:169], v[182:185], 0
	v_mfma_f32_16x16x32_bf16 v[112:115], v[174:177], v[182:185], 0
	v_mfma_f32_16x16x32_bf16 v[104:107], v[166:169], v[194:197], 0
	v_mfma_f32_16x16x32_bf16 v[96:99], v[174:177], v[194:197], 0
	v_mfma_f32_16x16x32_bf16 v[88:91], v[166:169], v[202:205], 0
	v_mfma_f32_16x16x32_bf16 v[80:83], v[174:177], v[202:205], 0
	v_mfma_f32_16x16x32_bf16 v[72:75], v[166:169], v[210:213], 0
	v_mfma_f32_16x16x32_bf16 v[64:67], v[174:177], v[210:213], 0
	v_mfma_f32_16x16x32_bf16 v[120:123], v[170:173], v[186:189], v[120:123]
	v_mfma_f32_16x16x32_bf16 v[112:115], v[178:181], v[186:189], v[112:115]
	v_mfma_f32_16x16x32_bf16 v[104:107], v[170:173], v[198:201], v[104:107]
	v_mfma_f32_16x16x32_bf16 v[96:99], v[178:181], v[198:201], v[96:99]
	v_mfma_f32_16x16x32_bf16 v[88:91], v[170:173], v[206:209], v[88:91]
	v_mfma_f32_16x16x32_bf16 v[80:83], v[178:181], v[206:209], v[80:83]
	v_mfma_f32_16x16x32_bf16 v[72:75], v[170:173], v[214:217], v[72:75]
	v_mfma_f32_16x16x32_bf16 v[64:67], v[178:181], v[214:217], v[64:67]
	s_barrier
	s_setprio 0
	s_add_i32 s50, s42, s28
	v_lshl_add_u64 v[190:191], s[24:25], 0, v[130:131]
	s_mov_b32 m0, s50
	ds_read_b128 v[182:185], v149 offset:16384
	ds_read_b128 v[186:189], v149 offset:17408
	ds_read_b128 v[194:197], v149 offset:18432
	ds_read_b128 v[198:201], v149 offset:19456
	ds_read_b128 v[202:205], v149 offset:20480
	ds_read_b128 v[206:209], v149 offset:21504
	ds_read_b128 v[210:213], v149 offset:22528
	ds_read_b128 v[214:217], v149 offset:23552
	global_load_lds_dwordx4 v[190:191], off
	s_add_i32 m0, s50, 0x2000
	s_add_u32 s50, s24, 0x80000
	v_lshl_add_u64 v[218:219], s[24:25], 0, v[134:135]
	s_addc_u32 s51, s25, 0
	s_add_i32 s52, s43, s28
	global_load_lds_dwordx4 v[218:219], off
	v_lshl_add_u64 v[220:221], s[50:51], 0, v[130:131]
	s_mov_b32 m0, s52
	v_lshl_add_u64 v[222:223], s[26:27], 0, v[132:133]
	global_load_lds_dwordx4 v[220:221], off
	v_lshl_add_u64 v[220:221], s[50:51], 0, v[134:135]
	s_add_i32 m0, s52, 0x2000
	s_nop 0
	global_load_lds_dwordx4 v[220:221], off
	v_lshl_add_u64 v[220:221], s[26:27], 0, v[128:129]
	s_mov_b32 m0, s21
	s_nop 0
	global_load_lds_dwordx4 v[220:221], off
	s_mov_b32 m0, s31
	s_nop 0
	global_load_lds_dwordx4 v[222:223], off
	s_waitcnt vmcnt(8)
	s_waitcnt lgkmcnt(0)
	s_setprio 1
	s_barrier
; #define PG8_STAGE(bufoff, gbase, voff) do { _Pragma("unroll") for (int _i = 0; _i < 2; ++_i) \
;         __builtin_amdgcn_global_load_lds((const unsigned*)((const char*)(gbase) + (voff)[_i]), (LAS unsigned*)(lds + (bufoff) + ldsw + _i * 8192), 16, 0, 0); } while (0)
; #define PG8_LDA(dst, b, h) do { _Pragma("unroll") for (int m = 0; m < 4; ++m) _Pragma("unroll") for (int k = 0; k < 2; ++k) dst[m][k] = *(const LAS bf16x8*)(lds + PG8_SA(b, h) + aoff + m * 2048 + k * 1024); } while (0)
; #define PG8_LDB(dst, b, h) do { _Pragma("unroll") for (int n = 0; n < 2; ++n) _Pragma("unroll") for (int k = 0; k < 2; ++k) dst[n][k] = *(const LAS bf16x8*)(lds + PG8_SB(b, h) + boff + n * 2048 + k * 1024); } while (0)
; #define PG8_MMA(ai, bj, At, Bt) do { __builtin_amdgcn_s_setprio(1); _Pragma("unroll") for (int m = 0; m < 4; ++m) _Pragma("unroll") for (int n = 0; n < 2; ++n) _Pragma("unroll") for (int k = 0; k < 2; ++k) \
;         acc[ai][bj][m][n] = __builtin_amdgcn_mfma_f32_16x16x32_bf16(Bt[n][k], At[m][k], acc[ai][bj][m][n], 0, 0, 0); __builtin_amdgcn_s_setprio(0); } while (0)
; #define PG8_WAIT_V(n) asm volatile("s_waitcnt vmcnt(" #n ")" ::: "memory")
; #define PG8_WAIT_L(n) asm volatile("s_waitcnt lgkmcnt(" #n ")" ::: "memory")
; #define PG8_BAR __builtin_amdgcn_s_barrier()
; #define PG8_SCHED __builtin_amdgcn_sched_barrier(0)
; template <class Epi, class Sched = StaticOrder, class EpiSub = NoSub, bool FAST = false>
; __device__ __forceinline__ void gemm_phase(LAS unsigned char* lds, const Gemm g, const Sched& S, const Epi& E, const EpiSub& ES = EpiSub()) {
;     ...
;             PG8_WAIT_V(8); PG8_WAIT_L(0); PG8_BAR; PG8_MMA(1, 0, At, B0); PG8_MMA(1, 1, At, B1); PG8_BAR; PG8_SCHED;
;             PG8_LDB(B0, 1, 0); PG8_LDB(B1, 1, 1); PG8_SCHED; PG8_LDA(At, 1, 0); PG8_STAGE(PG8_SA(0, 1), a2 + hstepA, voffA);
;             PG8_WAIT_V(8); PG8_WAIT_L(0); PG8_BAR; PG8_MMA(0, 0, At, B0); PG8_MMA(0, 1, At, B1); PG8_BAR; PG8_SCHED;
	v_mfma_f32_16x16x32_bf16 v[60:63], v[150:153], v[182:185], 0
	v_mfma_f32_16x16x32_bf16 v[52:55], v[158:161], v[182:185], 0
	v_mfma_f32_16x16x32_bf16 v[44:47], v[150:153], v[194:197], 0
	v_mfma_f32_16x16x32_bf16 v[36:39], v[158:161], v[194:197], 0
	v_mfma_f32_16x16x32_bf16 v[28:31], v[150:153], v[202:205], 0
	v_mfma_f32_16x16x32_bf16 v[20:23], v[158:161], v[202:205], 0
	v_mfma_f32_16x16x32_bf16 v[12:15], v[150:153], v[210:213], 0
	v_mfma_f32_16x16x32_bf16 v[4:7], v[158:161], v[210:213], 0
	v_mfma_f32_16x16x32_bf16 v[60:63], v[154:157], v[186:189], v[60:63]
	v_mfma_f32_16x16x32_bf16 v[52:55], v[162:165], v[186:189], v[52:55]
	v_mfma_f32_16x16x32_bf16 v[44:47], v[154:157], v[198:201], v[44:47]
	v_mfma_f32_16x16x32_bf16 v[36:39], v[162:165], v[198:201], v[36:39]
	v_mfma_f32_16x16x32_bf16 v[28:31], v[154:157], v[206:209], v[28:31]
	v_mfma_f32_16x16x32_bf16 v[20:23], v[162:165], v[206:209], v[20:23]
	v_mfma_f32_16x16x32_bf16 v[12:15], v[154:157], v[214:217], v[12:15]
	v_mfma_f32_16x16x32_bf16 v[4:7], v[162:165], v[214:217], v[4:7]
	v_mfma_f32_16x16x32_bf16 v[56:59], v[166:169], v[182:185], 0
	v_mfma_f32_16x16x32_bf16 v[48:51], v[174:177], v[182:185], 0
	v_mfma_f32_16x16x32_bf16 v[40:43], v[166:169], v[194:197], 0
	v_mfma_f32_16x16x32_bf16 v[32:35], v[174:177], v[194:197], 0
	v_mfma_f32_16x16x32_bf16 v[24:27], v[166:169], v[202:205], 0
	v_mfma_f32_16x16x32_bf16 v[16:19], v[174:177], v[202:205], 0
	v_mfma_f32_16x16x32_bf16 v[8:11], v[166:169], v[210:213], 0
	v_mfma_f32_16x16x32_bf16 v[0:3], v[174:177], v[210:213], 0
	v_mfma_f32_16x16x32_bf16 v[56:59], v[170:173], v[186:189], v[56:59]
	v_mfma_f32_16x16x32_bf16 v[48:51], v[178:181], v[186:189], v[48:51]
	v_mfma_f32_16x16x32_bf16 v[40:43], v[170:173], v[198:201], v[40:43]
	v_mfma_f32_16x16x32_bf16 v[32:35], v[178:181], v[198:201], v[32:35]
	v_mfma_f32_16x16x32_bf16 v[24:27], v[170:173], v[206:209], v[24:27]
	v_mfma_f32_16x16x32_bf16 v[16:19], v[178:181], v[206:209], v[16:19]
	v_mfma_f32_16x16x32_bf16 v[8:11], v[170:173], v[214:217], v[8:11]
	v_mfma_f32_16x16x32_bf16 v[0:3], v[178:181], v[214:217], v[0:3]
	s_barrier
	s_setprio 0
	s_add_i32 s50, 0, 0x18000
	s_add_i32 s51, 0, 0x1c000
	v_add_u32_e32 v162, s50, v145
	v_add_u32_e32 v178, s51, v145
	ds_read_b128 v[150:153], v162
	ds_read_b128 v[154:157], v162 offset:1024
	ds_read_b128 v[158:161], v162 offset:2048
	ds_read_b128 v[162:165], v162 offset:3072
	ds_read_b128 v[166:169], v178
	ds_read_b128 v[170:173], v178 offset:1024
	ds_read_b128 v[174:177], v178 offset:2048
	ds_read_b128 v[178:181], v178 offset:3072
	s_add_u32 s26, s26, 0x80000
	s_addc_u32 s27, s27, 0
	s_mov_b32 m0, s36
	v_lshl_add_u64 v[224:225], s[26:27], 0, v[128:129]
	ds_read_b128 v[182:185], v149 offset:32768
	ds_read_b128 v[186:189], v149 offset:33792
	ds_read_b128 v[194:197], v149 offset:34816
	ds_read_b128 v[198:201], v149 offset:35840
	ds_read_b128 v[202:205], v149 offset:36864
	ds_read_b128 v[206:209], v149 offset:37888
	ds_read_b128 v[210:213], v149 offset:38912
	ds_read_b128 v[214:217], v149 offset:39936
	global_load_lds_dwordx4 v[224:225], off
	v_lshl_add_u64 v[224:225], s[26:27], 0, v[132:133]
	s_mov_b32 m0, s37
	s_nop 0
	global_load_lds_dwordx4 v[224:225], off
	s_waitcnt vmcnt(8)
	s_waitcnt lgkmcnt(0)
	s_setprio 1
	s_barrier
	v_mfma_f32_16x16x32_bf16 v[124:127], v[150:153], v[182:185], v[124:127]
	v_mfma_f32_16x16x32_bf16 v[116:119], v[158:161], v[182:185], v[116:119]
	v_mfma_f32_16x16x32_bf16 v[108:111], v[150:153], v[194:197], v[108:111]
	v_mfma_f32_16x16x32_bf16 v[100:103], v[158:161], v[194:197], v[100:103]
	v_mfma_f32_16x16x32_bf16 v[92:95], v[150:153], v[202:205], v[92:95]
	v_mfma_f32_16x16x32_bf16 v[84:87], v[158:161], v[202:205], v[84:87]
	v_mfma_f32_16x16x32_bf16 v[76:79], v[150:153], v[210:213], v[76:79]
	v_mfma_f32_16x16x32_bf16 v[68:71], v[158:161], v[210:213], v[68:71]
	v_mfma_f32_16x16x32_bf16 v[124:127], v[154:157], v[186:189], v[124:127]
	v_mfma_f32_16x16x32_bf16 v[116:119], v[162:165], v[186:189], v[116:119]
	v_mfma_f32_16x16x32_bf16 v[108:111], v[154:157], v[198:201], v[108:111]
	v_mfma_f32_16x16x32_bf16 v[100:103], v[162:165], v[198:201], v[100:103]
	v_mfma_f32_16x16x32_bf16 v[92:95], v[154:157], v[206:209], v[92:95]
	v_mfma_f32_16x16x32_bf16 v[84:87], v[162:165], v[206:209], v[84:87]
	v_mfma_f32_16x16x32_bf16 v[76:79], v[154:157], v[214:217], v[76:79]
	v_mfma_f32_16x16x32_bf16 v[68:71], v[162:165], v[214:217], v[68:71]
	v_mfma_f32_16x16x32_bf16 v[120:123], v[166:169], v[182:185], v[120:123]
	v_mfma_f32_16x16x32_bf16 v[112:115], v[174:177], v[182:185], v[112:115]
	v_mfma_f32_16x16x32_bf16 v[104:107], v[166:169], v[194:197], v[104:107]
	v_mfma_f32_16x16x32_bf16 v[96:99], v[174:177], v[194:197], v[96:99]
	v_mfma_f32_16x16x32_bf16 v[88:91], v[166:169], v[202:205], v[88:91]
	v_mfma_f32_16x16x32_bf16 v[80:83], v[174:177], v[202:205], v[80:83]
	v_mfma_f32_16x16x32_bf16 v[72:75], v[166:169], v[210:213], v[72:75]
	v_mfma_f32_16x16x32_bf16 v[64:67], v[174:177], v[210:213], v[64:67]
	v_mfma_f32_16x16x32_bf16 v[120:123], v[170:173], v[186:189], v[120:123]
	v_mfma_f32_16x16x32_bf16 v[112:115], v[178:181], v[186:189], v[112:115]
	v_mfma_f32_16x16x32_bf16 v[104:107], v[170:173], v[198:201], v[104:107]
	v_mfma_f32_16x16x32_bf16 v[96:99], v[178:181], v[198:201], v[96:99]
	v_mfma_f32_16x16x32_bf16 v[88:91], v[170:173], v[206:209], v[88:91]
	v_mfma_f32_16x16x32_bf16 v[80:83], v[178:181], v[206:209], v[80:83]
	v_mfma_f32_16x16x32_bf16 v[72:75], v[170:173], v[214:217], v[72:75]
	v_mfma_f32_16x16x32_bf16 v[64:67], v[178:181], v[214:217], v[64:67]
	s_barrier
; #define PG8_STAGE(bufoff, gbase, voff) do { _Pragma("unroll") for (int _i = 0; _i < 2; ++_i) \
;         __builtin_amdgcn_global_load_lds((const unsigned*)((const char*)(gbase) + (voff)[_i]), (LAS unsigned*)(lds + (bufoff) + ldsw + _i * 8192), 16, 0, 0); } while (0)
; #define PG8_LDA(dst, b, h) do { _Pragma("unroll") for (int m = 0; m < 4; ++m) _Pragma("unroll") for (int k = 0; k < 2; ++k) dst[m][k] = *(const LAS bf16x8*)(lds + PG8_SA(b, h) + aoff + m * 2048 + k * 1024); } while (0)
; #define PG8_LDB(dst, b, h) do { _Pragma("unroll") for (int n = 0; n < 2; ++n) _Pragma("unroll") for (int k = 0; k < 2; ++k) dst[n][k] = *(const LAS bf16x8*)(lds + PG8_SB(b, h) + boff + n * 2048 + k * 1024); } while (0)
; template <class Epi, class Sched = StaticOrder, class EpiSub = NoSub, bool FAST = false>
; __device__ __forceinline__ void gemm_phase(LAS unsigned char* lds, const Gemm g, const Sched& S, const Epi& E, const EpiSub& ES = EpiSub()) {
;     ...
;         for (int t = 0; t < nt; t += 2) {
;             const bool last = (t == nt - 2);
;             const char* a1 = cA + (size_t)(t + 1) * kstep;
;             const char* a2 = last ? nA : cA + (size_t)(t + 2) * kstep; const char* b2 = last ? nB : cB + (size_t)(t + 2) * kstep;
;             const char* a3 = a2 + kstep; const char* b3 = b2 + kstep;
;             if constexpr (FAST && PG8_SP2) {
;             PG8_LDB(B0, 0, 0); PG8_LDB(B1, 0, 1); PG8_SCHED; PG8_LDA(At, 0, 0); PG8_STAGE(PG8_SA(1, 1), a1 + hstepA, voffA);
;             PG8_WAIT_V(8); PG8_WAIT_L(0); PG8_BAR; PG8_MMA(0, 0, At, B0); PG8_MMA(0, 1, At, B1); PG8_BAR; PG8_SCHED;
;             PG8_LDA(At, 0, 1); PG8_STAGE(PG8_SB(0, 0), b2, voffB); PG8_STAGE(PG8_SB(0, 1), b2 + hstepB, voffB); PG8_STAGE(PG8_SA(0, 0), a2, voffA);
;             PG8_WAIT_V(8); PG8_WAIT_L(0); PG8_BAR; PG8_MMA(1, 0, At, B0); PG8_MMA(1, 1, At, B1); PG8_BAR; PG8_SCHED;
;             PG8_LDB(B0, 1, 0); PG8_LDB(B1, 1, 1); PG8_SCHED; PG8_LDA(At, 1, 0); PG8_STAGE(PG8_SA(0, 1), a2 + hstepA, voffA);
;             PG8_WAIT_V(8); PG8_WAIT_L(0); PG8_BAR; PG8_MMA(0, 0, At, B0); PG8_MMA(0, 1, At, B1); PG8_BAR; PG8_SCHED;
;             PG8_LDA(At, 1, 1); PG8_STAGE(PG8_SB(1, 0), b3, voffB); PG8_STAGE(PG8_SB(1, 1), b3 + hstepB, voffB); PG8_STAGE(PG8_SA(1, 0), a3, voffA);
;             PG8_WAIT_V(8); PG8_WAIT_L(0); PG8_BAR; PG8_MMA(1, 0, At, B0); PG8_MMA(1, 1, At, B1); PG8_BAR; PG8_SCHED;
	s_setprio 0
	s_add_i32 s26, s50, s28
	v_lshl_add_u64 v[190:191], v[190:191], 0, s[8:9]
	s_mov_b32 m0, s26
	ds_read_b128 v[182:185], v149 offset:49152
	ds_read_b128 v[186:189], v149 offset:50176
	ds_read_b128 v[194:197], v149 offset:51200
	ds_read_b128 v[198:201], v149 offset:52224
	ds_read_b128 v[202:205], v149 offset:53248
	ds_read_b128 v[206:209], v149 offset:54272
	ds_read_b128 v[210:213], v149 offset:55296
	ds_read_b128 v[214:217], v149 offset:56320
	global_load_lds_dwordx4 v[190:191], off
	s_add_i32 m0, s26, 0x2000
	s_add_u32 s24, s24, 0x80080
	v_lshl_add_u64 v[190:191], v[218:219], 0, s[8:9]
	s_addc_u32 s25, s25, 0
	s_add_i32 s26, s51, s28
	global_load_lds_dwordx4 v[190:191], off
	v_lshl_add_u64 v[190:191], s[24:25], 0, v[130:131]
	s_mov_b32 m0, s26
	s_nop 0
	global_load_lds_dwordx4 v[190:191], off
	v_lshl_add_u64 v[190:191], s[24:25], 0, v[134:135]
	s_add_i32 m0, s26, 0x2000
	s_nop 0
	global_load_lds_dwordx4 v[190:191], off
	v_lshl_add_u64 v[190:191], v[220:221], 0, s[8:9]
	s_mov_b32 m0, s40
	s_nop 0
	global_load_lds_dwordx4 v[190:191], off
	v_lshl_add_u64 v[190:191], v[222:223], 0, s[8:9]
	s_mov_b32 m0, s41
	s_nop 0
	global_load_lds_dwordx4 v[190:191], off
	s_waitcnt vmcnt(8)
	s_waitcnt lgkmcnt(0)
	s_setprio 1
	s_barrier
	v_mfma_f32_16x16x32_bf16 v[60:63], v[150:153], v[182:185], v[60:63]
	v_mfma_f32_16x16x32_bf16 v[52:55], v[158:161], v[182:185], v[52:55]
	v_mfma_f32_16x16x32_bf16 v[44:47], v[150:153], v[194:197], v[44:47]
	v_mfma_f32_16x16x32_bf16 v[36:39], v[158:161], v[194:197], v[36:39]
	v_mfma_f32_16x16x32_bf16 v[28:31], v[150:153], v[202:205], v[28:31]
	v_mfma_f32_16x16x32_bf16 v[20:23], v[158:161], v[202:205], v[20:23]
	v_mfma_f32_16x16x32_bf16 v[12:15], v[150:153], v[210:213], v[12:15]
	v_mfma_f32_16x16x32_bf16 v[4:7], v[158:161], v[210:213], v[4:7]
	v_mfma_f32_16x16x32_bf16 v[60:63], v[154:157], v[186:189], v[60:63]
	v_mfma_f32_16x16x32_bf16 v[52:55], v[162:165], v[186:189], v[52:55]
	v_mfma_f32_16x16x32_bf16 v[44:47], v[154:157], v[198:201], v[44:47]
	v_mfma_f32_16x16x32_bf16 v[36:39], v[162:165], v[198:201], v[36:39]
	v_mfma_f32_16x16x32_bf16 v[28:31], v[154:157], v[206:209], v[28:31]
	v_mfma_f32_16x16x32_bf16 v[20:23], v[162:165], v[206:209], v[20:23]
	v_mfma_f32_16x16x32_bf16 v[12:15], v[154:157], v[214:217], v[12:15]
	v_mfma_f32_16x16x32_bf16 v[4:7], v[162:165], v[214:217], v[4:7]
	v_mfma_f32_16x16x32_bf16 v[56:59], v[166:169], v[182:185], v[56:59]
	v_mfma_f32_16x16x32_bf16 v[48:51], v[174:177], v[182:185], v[48:51]
	v_mfma_f32_16x16x32_bf16 v[40:43], v[166:169], v[194:197], v[40:43]
	v_mfma_f32_16x16x32_bf16 v[32:35], v[174:177], v[194:197], v[32:35]
	v_mfma_f32_16x16x32_bf16 v[24:27], v[166:169], v[202:205], v[24:27]
	v_mfma_f32_16x16x32_bf16 v[16:19], v[174:177], v[202:205], v[16:19]
	v_mfma_f32_16x16x32_bf16 v[8:11], v[166:169], v[210:213], v[8:11]
	v_mfma_f32_16x16x32_bf16 v[0:3], v[174:177], v[210:213], v[0:3]
	v_mfma_f32_16x16x32_bf16 v[56:59], v[170:173], v[186:189], v[56:59]
	v_mfma_f32_16x16x32_bf16 v[48:51], v[178:181], v[186:189], v[48:51]
	v_mfma_f32_16x16x32_bf16 v[40:43], v[170:173], v[198:201], v[40:43]
	v_mfma_f32_16x16x32_bf16 v[32:35], v[178:181], v[198:201], v[32:35]
	v_mfma_f32_16x16x32_bf16 v[24:27], v[170:173], v[206:209], v[24:27]
	v_mfma_f32_16x16x32_bf16 v[16:19], v[178:181], v[206:209], v[16:19]
	v_mfma_f32_16x16x32_bf16 v[8:11], v[170:173], v[214:217], v[8:11]
	v_mfma_f32_16x16x32_bf16 v[0:3], v[178:181], v[214:217], v[0:3]
	s_barrier
	s_setprio 0
	s_add_i32 s49, s49, 2
	s_add_u32 s22, s22, 0x100
	s_addc_u32 s23, s23, 0
	s_add_u32 s47, s47, 0x100
	s_addc_u32 s48, s48, 0
	s_cmp_gt_u32 s49, 29
	s_cbranch_scc1 .Lkpeel_985_exit
.LBB0_985:
	ds_read_b128 v[150:153], v147
	ds_read_b128 v[154:157], v147 offset:1024
	ds_read_b128 v[158:161], v147 offset:2048
	ds_read_b128 v[162:165], v147 offset:3072
	ds_read_b128 v[166:169], v148
	ds_read_b128 v[170:173], v148 offset:1024
	ds_read_b128 v[174:177], v148 offset:2048
	ds_read_b128 v[178:181], v148 offset:3072
	s_add_u32 s24, s22, 0xfff80080
	s_addc_u32 s25, s23, -1
	s_cmp_eq_u32 s49, 28
	s_cselect_b32 s27, s15, s25
	s_cselect_b32 s26, s45, s24
	s_cselect_b32 s25, s13, s48
	s_cselect_b32 s24, s46, s47
	v_lshl_add_u64 v[190:191], s[22:23], 0, v[136:137]
	s_add_i32 m0, s21, 0xc000
	ds_read_b128 v[182:185], v149
	ds_read_b128 v[186:189], v149 offset:1024
	ds_read_b128 v[194:197], v149 offset:2048
	ds_read_b128 v[198:201], v149 offset:3072
	ds_read_b128 v[202:205], v149 offset:4096
	ds_read_b128 v[206:209], v149 offset:5120
	ds_read_b128 v[210:213], v149 offset:6144
	ds_read_b128 v[214:217], v149 offset:7168
	global_load_lds_dwordx4 v[190:191], off
	v_lshl_add_u64 v[190:191], s[22:23], 0, v[138:139]
	s_add_i32 m0, s21, 0xe000
	s_nop 0
	global_load_lds_dwordx4 v[190:191], off
	s_waitcnt vmcnt(8)
	s_waitcnt lgkmcnt(0)
	s_setprio 1
	s_barrier
; #define PG8_STAGE(bufoff, gbase, voff) do { _Pragma("unroll") for (int _i = 0; _i < 2; ++_i) \
;         __builtin_amdgcn_global_load_lds((const unsigned*)((const char*)(gbase) + (voff)[_i]), (LAS unsigned*)(lds + (bufoff) + ldsw + _i * 8192), 16, 0, 0); } while (0)
; #define PG8_LDA(dst, b, h) do { _Pragma("unroll") for (int m = 0; m < 4; ++m) _Pragma("unroll") for (int k = 0; k < 2; ++k) dst[m][k] = *(const LAS bf16x8*)(lds + PG8_SA(b, h) + aoff + m * 2048 + k * 1024); } while (0)
; #define PG8_LDB(dst, b, h) do { _Pragma("unroll") for (int n = 0; n < 2; ++n) _Pragma("unroll") for (int k = 0; k < 2; ++k) dst[n][k] = *(const LAS bf16x8*)(lds + PG8_SB(b, h) + boff + n * 2048 + k * 1024); } while (0)
; #define PG8_MMA(ai, bj, At, Bt) do { __builtin_amdgcn_s_setprio(1); _Pragma("unroll") for (int m = 0; m < 4; ++m) _Pragma("unroll") for (int n = 0; n < 2; ++n) _Pragma("unroll") for (int k = 0; k < 2; ++k) \
;         acc[ai][bj][m][n] = __builtin_amdgcn_mfma_f32_16x16x32_bf16(Bt[n][k], At[m][k], acc[ai][bj][m][n], 0, 0, 0); __builtin_amdgcn_s_setprio(0); } while (0)
; #define PG8_WAIT_V(n) asm volatile("s_waitcnt vmcnt(" #n ")" ::: "memory")
; #define PG8_WAIT_L(n) asm volatile("s_waitcnt lgkmcnt(" #n ")" ::: "memory")
; #define PG8_BAR __builtin_amdgcn_s_barrier()
; #define PG8_SCHED __builtin_amdgcn_sched_barrier(0)
; template <class Epi, class Sched = StaticOrder, class EpiSub = NoSub, bool FAST = false>
; __device__ __forceinline__ void gemm_phase(LAS unsigned char* lds, const Gemm g, const Sched& S, const Epi& E, const EpiSub& ES = EpiSub()) {
;     ...
;             PG8_LDB(B0, 0, 0); PG8_LDB(B1, 0, 1); PG8_SCHED; PG8_LDA(At, 0, 0); PG8_STAGE(PG8_SA(1, 1), a1 + hstepA, voffA);
;             PG8_WAIT_V(8); PG8_WAIT_L(0); PG8_BAR; PG8_MMA(0, 0, At, B0); PG8_MMA(0, 1, At, B1); PG8_BAR; PG8_SCHED;
;             PG8_LDA(At, 0, 1); PG8_STAGE(PG8_SB(0, 0), b2, voffB); PG8_STAGE(PG8_SB(0, 1), b2 + hstepB, voffB); PG8_STAGE(PG8_SA(0, 0), a2, voffA);
;             PG8_WAIT_V(8); PG8_WAIT_L(0); PG8_BAR; PG8_MMA(1, 0, At, B0); PG8_MMA(1, 1, At, B1); PG8_BAR; PG8_SCHED;
	v_mfma_f32_16x16x32_bf16 v[124:127], v[150:153], v[182:185], v[124:127]
	v_mfma_f32_16x16x32_bf16 v[116:119], v[158:161], v[182:185], v[116:119]
	v_mfma_f32_16x16x32_bf16 v[108:111], v[150:153], v[194:197], v[108:111]
	v_mfma_f32_16x16x32_bf16 v[100:103], v[158:161], v[194:197], v[100:103]
	v_mfma_f32_16x16x32_bf16 v[92:95], v[150:153], v[202:205], v[92:95]
	v_mfma_f32_16x16x32_bf16 v[84:87], v[158:161], v[202:205], v[84:87]
	v_mfma_f32_16x16x32_bf16 v[76:79], v[150:153], v[210:213], v[76:79]
	v_mfma_f32_16x16x32_bf16 v[68:71], v[158:161], v[210:213], v[68:71]
	v_mfma_f32_16x16x32_bf16 v[124:127], v[154:157], v[186:189], v[124:127]
	v_mfma_f32_16x16x32_bf16 v[116:119], v[162:165], v[186:189], v[116:119]
	v_mfma_f32_16x16x32_bf16 v[108:111], v[154:157], v[198:201], v[108:111]
	v_mfma_f32_16x16x32_bf16 v[100:103], v[162:165], v[198:201], v[100:103]
	v_mfma_f32_16x16x32_bf16 v[92:95], v[154:157], v[206:209], v[92:95]
	v_mfma_f32_16x16x32_bf16 v[84:87], v[162:165], v[206:209], v[84:87]
	v_mfma_f32_16x16x32_bf16 v[76:79], v[154:157], v[214:217], v[76:79]
	v_mfma_f32_16x16x32_bf16 v[68:71], v[162:165], v[214:217], v[68:71]
	v_mfma_f32_16x16x32_bf16 v[120:123], v[166:169], v[182:185], v[120:123]
	v_mfma_f32_16x16x32_bf16 v[112:115], v[174:177], v[182:185], v[112:115]
	v_mfma_f32_16x16x32_bf16 v[104:107], v[166:169], v[194:197], v[104:107]
	v_mfma_f32_16x16x32_bf16 v[96:99], v[174:177], v[194:197], v[96:99]
	v_mfma_f32_16x16x32_bf16 v[88:91], v[166:169], v[202:205], v[88:91]
	v_mfma_f32_16x16x32_bf16 v[80:83], v[174:177], v[202:205], v[80:83]
	v_mfma_f32_16x16x32_bf16 v[72:75], v[166:169], v[210:213], v[72:75]
	v_mfma_f32_16x16x32_bf16 v[64:67], v[174:177], v[210:213], v[64:67]
	v_mfma_f32_16x16x32_bf16 v[120:123], v[170:173], v[186:189], v[120:123]
	v_mfma_f32_16x16x32_bf16 v[112:115], v[178:181], v[186:189], v[112:115]
	v_mfma_f32_16x16x32_bf16 v[104:107], v[170:173], v[198:201], v[104:107]
	v_mfma_f32_16x16x32_bf16 v[96:99], v[178:181], v[198:201], v[96:99]
	v_mfma_f32_16x16x32_bf16 v[88:91], v[170:173], v[206:209], v[88:91]
	v_mfma_f32_16x16x32_bf16 v[80:83], v[178:181], v[206:209], v[80:83]
	v_mfma_f32_16x16x32_bf16 v[72:75], v[170:173], v[214:217], v[72:75]
	v_mfma_f32_16x16x32_bf16 v[64:67], v[178:181], v[214:217], v[64:67]
	s_barrier
	s_setprio 0
	s_add_i32 s50, s42, s28
	v_lshl_add_u64 v[190:191], s[24:25], 0, v[130:131]
	s_mov_b32 m0, s50
	ds_read_b128 v[182:185], v149 offset:16384
	ds_read_b128 v[186:189], v149 offset:17408
	ds_read_b128 v[194:197], v149 offset:18432
	ds_read_b128 v[198:201], v149 offset:19456
	ds_read_b128 v[202:205], v149 offset:20480
	ds_read_b128 v[206:209], v149 offset:21504
	ds_read_b128 v[210:213], v149 offset:22528
	ds_read_b128 v[214:217], v149 offset:23552
	global_load_lds_dwordx4 v[190:191], off
	s_add_i32 m0, s50, 0x2000
	s_add_u32 s50, s24, 0x80000
	v_lshl_add_u64 v[218:219], s[24:25], 0, v[134:135]
	s_addc_u32 s51, s25, 0
	s_add_i32 s52, s43, s28
	global_load_lds_dwordx4 v[218:219], off
	v_lshl_add_u64 v[220:221], s[50:51], 0, v[130:131]
	s_mov_b32 m0, s52
	v_lshl_add_u64 v[222:223], s[26:27], 0, v[132:133]
	global_load_lds_dwordx4 v[220:221], off
	v_lshl_add_u64 v[220:221], s[50:51], 0, v[134:135]
	s_add_i32 m0, s52, 0x2000
	s_nop 0
	global_load_lds_dwordx4 v[220:221], off
	v_lshl_add_u64 v[220:221], s[26:27], 0, v[128:129]
	s_mov_b32 m0, s21
	s_nop 0
	global_load_lds_dwordx4 v[220:221], off
	s_mov_b32 m0, s31
	s_nop 0
	global_load_lds_dwordx4 v[222:223], off
	s_waitcnt vmcnt(8)
	s_waitcnt lgkmcnt(0)
	s_setprio 1
	s_barrier
	v_mfma_f32_16x16x32_bf16 v[60:63], v[150:153], v[182:185], v[60:63]
	v_mfma_f32_16x16x32_bf16 v[52:55], v[158:161], v[182:185], v[52:55]
	v_mfma_f32_16x16x32_bf16 v[44:47], v[150:153], v[194:197], v[44:47]
	v_mfma_f32_16x16x32_bf16 v[36:39], v[158:161], v[194:197], v[36:39]
	v_mfma_f32_16x16x32_bf16 v[28:31], v[150:153], v[202:205], v[28:31]
	v_mfma_f32_16x16x32_bf16 v[20:23], v[158:161], v[202:205], v[20:23]
	v_mfma_f32_16x16x32_bf16 v[12:15], v[150:153], v[210:213], v[12:15]
	v_mfma_f32_16x16x32_bf16 v[4:7], v[158:161], v[210:213], v[4:7]
	v_mfma_f32_16x16x32_bf16 v[60:63], v[154:157], v[186:189], v[60:63]
	v_mfma_f32_16x16x32_bf16 v[52:55], v[162:165], v[186:189], v[52:55]
	v_mfma_f32_16x16x32_bf16 v[44:47], v[154:157], v[198:201], v[44:47]
	v_mfma_f32_16x16x32_bf16 v[36:39], v[162:165], v[198:201], v[36:39]
	v_mfma_f32_16x16x32_bf16 v[28:31], v[154:157], v[206:209], v[28:31]
	v_mfma_f32_16x16x32_bf16 v[20:23], v[162:165], v[206:209], v[20:23]
	v_mfma_f32_16x16x32_bf16 v[12:15], v[154:157], v[214:217], v[12:15]
	v_mfma_f32_16x16x32_bf16 v[4:7], v[162:165], v[214:217], v[4:7]
	v_mfma_f32_16x16x32_bf16 v[56:59], v[166:169], v[182:185], v[56:59]
	v_mfma_f32_16x16x32_bf16 v[48:51], v[174:177], v[182:185], v[48:51]
	v_mfma_f32_16x16x32_bf16 v[40:43], v[166:169], v[194:197], v[40:43]
	v_mfma_f32_16x16x32_bf16 v[32:35], v[174:177], v[194:197], v[32:35]
	v_mfma_f32_16x16x32_bf16 v[24:27], v[166:169], v[202:205], v[24:27]
	v_mfma_f32_16x16x32_bf16 v[16:19], v[174:177], v[202:205], v[16:19]
	v_mfma_f32_16x16x32_bf16 v[8:11], v[166:169], v[210:213], v[8:11]
	v_mfma_f32_16x16x32_bf16 v[0:3], v[174:177], v[210:213], v[0:3]
	v_mfma_f32_16x16x32_bf16 v[56:59], v[170:173], v[186:189], v[56:59]
	v_mfma_f32_16x16x32_bf16 v[48:51], v[178:181], v[186:189], v[48:51]
	v_mfma_f32_16x16x32_bf16 v[40:43], v[170:173], v[198:201], v[40:43]
	v_mfma_f32_16x16x32_bf16 v[32:35], v[178:181], v[198:201], v[32:35]
	v_mfma_f32_16x16x32_bf16 v[24:27], v[170:173], v[206:209], v[24:27]
	v_mfma_f32_16x16x32_bf16 v[16:19], v[178:181], v[206:209], v[16:19]
	v_mfma_f32_16x16x32_bf16 v[8:11], v[170:173], v[214:217], v[8:11]
	v_mfma_f32_16x16x32_bf16 v[0:3], v[178:181], v[214:217], v[0:3]
	s_barrier
; #define PG8_STAGE(bufoff, gbase, voff) do { _Pragma("unroll") for (int _i = 0; _i < 2; ++_i) \
;         __builtin_amdgcn_global_load_lds((const unsigned*)((const char*)(gbase) + (voff)[_i]), (LAS unsigned*)(lds + (bufoff) + ldsw + _i * 8192), 16, 0, 0); } while (0)
; #define PG8_LDA(dst, b, h) do { _Pragma("unroll") for (int m = 0; m < 4; ++m) _Pragma("unroll") for (int k = 0; k < 2; ++k) dst[m][k] = *(const LAS bf16x8*)(lds + PG8_SA(b, h) + aoff + m * 2048 + k * 1024); } while (0)
; #define PG8_LDB(dst, b, h) do { _Pragma("unroll") for (int n = 0; n < 2; ++n) _Pragma("unroll") for (int k = 0; k < 2; ++k) dst[n][k] = *(const LAS bf16x8*)(lds + PG8_SB(b, h) + boff + n * 2048 + k * 1024); } while (0)
; #define PG8_MMA(ai, bj, At, Bt) do { __builtin_amdgcn_s_setprio(1); _Pragma("unroll") for (int m = 0; m < 4; ++m) _Pragma("unroll") for (int n = 0; n < 2; ++n) _Pragma("unroll") for (int k = 0; k < 2; ++k) \
;         acc[ai][bj][m][n] = __builtin_amdgcn_mfma_f32_16x16x32_bf16(Bt[n][k], At[m][k], acc[ai][bj][m][n], 0, 0, 0); __builtin_amdgcn_s_setprio(0); } while (0)
; #define PG8_WAIT_V(n) asm volatile("s_waitcnt vmcnt(" #n ")" ::: "memory")
; #define PG8_WAIT_L(n) asm volatile("s_waitcnt lgkmcnt(" #n ")" ::: "memory")
; #define PG8_BAR __builtin_amdgcn_s_barrier()
; #define PG8_SCHED __builtin_amdgcn_sched_barrier(0)
; template <class Epi, class Sched = StaticOrder, class EpiSub = NoSub, bool FAST = false>
; __device__ __forceinline__ void gemm_phase(LAS unsigned char* lds, const Gemm g, const Sched& S, const Epi& E, const EpiSub& ES = EpiSub()) {
;     ...
;             PG8_LDB(B0, 1, 0); PG8_LDB(B1, 1, 1); PG8_SCHED; PG8_LDA(At, 1, 0); PG8_STAGE(PG8_SA(0, 1), a2 + hstepA, voffA);
;             PG8_WAIT_V(8); PG8_WAIT_L(0); PG8_BAR; PG8_MMA(0, 0, At, B0); PG8_MMA(0, 1, At, B1); PG8_BAR; PG8_SCHED;
	s_setprio 0
	s_add_i32 s50, 0, 0x18000
	s_add_i32 s51, 0, 0x1c000
	v_add_u32_e32 v162, s50, v145
	v_add_u32_e32 v178, s51, v145
	ds_read_b128 v[150:153], v162
	ds_read_b128 v[154:157], v162 offset:1024
	ds_read_b128 v[158:161], v162 offset:2048
	ds_read_b128 v[162:165], v162 offset:3072
	ds_read_b128 v[166:169], v178
	ds_read_b128 v[170:173], v178 offset:1024
	ds_read_b128 v[174:177], v178 offset:2048
	ds_read_b128 v[178:181], v178 offset:3072
	s_add_u32 s26, s26, 0x80000
	s_addc_u32 s27, s27, 0
	s_mov_b32 m0, s36
	v_lshl_add_u64 v[224:225], s[26:27], 0, v[128:129]
	ds_read_b128 v[182:185], v149 offset:32768
	ds_read_b128 v[186:189], v149 offset:33792
	ds_read_b128 v[194:197], v149 offset:34816
	ds_read_b128 v[198:201], v149 offset:35840
	ds_read_b128 v[202:205], v149 offset:36864
	ds_read_b128 v[206:209], v149 offset:37888
	ds_read_b128 v[210:213], v149 offset:38912
	ds_read_b128 v[214:217], v149 offset:39936
	global_load_lds_dwordx4 v[224:225], off
	v_lshl_add_u64 v[224:225], s[26:27], 0, v[132:133]
	s_mov_b32 m0, s37
	s_nop 0
	global_load_lds_dwordx4 v[224:225], off
	s_waitcnt vmcnt(8)
	s_waitcnt lgkmcnt(0)
	s_setprio 1
	s_barrier
	v_mfma_f32_16x16x32_bf16 v[124:127], v[150:153], v[182:185], v[124:127]
	v_mfma_f32_16x16x32_bf16 v[116:119], v[158:161], v[182:185], v[116:119]
	v_mfma_f32_16x16x32_bf16 v[108:111], v[150:153], v[194:197], v[108:111]
	v_mfma_f32_16x16x32_bf16 v[100:103], v[158:161], v[194:197], v[100:103]
	v_mfma_f32_16x16x32_bf16 v[92:95], v[150:153], v[202:205], v[92:95]
	v_mfma_f32_16x16x32_bf16 v[84:87], v[158:161], v[202:205], v[84:87]
	v_mfma_f32_16x16x32_bf16 v[76:79], v[150:153], v[210:213], v[76:79]
	v_mfma_f32_16x16x32_bf16 v[68:71], v[158:161], v[210:213], v[68:71]
	v_mfma_f32_16x16x32_bf16 v[124:127], v[154:157], v[186:189], v[124:127]
	v_mfma_f32_16x16x32_bf16 v[116:119], v[162:165], v[186:189], v[116:119]
	v_mfma_f32_16x16x32_bf16 v[108:111], v[154:157], v[198:201], v[108:111]
	v_mfma_f32_16x16x32_bf16 v[100:103], v[162:165], v[198:201], v[100:103]
	v_mfma_f32_16x16x32_bf16 v[92:95], v[154:157], v[206:209], v[92:95]
	v_mfma_f32_16x16x32_bf16 v[84:87], v[162:165], v[206:209], v[84:87]
	v_mfma_f32_16x16x32_bf16 v[76:79], v[154:157], v[214:217], v[76:79]
	v_mfma_f32_16x16x32_bf16 v[68:71], v[162:165], v[214:217], v[68:71]
	v_mfma_f32_16x16x32_bf16 v[120:123], v[166:169], v[182:185], v[120:123]
	v_mfma_f32_16x16x32_bf16 v[112:115], v[174:177], v[182:185], v[112:115]
	v_mfma_f32_16x16x32_bf16 v[104:107], v[166:169], v[194:197], v[104:107]
	v_mfma_f32_16x16x32_bf16 v[96:99], v[174:177], v[194:197], v[96:99]
	v_mfma_f32_16x16x32_bf16 v[88:91], v[166:169], v[202:205], v[88:91]
	v_mfma_f32_16x16x32_bf16 v[80:83], v[174:177], v[202:205], v[80:83]
	v_mfma_f32_16x16x32_bf16 v[72:75], v[166:169], v[210:213], v[72:75]
	v_mfma_f32_16x16x32_bf16 v[64:67], v[174:177], v[210:213], v[64:67]
	v_mfma_f32_16x16x32_bf16 v[120:123], v[170:173], v[186:189], v[120:123]
	v_mfma_f32_16x16x32_bf16 v[112:115], v[178:181], v[186:189], v[112:115]
	v_mfma_f32_16x16x32_bf16 v[104:107], v[170:173], v[198:201], v[104:107]
	v_mfma_f32_16x16x32_bf16 v[96:99], v[178:181], v[198:201], v[96:99]
	v_mfma_f32_16x16x32_bf16 v[88:91], v[170:173], v[206:209], v[88:91]
	v_mfma_f32_16x16x32_bf16 v[80:83], v[178:181], v[206:209], v[80:83]
	v_mfma_f32_16x16x32_bf16 v[72:75], v[170:173], v[214:217], v[72:75]
	v_mfma_f32_16x16x32_bf16 v[64:67], v[178:181], v[214:217], v[64:67]
	s_barrier
; #define PG8_STAGE(bufoff, gbase, voff) do { _Pragma("unroll") for (int _i = 0; _i < 2; ++_i) \
;         __builtin_amdgcn_global_load_lds((const unsigned*)((const char*)(gbase) + (voff)[_i]), (LAS unsigned*)(lds + (bufoff) + ldsw + _i * 8192), 16, 0, 0); } while (0)
; #define PG8_LDA(dst, b, h) do { _Pragma("unroll") for (int m = 0; m < 4; ++m) _Pragma("unroll") for (int k = 0; k < 2; ++k) dst[m][k] = *(const LAS bf16x8*)(lds + PG8_SA(b, h) + aoff + m * 2048 + k * 1024); } while (0)
; #define PG8_MMA(ai, bj, At, Bt) do { __builtin_amdgcn_s_setprio(1); _Pragma("unroll") for (int m = 0; m < 4; ++m) _Pragma("unroll") for (int n = 0; n < 2; ++n) _Pragma("unroll") for (int k = 0; k < 2; ++k) \
;         acc[ai][bj][m][n] = __builtin_amdgcn_mfma_f32_16x16x32_bf16(Bt[n][k], At[m][k], acc[ai][bj][m][n], 0, 0, 0); __builtin_amdgcn_s_setprio(0); } while (0)
; #define PG8_WAIT_V(n) asm volatile("s_waitcnt vmcnt(" #n ")" ::: "memory")
; #define PG8_WAIT_L(n) asm volatile("s_waitcnt lgkmcnt(" #n ")" ::: "memory")
; #define PG8_BAR __builtin_amdgcn_s_barrier()
; #define PG8_SCHED __builtin_amdgcn_sched_barrier(0)
; template <class Epi, class Sched = StaticOrder, class EpiSub = NoSub, bool FAST = false>
; __device__ __forceinline__ void gemm_phase(LAS unsigned char* lds, const Gemm g, const Sched& S, const Epi& E, const EpiSub& ES = EpiSub()) {
;     ...
;         for (int t = 0; t < nt; t += 2) {
;     ...
;             PG8_LDA(At, 1, 1); PG8_STAGE(PG8_SB(1, 0), b3, voffB); PG8_STAGE(PG8_SB(1, 1), b3 + hstepB, voffB); PG8_STAGE(PG8_SA(1, 0), a3, voffA);
;             PG8_WAIT_V(8); PG8_WAIT_L(0); PG8_BAR; PG8_MMA(1, 0, At, B0); PG8_MMA(1, 1, At, B1); PG8_BAR; PG8_SCHED;
	s_setprio 0
	s_add_i32 s26, s50, s28
	v_lshl_add_u64 v[190:191], v[190:191], 0, s[8:9]
	s_mov_b32 m0, s26
	ds_read_b128 v[182:185], v149 offset:49152
	ds_read_b128 v[186:189], v149 offset:50176
	ds_read_b128 v[194:197], v149 offset:51200
	ds_read_b128 v[198:201], v149 offset:52224
	ds_read_b128 v[202:205], v149 offset:53248
	ds_read_b128 v[206:209], v149 offset:54272
	ds_read_b128 v[210:213], v149 offset:55296
	ds_read_b128 v[214:217], v149 offset:56320
	global_load_lds_dwordx4 v[190:191], off
	s_add_i32 m0, s26, 0x2000
	s_add_u32 s24, s24, 0x80080
	v_lshl_add_u64 v[190:191], v[218:219], 0, s[8:9]
	s_addc_u32 s25, s25, 0
	s_add_i32 s26, s51, s28
	global_load_lds_dwordx4 v[190:191], off
	v_lshl_add_u64 v[190:191], s[24:25], 0, v[130:131]
	s_mov_b32 m0, s26
	s_nop 0
	global_load_lds_dwordx4 v[190:191], off
	v_lshl_add_u64 v[190:191], s[24:25], 0, v[134:135]
	s_add_i32 m0, s26, 0x2000
	s_nop 0
	global_load_lds_dwordx4 v[190:191], off
	v_lshl_add_u64 v[190:191], v[220:221], 0, s[8:9]
	s_mov_b32 m0, s40
	s_nop 0
	global_load_lds_dwordx4 v[190:191], off
	v_lshl_add_u64 v[190:191], v[222:223], 0, s[8:9]
	s_mov_b32 m0, s41
	s_nop 0
	global_load_lds_dwordx4 v[190:191], off
	s_waitcnt vmcnt(8)
	s_waitcnt lgkmcnt(0)
	s_setprio 1
	s_barrier
	v_mfma_f32_16x16x32_bf16 v[60:63], v[150:153], v[182:185], v[60:63]
	v_mfma_f32_16x16x32_bf16 v[52:55], v[158:161], v[182:185], v[52:55]
	v_mfma_f32_16x16x32_bf16 v[44:47], v[150:153], v[194:197], v[44:47]
	v_mfma_f32_16x16x32_bf16 v[36:39], v[158:161], v[194:197], v[36:39]
	v_mfma_f32_16x16x32_bf16 v[28:31], v[150:153], v[202:205], v[28:31]
	v_mfma_f32_16x16x32_bf16 v[20:23], v[158:161], v[202:205], v[20:23]
	v_mfma_f32_16x16x32_bf16 v[12:15], v[150:153], v[210:213], v[12:15]
	v_mfma_f32_16x16x32_bf16 v[4:7], v[158:161], v[210:213], v[4:7]
	v_mfma_f32_16x16x32_bf16 v[60:63], v[154:157], v[186:189], v[60:63]
	v_mfma_f32_16x16x32_bf16 v[52:55], v[162:165], v[186:189], v[52:55]
	v_mfma_f32_16x16x32_bf16 v[44:47], v[154:157], v[198:201], v[44:47]
	v_mfma_f32_16x16x32_bf16 v[36:39], v[162:165], v[198:201], v[36:39]
	v_mfma_f32_16x16x32_bf16 v[28:31], v[154:157], v[206:209], v[28:31]
	v_mfma_f32_16x16x32_bf16 v[20:23], v[162:165], v[206:209], v[20:23]
	v_mfma_f32_16x16x32_bf16 v[12:15], v[154:157], v[214:217], v[12:15]
	v_mfma_f32_16x16x32_bf16 v[4:7], v[162:165], v[214:217], v[4:7]
	v_mfma_f32_16x16x32_bf16 v[56:59], v[166:169], v[182:185], v[56:59]
	v_mfma_f32_16x16x32_bf16 v[48:51], v[174:177], v[182:185], v[48:51]
	v_mfma_f32_16x16x32_bf16 v[40:43], v[166:169], v[194:197], v[40:43]
	v_mfma_f32_16x16x32_bf16 v[32:35], v[174:177], v[194:197], v[32:35]
	v_mfma_f32_16x16x32_bf16 v[24:27], v[166:169], v[202:205], v[24:27]
	v_mfma_f32_16x16x32_bf16 v[16:19], v[174:177], v[202:205], v[16:19]
	v_mfma_f32_16x16x32_bf16 v[8:11], v[166:169], v[210:213], v[8:11]
	v_mfma_f32_16x16x32_bf16 v[0:3], v[174:177], v[210:213], v[0:3]
	v_mfma_f32_16x16x32_bf16 v[56:59], v[170:173], v[186:189], v[56:59]
	v_mfma_f32_16x16x32_bf16 v[48:51], v[178:181], v[186:189], v[48:51]
	v_mfma_f32_16x16x32_bf16 v[40:43], v[170:173], v[198:201], v[40:43]
	v_mfma_f32_16x16x32_bf16 v[32:35], v[178:181], v[198:201], v[32:35]
	v_mfma_f32_16x16x32_bf16 v[24:27], v[170:173], v[206:209], v[24:27]
	v_mfma_f32_16x16x32_bf16 v[16:19], v[178:181], v[206:209], v[16:19]
	v_mfma_f32_16x16x32_bf16 v[8:11], v[170:173], v[214:217], v[8:11]
	v_mfma_f32_16x16x32_bf16 v[0:3], v[178:181], v[214:217], v[0:3]
	s_barrier
	s_setprio 0
	s_add_i32 s49, s49, 2
	s_add_u32 s22, s22, 0x100
	s_addc_u32 s23, s23, 0
	s_add_u32 s47, s47, 0x100
	s_addc_u32 s48, s48, 0
	s_cmp_gt_u32 s49, 29
	s_cbranch_scc0 .LBB0_985

; #define PG8_STAGE(bufoff, gbase, voff) do { _Pragma("unroll") for (int _i = 0; _i < 2; ++_i) \
;         __builtin_amdgcn_global_load_lds((const unsigned*)((const char*)(gbase) + (voff)[_i]), (LAS unsigned*)(lds + (bufoff) + ldsw + _i * 8192), 16, 0, 0); } while (0)
; #define PG8_LDA(dst, b, h) do { _Pragma("unroll") for (int m = 0; m < 4; ++m) _Pragma("unroll") for (int k = 0; k < 2; ++k) dst[m][k] = *(const LAS bf16x8*)(lds + PG8_SA(b, h) + aoff + m * 2048 + k * 1024); } while (0)
; #define PG8_LDB(dst, b, h) do { _Pragma("unroll") for (int n = 0; n < 2; ++n) _Pragma("unroll") for (int k = 0; k < 2; ++k) dst[n][k] = *(const LAS bf16x8*)(lds + PG8_SB(b, h) + boff + n * 2048 + k * 1024); } while (0)
; #define PG8_WAIT_V(n) asm volatile("s_waitcnt vmcnt(" #n ")" ::: "memory")
; #define PG8_BAR __builtin_amdgcn_s_barrier()
; template <class Epi, class Sched = StaticOrder, class EpiSub = NoSub, bool FAST = false>
; __device__ __forceinline__ void gemm_phase(LAS unsigned char* lds, const Gemm g, const Sched& S, const Epi& E, const EpiSub& ES = EpiSub()) {
;     ...
;         const bool has_next = S.next(ui + 1, nxt);
;         const size_t nko = (has_next && nxt.kb >= 0) ? nxt.kb * ksubB : 0;
;         const char* nA = has_next ? (const char*)g.A + (size_t)nxt.pm * tstepA + (size_t)nxt.pn * g.acs + nko : cA; const char* nB = has_next ? (const char*)g.Bt + (size_t)nxt.pn * tstepB + nko : cB;
;         const int nt = cur.kb < 0 ? ntMain : ntSub;
;         for (int t = 0; t < nt; t += 2) {
;             const bool last = (t == nt - 2);
;             const char* a1 = cA + (size_t)(t + 1) * kstep;
;             const char* a2 = last ? nA : cA + (size_t)(t + 2) * kstep; const char* b2 = last ? nB : cB + (size_t)(t + 2) * kstep;
;             const char* a3 = a2 + kstep; const char* b3 = b2 + kstep;
;             if constexpr (FAST && PG8_SP2) {
;             PG8_LDB(B0, 0, 0); PG8_LDB(B1, 0, 1); PG8_SCHED; PG8_LDA(At, 0, 0); PG8_STAGE(PG8_SA(1, 1), a1 + hstepA, voffA);
;             PG8_WAIT_V(8); PG8_WAIT_L(0); PG8_BAR; PG8_MMA(0, 0, At, B0); PG8_MMA(0, 1, At, B1); PG8_BAR; PG8_SCHED;
;             PG8_LDA(At, 0, 1); PG8_STAGE(PG8_SB(0, 0), b2, voffB); PG8_STAGE(PG8_SB(0, 1), b2 + hstepB, voffB); PG8_STAGE(PG8_SA(0, 0), a2, voffA);
;             PG8_WAIT_V(8); PG8_WAIT_L(0); PG8_BAR; PG8_MMA(1, 0, At, B0); PG8_MMA(1, 1, At, B1); PG8_BAR; PG8_SCHED;
.LBB0_1078:
	s_cmp_gt_i32 s8, -1
	s_cselect_b64 s[4:5], -1, 0
	s_cmp_lt_i32 s8, 0
	s_cselect_b32 s70, 0x58, 22
	s_add_i32 s71, s70, -2
	s_add_u32 s42, s42, 0x160080
	s_addc_u32 s43, s43, 0
	s_add_u32 s83, s44, 0x100
	s_mov_b32 s46, 0
	s_addc_u32 s84, s45, 0
	ds_read_b128 v[96:99], v201
	ds_read_b128 v[100:103], v201 offset:1024
	ds_read_b128 v[108:111], v201 offset:2048
	ds_read_b128 v[116:119], v201 offset:3072
	ds_read_b128 v[144:147], v202
	ds_read_b128 v[148:151], v202 offset:1024
	ds_read_b128 v[152:155], v202 offset:2048
	ds_read_b128 v[156:159], v202 offset:3072
	s_add_i32 s85, s46, 2
	s_add_u32 s44, s42, 0xffea0080
	s_addc_u32 s45, s43, -1
	s_cmp_eq_u32 s71, s46
	s_cselect_b32 s46, s38, s44
	s_cselect_b32 s47, s39, s45
	s_cselect_b32 s45, s41, s84
	s_cselect_b32 s44, s40, s83
	v_lshl_add_u64 v[190:191], s[42:43], 0, v[176:177]
	s_add_i32 m0, s48, 0xc000
	ds_read_b128 v[160:163], v203
	ds_read_b128 v[164:167], v203 offset:1024
	ds_read_b128 v[182:185], v203 offset:2048
	ds_read_b128 v[186:189], v203 offset:3072
	ds_read_b128 v[194:197], v203 offset:4096
	ds_read_b128 v[204:207], v203 offset:5120
	ds_read_b128 v[208:211], v203 offset:6144
	ds_read_b128 v[212:215], v203 offset:7168
	global_load_lds_dwordx4 v[190:191], off
	v_lshl_add_u64 v[190:191], s[42:43], 0, v[178:179]
	s_add_i32 m0, s48, 0xe000
	s_nop 0
	global_load_lds_dwordx4 v[190:191], off
	s_waitcnt vmcnt(8)
	s_waitcnt lgkmcnt(0)
	s_setprio 1
	s_barrier
	v_mfma_f32_16x16x32_bf16 v[140:143], v[96:99], v[160:163], 0
	v_mfma_f32_16x16x32_bf16 v[136:139], v[108:111], v[160:163], 0
	v_mfma_f32_16x16x32_bf16 v[124:127], v[96:99], v[182:185], 0
	v_mfma_f32_16x16x32_bf16 v[120:123], v[108:111], v[182:185], 0
	v_mfma_f32_16x16x32_bf16 v[92:95], v[96:99], v[194:197], 0
	v_mfma_f32_16x16x32_bf16 v[88:91], v[108:111], v[194:197], 0
	v_mfma_f32_16x16x32_bf16 v[76:79], v[96:99], v[208:211], 0
	v_mfma_f32_16x16x32_bf16 v[72:75], v[108:111], v[208:211], 0
	v_mfma_f32_16x16x32_bf16 v[140:143], v[100:103], v[164:167], v[140:143]
	v_mfma_f32_16x16x32_bf16 v[136:139], v[116:119], v[164:167], v[136:139]
	v_mfma_f32_16x16x32_bf16 v[124:127], v[100:103], v[186:189], v[124:127]
	v_mfma_f32_16x16x32_bf16 v[120:123], v[116:119], v[186:189], v[120:123]
	v_mfma_f32_16x16x32_bf16 v[92:95], v[100:103], v[204:207], v[92:95]
	v_mfma_f32_16x16x32_bf16 v[88:91], v[116:119], v[204:207], v[88:91]
	v_mfma_f32_16x16x32_bf16 v[76:79], v[100:103], v[212:215], v[76:79]
	v_mfma_f32_16x16x32_bf16 v[72:75], v[116:119], v[212:215], v[72:75]
	v_mfma_f32_16x16x32_bf16 v[132:135], v[144:147], v[160:163], 0
	v_mfma_f32_16x16x32_bf16 v[128:131], v[152:155], v[160:163], 0
	v_mfma_f32_16x16x32_bf16 v[112:115], v[144:147], v[182:185], 0
	v_mfma_f32_16x16x32_bf16 v[104:107], v[152:155], v[182:185], 0
	v_mfma_f32_16x16x32_bf16 v[84:87], v[144:147], v[194:197], 0
	v_mfma_f32_16x16x32_bf16 v[80:83], v[152:155], v[194:197], 0
	v_mfma_f32_16x16x32_bf16 v[68:71], v[144:147], v[208:211], 0
	v_mfma_f32_16x16x32_bf16 v[64:67], v[152:155], v[208:211], 0
	v_mfma_f32_16x16x32_bf16 v[132:135], v[148:151], v[164:167], v[132:135]
	v_mfma_f32_16x16x32_bf16 v[128:131], v[156:159], v[164:167], v[128:131]
	v_mfma_f32_16x16x32_bf16 v[112:115], v[148:151], v[186:189], v[112:115]
	v_mfma_f32_16x16x32_bf16 v[104:107], v[156:159], v[186:189], v[104:107]
	v_mfma_f32_16x16x32_bf16 v[84:87], v[148:151], v[204:207], v[84:87]
	v_mfma_f32_16x16x32_bf16 v[80:83], v[156:159], v[204:207], v[80:83]
	v_mfma_f32_16x16x32_bf16 v[68:71], v[148:151], v[212:215], v[68:71]
	v_mfma_f32_16x16x32_bf16 v[64:67], v[156:159], v[212:215], v[64:67]
	s_barrier
	s_setprio 0
	s_add_i32 s86, s58, s27
	v_lshl_add_u64 v[190:191], s[44:45], 0, v[170:171]
	s_mov_b32 m0, s86
	ds_read_b128 v[160:163], v203 offset:16384
	ds_read_b128 v[164:167], v203 offset:17408
	ds_read_b128 v[182:185], v203 offset:18432
	ds_read_b128 v[186:189], v203 offset:19456
	ds_read_b128 v[194:197], v203 offset:20480
	ds_read_b128 v[204:207], v203 offset:21504
	ds_read_b128 v[208:211], v203 offset:22528
	ds_read_b128 v[212:215], v203 offset:23552
	global_load_lds_dwordx4 v[190:191], off
	s_add_i32 m0, s86, 0x2000
	s_add_u32 s86, s44, 0x160000
	v_lshl_add_u64 v[216:217], s[44:45], 0, v[174:175]
	s_addc_u32 s87, s45, 0
	s_add_i32 s88, s59, s27
	global_load_lds_dwordx4 v[216:217], off
	v_lshl_add_u64 v[218:219], s[86:87], 0, v[170:171]
	s_mov_b32 m0, s88
	v_lshl_add_u64 v[220:221], s[46:47], 0, v[172:173]
	global_load_lds_dwordx4 v[218:219], off
	v_lshl_add_u64 v[218:219], s[86:87], 0, v[174:175]
	s_add_i32 m0, s88, 0x2000
	s_nop 0
	global_load_lds_dwordx4 v[218:219], off
	v_lshl_add_u64 v[218:219], s[46:47], 0, v[168:169]
	s_mov_b32 m0, s48
	s_nop 0
	global_load_lds_dwordx4 v[218:219], off
	s_mov_b32 m0, s49
	s_nop 0
	global_load_lds_dwordx4 v[220:221], off
	s_waitcnt vmcnt(8)
	s_waitcnt lgkmcnt(0)
	s_setprio 1
	s_barrier
; #define PG8_STAGE(bufoff, gbase, voff) do { _Pragma("unroll") for (int _i = 0; _i < 2; ++_i) \
;         __builtin_amdgcn_global_load_lds((const unsigned*)((const char*)(gbase) + (voff)[_i]), (LAS unsigned*)(lds + (bufoff) + ldsw + _i * 8192), 16, 0, 0); } while (0)
; #define PG8_LDA(dst, b, h) do { _Pragma("unroll") for (int m = 0; m < 4; ++m) _Pragma("unroll") for (int k = 0; k < 2; ++k) dst[m][k] = *(const LAS bf16x8*)(lds + PG8_SA(b, h) + aoff + m * 2048 + k * 1024); } while (0)
; #define PG8_LDB(dst, b, h) do { _Pragma("unroll") for (int n = 0; n < 2; ++n) _Pragma("unroll") for (int k = 0; k < 2; ++k) dst[n][k] = *(const LAS bf16x8*)(lds + PG8_SB(b, h) + boff + n * 2048 + k * 1024); } while (0)
; #define PG8_MMA(ai, bj, At, Bt) do { __builtin_amdgcn_s_setprio(1); _Pragma("unroll") for (int m = 0; m < 4; ++m) _Pragma("unroll") for (int n = 0; n < 2; ++n) _Pragma("unroll") for (int k = 0; k < 2; ++k) \
;         acc[ai][bj][m][n] = __builtin_amdgcn_mfma_f32_16x16x32_bf16(Bt[n][k], At[m][k], acc[ai][bj][m][n], 0, 0, 0); __builtin_amdgcn_s_setprio(0); } while (0)
; #define PG8_WAIT_V(n) asm volatile("s_waitcnt vmcnt(" #n ")" ::: "memory")
; #define PG8_WAIT_L(n) asm volatile("s_waitcnt lgkmcnt(" #n ")" ::: "memory")
; #define PG8_BAR __builtin_amdgcn_s_barrier()
; #define PG8_SCHED __builtin_amdgcn_sched_barrier(0)
; template <class Epi, class Sched = StaticOrder, class EpiSub = NoSub, bool FAST = false>
; __device__ __forceinline__ void gemm_phase(LAS unsigned char* lds, const Gemm g, const Sched& S, const Epi& E, const EpiSub& ES = EpiSub()) {
;     ...
;             PG8_WAIT_V(8); PG8_WAIT_L(0); PG8_BAR; PG8_MMA(1, 0, At, B0); PG8_MMA(1, 1, At, B1); PG8_BAR; PG8_SCHED;
;             PG8_LDB(B0, 1, 0); PG8_LDB(B1, 1, 1); PG8_SCHED; PG8_LDA(At, 1, 0); PG8_STAGE(PG8_SA(0, 1), a2 + hstepA, voffA);
;             PG8_WAIT_V(8); PG8_WAIT_L(0); PG8_BAR; PG8_MMA(0, 0, At, B0); PG8_MMA(0, 1, At, B1); PG8_BAR; PG8_SCHED;
	v_mfma_f32_16x16x32_bf16 v[60:63], v[96:99], v[160:163], 0
	v_mfma_f32_16x16x32_bf16 v[56:59], v[108:111], v[160:163], 0
	v_mfma_f32_16x16x32_bf16 v[44:47], v[96:99], v[182:185], 0
	v_mfma_f32_16x16x32_bf16 v[40:43], v[108:111], v[182:185], 0
	v_mfma_f32_16x16x32_bf16 v[28:31], v[96:99], v[194:197], 0
	v_mfma_f32_16x16x32_bf16 v[24:27], v[108:111], v[194:197], 0
	v_mfma_f32_16x16x32_bf16 v[12:15], v[96:99], v[208:211], 0
	v_mfma_f32_16x16x32_bf16 v[8:11], v[108:111], v[208:211], 0
	v_mfma_f32_16x16x32_bf16 v[60:63], v[100:103], v[164:167], v[60:63]
	v_mfma_f32_16x16x32_bf16 v[56:59], v[116:119], v[164:167], v[56:59]
	v_mfma_f32_16x16x32_bf16 v[44:47], v[100:103], v[186:189], v[44:47]
	v_mfma_f32_16x16x32_bf16 v[40:43], v[116:119], v[186:189], v[40:43]
	v_mfma_f32_16x16x32_bf16 v[28:31], v[100:103], v[204:207], v[28:31]
	v_mfma_f32_16x16x32_bf16 v[24:27], v[116:119], v[204:207], v[24:27]
	v_mfma_f32_16x16x32_bf16 v[12:15], v[100:103], v[212:215], v[12:15]
	v_mfma_f32_16x16x32_bf16 v[8:11], v[116:119], v[212:215], v[8:11]
	v_mfma_f32_16x16x32_bf16 v[52:55], v[144:147], v[160:163], 0
	v_mfma_f32_16x16x32_bf16 v[48:51], v[152:155], v[160:163], 0
	v_mfma_f32_16x16x32_bf16 v[36:39], v[144:147], v[182:185], 0
	v_mfma_f32_16x16x32_bf16 v[32:35], v[152:155], v[182:185], 0
	v_mfma_f32_16x16x32_bf16 v[20:23], v[144:147], v[194:197], 0
	v_mfma_f32_16x16x32_bf16 v[16:19], v[152:155], v[194:197], 0
	v_mfma_f32_16x16x32_bf16 v[4:7], v[144:147], v[208:211], 0
	v_mfma_f32_16x16x32_bf16 v[0:3], v[152:155], v[208:211], 0
	v_mfma_f32_16x16x32_bf16 v[52:55], v[148:151], v[164:167], v[52:55]
	v_mfma_f32_16x16x32_bf16 v[48:51], v[156:159], v[164:167], v[48:51]
	v_mfma_f32_16x16x32_bf16 v[36:39], v[148:151], v[186:189], v[36:39]
	v_mfma_f32_16x16x32_bf16 v[32:35], v[156:159], v[186:189], v[32:35]
	v_mfma_f32_16x16x32_bf16 v[20:23], v[148:151], v[204:207], v[20:23]
	v_mfma_f32_16x16x32_bf16 v[16:19], v[156:159], v[204:207], v[16:19]
	v_mfma_f32_16x16x32_bf16 v[4:7], v[148:151], v[212:215], v[4:7]
	v_mfma_f32_16x16x32_bf16 v[0:3], v[156:159], v[212:215], v[0:3]
	s_barrier
	s_setprio 0
	s_add_i32 s86, 0, 0x18000
	s_add_i32 s87, 0, 0x1c000
	v_add_u32_e32 v116, s86, v198
	v_add_u32_e32 v156, s87, v198
	ds_read_b128 v[96:99], v116
	ds_read_b128 v[100:103], v116 offset:1024
	ds_read_b128 v[108:111], v116 offset:2048
	ds_read_b128 v[116:119], v116 offset:3072
	ds_read_b128 v[144:147], v156
	ds_read_b128 v[148:151], v156 offset:1024
	ds_read_b128 v[152:155], v156 offset:2048
	ds_read_b128 v[156:159], v156 offset:3072
	s_add_u32 s46, s46, 0x160000
	s_addc_u32 s47, s47, 0
	s_mov_b32 m0, s50
	v_lshl_add_u64 v[222:223], s[46:47], 0, v[168:169]
	ds_read_b128 v[160:163], v203 offset:32768
	ds_read_b128 v[164:167], v203 offset:33792
	ds_read_b128 v[182:185], v203 offset:34816
	ds_read_b128 v[186:189], v203 offset:35840
	ds_read_b128 v[194:197], v203 offset:36864
	ds_read_b128 v[204:207], v203 offset:37888
	ds_read_b128 v[208:211], v203 offset:38912
	ds_read_b128 v[212:215], v203 offset:39936
	global_load_lds_dwordx4 v[222:223], off
	v_lshl_add_u64 v[222:223], s[46:47], 0, v[172:173]
	s_mov_b32 m0, s51
	s_nop 0
	global_load_lds_dwordx4 v[222:223], off
	s_waitcnt vmcnt(8)
	s_waitcnt lgkmcnt(0)
	s_setprio 1
	s_barrier
	v_mfma_f32_16x16x32_bf16 v[140:143], v[96:99], v[160:163], v[140:143]
	v_mfma_f32_16x16x32_bf16 v[136:139], v[108:111], v[160:163], v[136:139]
	v_mfma_f32_16x16x32_bf16 v[124:127], v[96:99], v[182:185], v[124:127]
	v_mfma_f32_16x16x32_bf16 v[120:123], v[108:111], v[182:185], v[120:123]
	v_mfma_f32_16x16x32_bf16 v[92:95], v[96:99], v[194:197], v[92:95]
	v_mfma_f32_16x16x32_bf16 v[88:91], v[108:111], v[194:197], v[88:91]
	v_mfma_f32_16x16x32_bf16 v[76:79], v[96:99], v[208:211], v[76:79]
	v_mfma_f32_16x16x32_bf16 v[72:75], v[108:111], v[208:211], v[72:75]
	v_mfma_f32_16x16x32_bf16 v[140:143], v[100:103], v[164:167], v[140:143]
	v_mfma_f32_16x16x32_bf16 v[136:139], v[116:119], v[164:167], v[136:139]
	v_mfma_f32_16x16x32_bf16 v[124:127], v[100:103], v[186:189], v[124:127]
	v_mfma_f32_16x16x32_bf16 v[120:123], v[116:119], v[186:189], v[120:123]
	v_mfma_f32_16x16x32_bf16 v[92:95], v[100:103], v[204:207], v[92:95]
	v_mfma_f32_16x16x32_bf16 v[88:91], v[116:119], v[204:207], v[88:91]
	v_mfma_f32_16x16x32_bf16 v[76:79], v[100:103], v[212:215], v[76:79]
	v_mfma_f32_16x16x32_bf16 v[72:75], v[116:119], v[212:215], v[72:75]
	v_mfma_f32_16x16x32_bf16 v[132:135], v[144:147], v[160:163], v[132:135]
	v_mfma_f32_16x16x32_bf16 v[128:131], v[152:155], v[160:163], v[128:131]
	v_mfma_f32_16x16x32_bf16 v[112:115], v[144:147], v[182:185], v[112:115]
	v_mfma_f32_16x16x32_bf16 v[104:107], v[152:155], v[182:185], v[104:107]
	v_mfma_f32_16x16x32_bf16 v[84:87], v[144:147], v[194:197], v[84:87]
	v_mfma_f32_16x16x32_bf16 v[80:83], v[152:155], v[194:197], v[80:83]
	v_mfma_f32_16x16x32_bf16 v[68:71], v[144:147], v[208:211], v[68:71]
	v_mfma_f32_16x16x32_bf16 v[64:67], v[152:155], v[208:211], v[64:67]
	v_mfma_f32_16x16x32_bf16 v[132:135], v[148:151], v[164:167], v[132:135]
	v_mfma_f32_16x16x32_bf16 v[128:131], v[156:159], v[164:167], v[128:131]
	v_mfma_f32_16x16x32_bf16 v[112:115], v[148:151], v[186:189], v[112:115]
	v_mfma_f32_16x16x32_bf16 v[104:107], v[156:159], v[186:189], v[104:107]
	v_mfma_f32_16x16x32_bf16 v[84:87], v[148:151], v[204:207], v[84:87]
	v_mfma_f32_16x16x32_bf16 v[80:83], v[156:159], v[204:207], v[80:83]
	v_mfma_f32_16x16x32_bf16 v[68:71], v[148:151], v[212:215], v[68:71]
	v_mfma_f32_16x16x32_bf16 v[64:67], v[156:159], v[212:215], v[64:67]
	s_barrier
; #define PG8_STAGE(bufoff, gbase, voff) do { _Pragma("unroll") for (int _i = 0; _i < 2; ++_i) \
;         __builtin_amdgcn_global_load_lds((const unsigned*)((const char*)(gbase) + (voff)[_i]), (LAS unsigned*)(lds + (bufoff) + ldsw + _i * 8192), 16, 0, 0); } while (0)
; #define PG8_LDA(dst, b, h) do { _Pragma("unroll") for (int m = 0; m < 4; ++m) _Pragma("unroll") for (int k = 0; k < 2; ++k) dst[m][k] = *(const LAS bf16x8*)(lds + PG8_SA(b, h) + aoff + m * 2048 + k * 1024); } while (0)
; #define PG8_LDB(dst, b, h) do { _Pragma("unroll") for (int n = 0; n < 2; ++n) _Pragma("unroll") for (int k = 0; k < 2; ++k) dst[n][k] = *(const LAS bf16x8*)(lds + PG8_SB(b, h) + boff + n * 2048 + k * 1024); } while (0)
; template <class Epi, class Sched = StaticOrder, class EpiSub = NoSub, bool FAST = false>
; __device__ __forceinline__ void gemm_phase(LAS unsigned char* lds, const Gemm g, const Sched& S, const Epi& E, const EpiSub& ES = EpiSub()) {
;     ...
;         for (int t = 0; t < nt; t += 2) {
;             const bool last = (t == nt - 2);
;             const char* a1 = cA + (size_t)(t + 1) * kstep;
;             const char* a2 = last ? nA : cA + (size_t)(t + 2) * kstep; const char* b2 = last ? nB : cB + (size_t)(t + 2) * kstep;
;             const char* a3 = a2 + kstep; const char* b3 = b2 + kstep;
;             if constexpr (FAST && PG8_SP2) {
;             PG8_LDB(B0, 0, 0); PG8_LDB(B1, 0, 1); PG8_SCHED; PG8_LDA(At, 0, 0); PG8_STAGE(PG8_SA(1, 1), a1 + hstepA, voffA);
;             PG8_WAIT_V(8); PG8_WAIT_L(0); PG8_BAR; PG8_MMA(0, 0, At, B0); PG8_MMA(0, 1, At, B1); PG8_BAR; PG8_SCHED;
;             PG8_LDA(At, 0, 1); PG8_STAGE(PG8_SB(0, 0), b2, voffB); PG8_STAGE(PG8_SB(0, 1), b2 + hstepB, voffB); PG8_STAGE(PG8_SA(0, 0), a2, voffA);
;             PG8_WAIT_V(8); PG8_WAIT_L(0); PG8_BAR; PG8_MMA(1, 0, At, B0); PG8_MMA(1, 1, At, B1); PG8_BAR; PG8_SCHED;
;             PG8_LDB(B0, 1, 0); PG8_LDB(B1, 1, 1); PG8_SCHED; PG8_LDA(At, 1, 0); PG8_STAGE(PG8_SA(0, 1), a2 + hstepA, voffA);
;             PG8_WAIT_V(8); PG8_WAIT_L(0); PG8_BAR; PG8_MMA(0, 0, At, B0); PG8_MMA(0, 1, At, B1); PG8_BAR; PG8_SCHED;
;             PG8_LDA(At, 1, 1); PG8_STAGE(PG8_SB(1, 0), b3, voffB); PG8_STAGE(PG8_SB(1, 1), b3 + hstepB, voffB); PG8_STAGE(PG8_SA(1, 0), a3, voffA);
;             PG8_WAIT_V(8); PG8_WAIT_L(0); PG8_BAR; PG8_MMA(1, 0, At, B0); PG8_MMA(1, 1, At, B1); PG8_BAR; PG8_SCHED;
	s_setprio 0
	s_add_i32 s46, s86, s27
	v_lshl_add_u64 v[190:191], v[190:191], 0, s[16:17]
	s_mov_b32 m0, s46
	ds_read_b128 v[160:163], v203 offset:49152
	ds_read_b128 v[164:167], v203 offset:50176
	ds_read_b128 v[182:185], v203 offset:51200
	ds_read_b128 v[186:189], v203 offset:52224
	ds_read_b128 v[194:197], v203 offset:53248
	ds_read_b128 v[204:207], v203 offset:54272
	ds_read_b128 v[208:211], v203 offset:55296
	ds_read_b128 v[212:215], v203 offset:56320
	global_load_lds_dwordx4 v[190:191], off
	s_add_i32 m0, s46, 0x2000
	s_add_u32 s44, s44, 0x160080
	v_lshl_add_u64 v[190:191], v[216:217], 0, s[16:17]
	s_addc_u32 s45, s45, 0
	s_add_i32 s46, s87, s27
	global_load_lds_dwordx4 v[190:191], off
	v_lshl_add_u64 v[190:191], s[44:45], 0, v[170:171]
	s_mov_b32 m0, s46
	s_nop 0
	global_load_lds_dwordx4 v[190:191], off
	v_lshl_add_u64 v[190:191], s[44:45], 0, v[174:175]
	s_add_i32 m0, s46, 0x2000
	s_nop 0
	global_load_lds_dwordx4 v[190:191], off
	v_lshl_add_u64 v[190:191], v[218:219], 0, s[16:17]
	s_mov_b32 m0, s53
	s_nop 0
	global_load_lds_dwordx4 v[190:191], off
	v_lshl_add_u64 v[190:191], v[220:221], 0, s[16:17]
	s_mov_b32 m0, s54
	s_nop 0
	global_load_lds_dwordx4 v[190:191], off
	s_waitcnt vmcnt(8)
	s_waitcnt lgkmcnt(0)
	s_setprio 1
	s_barrier
	v_mfma_f32_16x16x32_bf16 v[60:63], v[96:99], v[160:163], v[60:63]
	v_mfma_f32_16x16x32_bf16 v[56:59], v[108:111], v[160:163], v[56:59]
	v_mfma_f32_16x16x32_bf16 v[44:47], v[96:99], v[182:185], v[44:47]
	v_mfma_f32_16x16x32_bf16 v[40:43], v[108:111], v[182:185], v[40:43]
	v_mfma_f32_16x16x32_bf16 v[28:31], v[96:99], v[194:197], v[28:31]
	v_mfma_f32_16x16x32_bf16 v[24:27], v[108:111], v[194:197], v[24:27]
	v_mfma_f32_16x16x32_bf16 v[12:15], v[96:99], v[208:211], v[12:15]
	v_mfma_f32_16x16x32_bf16 v[8:11], v[108:111], v[208:211], v[8:11]
	v_mfma_f32_16x16x32_bf16 v[60:63], v[100:103], v[164:167], v[60:63]
	v_mfma_f32_16x16x32_bf16 v[56:59], v[116:119], v[164:167], v[56:59]
	v_mfma_f32_16x16x32_bf16 v[44:47], v[100:103], v[186:189], v[44:47]
	v_mfma_f32_16x16x32_bf16 v[40:43], v[116:119], v[186:189], v[40:43]
	v_mfma_f32_16x16x32_bf16 v[28:31], v[100:103], v[204:207], v[28:31]
	v_mfma_f32_16x16x32_bf16 v[24:27], v[116:119], v[204:207], v[24:27]
	v_mfma_f32_16x16x32_bf16 v[12:15], v[100:103], v[212:215], v[12:15]
	v_mfma_f32_16x16x32_bf16 v[8:11], v[116:119], v[212:215], v[8:11]
	v_mfma_f32_16x16x32_bf16 v[52:55], v[144:147], v[160:163], v[52:55]
	v_mfma_f32_16x16x32_bf16 v[48:51], v[152:155], v[160:163], v[48:51]
	v_mfma_f32_16x16x32_bf16 v[36:39], v[144:147], v[182:185], v[36:39]
	v_mfma_f32_16x16x32_bf16 v[32:35], v[152:155], v[182:185], v[32:35]
	v_mfma_f32_16x16x32_bf16 v[20:23], v[144:147], v[194:197], v[20:23]
	v_mfma_f32_16x16x32_bf16 v[16:19], v[152:155], v[194:197], v[16:19]
	v_mfma_f32_16x16x32_bf16 v[4:7], v[144:147], v[208:211], v[4:7]
	v_mfma_f32_16x16x32_bf16 v[0:3], v[152:155], v[208:211], v[0:3]
	v_mfma_f32_16x16x32_bf16 v[52:55], v[148:151], v[164:167], v[52:55]
	v_mfma_f32_16x16x32_bf16 v[48:51], v[156:159], v[164:167], v[48:51]
	v_mfma_f32_16x16x32_bf16 v[36:39], v[148:151], v[186:189], v[36:39]
	v_mfma_f32_16x16x32_bf16 v[32:35], v[156:159], v[186:189], v[32:35]
	v_mfma_f32_16x16x32_bf16 v[20:23], v[148:151], v[204:207], v[20:23]
	v_mfma_f32_16x16x32_bf16 v[16:19], v[156:159], v[204:207], v[16:19]
	v_mfma_f32_16x16x32_bf16 v[4:7], v[148:151], v[212:215], v[4:7]
	v_mfma_f32_16x16x32_bf16 v[0:3], v[156:159], v[212:215], v[0:3]
	s_barrier
	s_setprio 0
	s_add_u32 s42, s42, 0x100
	s_addc_u32 s43, s43, 0
	s_add_u32 s83, s83, 0x100
	s_addc_u32 s84, s84, 0
	s_cmp_ge_u32 s85, s70
	s_mov_b32 s46, s85
	s_cbranch_scc1 .Lkpeel_1079_exit
.LBB0_1079:
	ds_read_b128 v[96:99], v201
	ds_read_b128 v[100:103], v201 offset:1024
	ds_read_b128 v[108:111], v201 offset:2048
	ds_read_b128 v[116:119], v201 offset:3072
	ds_read_b128 v[144:147], v202
	ds_read_b128 v[148:151], v202 offset:1024
	ds_read_b128 v[152:155], v202 offset:2048
	ds_read_b128 v[156:159], v202 offset:3072
	s_add_i32 s85, s46, 2
	s_add_u32 s44, s42, 0xffea0080
	s_addc_u32 s45, s43, -1
	s_cmp_eq_u32 s71, s46
	s_cselect_b32 s46, s38, s44
	s_cselect_b32 s47, s39, s45
	s_cselect_b32 s45, s41, s84
	s_cselect_b32 s44, s40, s83
	v_lshl_add_u64 v[190:191], s[42:43], 0, v[176:177]
	s_add_i32 m0, s48, 0xc000
	ds_read_b128 v[160:163], v203
	ds_read_b128 v[164:167], v203 offset:1024
	ds_read_b128 v[182:185], v203 offset:2048
	ds_read_b128 v[186:189], v203 offset:3072
	ds_read_b128 v[194:197], v203 offset:4096
	ds_read_b128 v[204:207], v203 offset:5120
	ds_read_b128 v[208:211], v203 offset:6144
	ds_read_b128 v[212:215], v203 offset:7168
	global_load_lds_dwordx4 v[190:191], off
	v_lshl_add_u64 v[190:191], s[42:43], 0, v[178:179]
	s_add_i32 m0, s48, 0xe000
	s_nop 0
	global_load_lds_dwordx4 v[190:191], off
	s_waitcnt vmcnt(8)
	s_waitcnt lgkmcnt(0)
	s_setprio 1
	s_barrier
; #define PG8_STAGE(bufoff, gbase, voff) do { _Pragma("unroll") for (int _i = 0; _i < 2; ++_i) \
;         __builtin_amdgcn_global_load_lds((const unsigned*)((const char*)(gbase) + (voff)[_i]), (LAS unsigned*)(lds + (bufoff) + ldsw + _i * 8192), 16, 0, 0); } while (0)
; #define PG8_LDA(dst, b, h) do { _Pragma("unroll") for (int m = 0; m < 4; ++m) _Pragma("unroll") for (int k = 0; k < 2; ++k) dst[m][k] = *(const LAS bf16x8*)(lds + PG8_SA(b, h) + aoff + m * 2048 + k * 1024); } while (0)
; #define PG8_LDB(dst, b, h) do { _Pragma("unroll") for (int n = 0; n < 2; ++n) _Pragma("unroll") for (int k = 0; k < 2; ++k) dst[n][k] = *(const LAS bf16x8*)(lds + PG8_SB(b, h) + boff + n * 2048 + k * 1024); } while (0)
; #define PG8_MMA(ai, bj, At, Bt) do { __builtin_amdgcn_s_setprio(1); _Pragma("unroll") for (int m = 0; m < 4; ++m) _Pragma("unroll") for (int n = 0; n < 2; ++n) _Pragma("unroll") for (int k = 0; k < 2; ++k) \
;         acc[ai][bj][m][n] = __builtin_amdgcn_mfma_f32_16x16x32_bf16(Bt[n][k], At[m][k], acc[ai][bj][m][n], 0, 0, 0); __builtin_amdgcn_s_setprio(0); } while (0)
; #define PG8_WAIT_V(n) asm volatile("s_waitcnt vmcnt(" #n ")" ::: "memory")
; #define PG8_WAIT_L(n) asm volatile("s_waitcnt lgkmcnt(" #n ")" ::: "memory")
; #define PG8_BAR __builtin_amdgcn_s_barrier()
; #define PG8_SCHED __builtin_amdgcn_sched_barrier(0)
; template <class Epi, class Sched = StaticOrder, class EpiSub = NoSub, bool FAST = false>
; __device__ __forceinline__ void gemm_phase(LAS unsigned char* lds, const Gemm g, const Sched& S, const Epi& E, const EpiSub& ES = EpiSub()) {
;     ...
;             PG8_LDB(B0, 0, 0); PG8_LDB(B1, 0, 1); PG8_SCHED; PG8_LDA(At, 0, 0); PG8_STAGE(PG8_SA(1, 1), a1 + hstepA, voffA);
;             PG8_WAIT_V(8); PG8_WAIT_L(0); PG8_BAR; PG8_MMA(0, 0, At, B0); PG8_MMA(0, 1, At, B1); PG8_BAR; PG8_SCHED;
;             PG8_LDA(At, 0, 1); PG8_STAGE(PG8_SB(0, 0), b2, voffB); PG8_STAGE(PG8_SB(0, 1), b2 + hstepB, voffB); PG8_STAGE(PG8_SA(0, 0), a2, voffA);
;             PG8_WAIT_V(8); PG8_WAIT_L(0); PG8_BAR; PG8_MMA(1, 0, At, B0); PG8_MMA(1, 1, At, B1); PG8_BAR; PG8_SCHED;
	v_mfma_f32_16x16x32_bf16 v[140:143], v[96:99], v[160:163], v[140:143]
	v_mfma_f32_16x16x32_bf16 v[136:139], v[108:111], v[160:163], v[136:139]
	v_mfma_f32_16x16x32_bf16 v[124:127], v[96:99], v[182:185], v[124:127]
	v_mfma_f32_16x16x32_bf16 v[120:123], v[108:111], v[182:185], v[120:123]
	v_mfma_f32_16x16x32_bf16 v[92:95], v[96:99], v[194:197], v[92:95]
	v_mfma_f32_16x16x32_bf16 v[88:91], v[108:111], v[194:197], v[88:91]
	v_mfma_f32_16x16x32_bf16 v[76:79], v[96:99], v[208:211], v[76:79]
	v_mfma_f32_16x16x32_bf16 v[72:75], v[108:111], v[208:211], v[72:75]
	v_mfma_f32_16x16x32_bf16 v[140:143], v[100:103], v[164:167], v[140:143]
	v_mfma_f32_16x16x32_bf16 v[136:139], v[116:119], v[164:167], v[136:139]
	v_mfma_f32_16x16x32_bf16 v[124:127], v[100:103], v[186:189], v[124:127]
	v_mfma_f32_16x16x32_bf16 v[120:123], v[116:119], v[186:189], v[120:123]
	v_mfma_f32_16x16x32_bf16 v[92:95], v[100:103], v[204:207], v[92:95]
	v_mfma_f32_16x16x32_bf16 v[88:91], v[116:119], v[204:207], v[88:91]
	v_mfma_f32_16x16x32_bf16 v[76:79], v[100:103], v[212:215], v[76:79]
	v_mfma_f32_16x16x32_bf16 v[72:75], v[116:119], v[212:215], v[72:75]
	v_mfma_f32_16x16x32_bf16 v[132:135], v[144:147], v[160:163], v[132:135]
	v_mfma_f32_16x16x32_bf16 v[128:131], v[152:155], v[160:163], v[128:131]
	v_mfma_f32_16x16x32_bf16 v[112:115], v[144:147], v[182:185], v[112:115]
	v_mfma_f32_16x16x32_bf16 v[104:107], v[152:155], v[182:185], v[104:107]
	v_mfma_f32_16x16x32_bf16 v[84:87], v[144:147], v[194:197], v[84:87]
	v_mfma_f32_16x16x32_bf16 v[80:83], v[152:155], v[194:197], v[80:83]
	v_mfma_f32_16x16x32_bf16 v[68:71], v[144:147], v[208:211], v[68:71]
	v_mfma_f32_16x16x32_bf16 v[64:67], v[152:155], v[208:211], v[64:67]
	v_mfma_f32_16x16x32_bf16 v[132:135], v[148:151], v[164:167], v[132:135]
	v_mfma_f32_16x16x32_bf16 v[128:131], v[156:159], v[164:167], v[128:131]
	v_mfma_f32_16x16x32_bf16 v[112:115], v[148:151], v[186:189], v[112:115]
	v_mfma_f32_16x16x32_bf16 v[104:107], v[156:159], v[186:189], v[104:107]
	v_mfma_f32_16x16x32_bf16 v[84:87], v[148:151], v[204:207], v[84:87]
	v_mfma_f32_16x16x32_bf16 v[80:83], v[156:159], v[204:207], v[80:83]
	v_mfma_f32_16x16x32_bf16 v[68:71], v[148:151], v[212:215], v[68:71]
	v_mfma_f32_16x16x32_bf16 v[64:67], v[156:159], v[212:215], v[64:67]
	s_barrier
	s_setprio 0
	s_add_i32 s86, s58, s27
	v_lshl_add_u64 v[190:191], s[44:45], 0, v[170:171]
	s_mov_b32 m0, s86
	ds_read_b128 v[160:163], v203 offset:16384
	ds_read_b128 v[164:167], v203 offset:17408
	ds_read_b128 v[182:185], v203 offset:18432
	ds_read_b128 v[186:189], v203 offset:19456
	ds_read_b128 v[194:197], v203 offset:20480
	ds_read_b128 v[204:207], v203 offset:21504
	ds_read_b128 v[208:211], v203 offset:22528
	ds_read_b128 v[212:215], v203 offset:23552
	global_load_lds_dwordx4 v[190:191], off
	s_add_i32 m0, s86, 0x2000
	s_add_u32 s86, s44, 0x160000
	v_lshl_add_u64 v[216:217], s[44:45], 0, v[174:175]
	s_addc_u32 s87, s45, 0
	s_add_i32 s88, s59, s27
	global_load_lds_dwordx4 v[216:217], off
	v_lshl_add_u64 v[218:219], s[86:87], 0, v[170:171]
	s_mov_b32 m0, s88
	v_lshl_add_u64 v[220:221], s[46:47], 0, v[172:173]
	global_load_lds_dwordx4 v[218:219], off
	v_lshl_add_u64 v[218:219], s[86:87], 0, v[174:175]
	s_add_i32 m0, s88, 0x2000
	s_nop 0
	global_load_lds_dwordx4 v[218:219], off
	v_lshl_add_u64 v[218:219], s[46:47], 0, v[168:169]
	s_mov_b32 m0, s48
	s_nop 0
	global_load_lds_dwordx4 v[218:219], off
	s_mov_b32 m0, s49
	s_nop 0
	global_load_lds_dwordx4 v[220:221], off
	s_waitcnt vmcnt(8)
	s_waitcnt lgkmcnt(0)
	s_setprio 1
	s_barrier
	v_mfma_f32_16x16x32_bf16 v[60:63], v[96:99], v[160:163], v[60:63]
	v_mfma_f32_16x16x32_bf16 v[56:59], v[108:111], v[160:163], v[56:59]
	v_mfma_f32_16x16x32_bf16 v[44:47], v[96:99], v[182:185], v[44:47]
	v_mfma_f32_16x16x32_bf16 v[40:43], v[108:111], v[182:185], v[40:43]
	v_mfma_f32_16x16x32_bf16 v[28:31], v[96:99], v[194:197], v[28:31]
	v_mfma_f32_16x16x32_bf16 v[24:27], v[108:111], v[194:197], v[24:27]
	v_mfma_f32_16x16x32_bf16 v[12:15], v[96:99], v[208:211], v[12:15]
	v_mfma_f32_16x16x32_bf16 v[8:11], v[108:111], v[208:211], v[8:11]
	v_mfma_f32_16x16x32_bf16 v[60:63], v[100:103], v[164:167], v[60:63]
	v_mfma_f32_16x16x32_bf16 v[56:59], v[116:119], v[164:167], v[56:59]
	v_mfma_f32_16x16x32_bf16 v[44:47], v[100:103], v[186:189], v[44:47]
	v_mfma_f32_16x16x32_bf16 v[40:43], v[116:119], v[186:189], v[40:43]
	v_mfma_f32_16x16x32_bf16 v[28:31], v[100:103], v[204:207], v[28:31]
	v_mfma_f32_16x16x32_bf16 v[24:27], v[116:119], v[204:207], v[24:27]
	v_mfma_f32_16x16x32_bf16 v[12:15], v[100:103], v[212:215], v[12:15]
	v_mfma_f32_16x16x32_bf16 v[8:11], v[116:119], v[212:215], v[8:11]
	v_mfma_f32_16x16x32_bf16 v[52:55], v[144:147], v[160:163], v[52:55]
	v_mfma_f32_16x16x32_bf16 v[48:51], v[152:155], v[160:163], v[48:51]
	v_mfma_f32_16x16x32_bf16 v[36:39], v[144:147], v[182:185], v[36:39]
	v_mfma_f32_16x16x32_bf16 v[32:35], v[152:155], v[182:185], v[32:35]
	v_mfma_f32_16x16x32_bf16 v[20:23], v[144:147], v[194:197], v[20:23]
	v_mfma_f32_16x16x32_bf16 v[16:19], v[152:155], v[194:197], v[16:19]
	v_mfma_f32_16x16x32_bf16 v[4:7], v[144:147], v[208:211], v[4:7]
	v_mfma_f32_16x16x32_bf16 v[0:3], v[152:155], v[208:211], v[0:3]
	v_mfma_f32_16x16x32_bf16 v[52:55], v[148:151], v[164:167], v[52:55]
	v_mfma_f32_16x16x32_bf16 v[48:51], v[156:159], v[164:167], v[48:51]
	v_mfma_f32_16x16x32_bf16 v[36:39], v[148:151], v[186:189], v[36:39]
	v_mfma_f32_16x16x32_bf16 v[32:35], v[156:159], v[186:189], v[32:35]
	v_mfma_f32_16x16x32_bf16 v[20:23], v[148:151], v[204:207], v[20:23]
	v_mfma_f32_16x16x32_bf16 v[16:19], v[156:159], v[204:207], v[16:19]
	v_mfma_f32_16x16x32_bf16 v[4:7], v[148:151], v[212:215], v[4:7]
	v_mfma_f32_16x16x32_bf16 v[0:3], v[156:159], v[212:215], v[0:3]
	s_barrier
; #define PG8_STAGE(bufoff, gbase, voff) do { _Pragma("unroll") for (int _i = 0; _i < 2; ++_i) \
;         __builtin_amdgcn_global_load_lds((const unsigned*)((const char*)(gbase) + (voff)[_i]), (LAS unsigned*)(lds + (bufoff) + ldsw + _i * 8192), 16, 0, 0); } while (0)
; #define PG8_LDA(dst, b, h) do { _Pragma("unroll") for (int m = 0; m < 4; ++m) _Pragma("unroll") for (int k = 0; k < 2; ++k) dst[m][k] = *(const LAS bf16x8*)(lds + PG8_SA(b, h) + aoff + m * 2048 + k * 1024); } while (0)
; #define PG8_LDB(dst, b, h) do { _Pragma("unroll") for (int n = 0; n < 2; ++n) _Pragma("unroll") for (int k = 0; k < 2; ++k) dst[n][k] = *(const LAS bf16x8*)(lds + PG8_SB(b, h) + boff + n * 2048 + k * 1024); } while (0)
; #define PG8_MMA(ai, bj, At, Bt) do { __builtin_amdgcn_s_setprio(1); _Pragma("unroll") for (int m = 0; m < 4; ++m) _Pragma("unroll") for (int n = 0; n < 2; ++n) _Pragma("unroll") for (int k = 0; k < 2; ++k) \
;         acc[ai][bj][m][n] = __builtin_amdgcn_mfma_f32_16x16x32_bf16(Bt[n][k], At[m][k], acc[ai][bj][m][n], 0, 0, 0); __builtin_amdgcn_s_setprio(0); } while (0)
; #define PG8_WAIT_V(n) asm volatile("s_waitcnt vmcnt(" #n ")" ::: "memory")
; #define PG8_WAIT_L(n) asm volatile("s_waitcnt lgkmcnt(" #n ")" ::: "memory")
; #define PG8_BAR __builtin_amdgcn_s_barrier()
; #define PG8_SCHED __builtin_amdgcn_sched_barrier(0)
; template <class Epi, class Sched = StaticOrder, class EpiSub = NoSub, bool FAST = false>
; __device__ __forceinline__ void gemm_phase(LAS unsigned char* lds, const Gemm g, const Sched& S, const Epi& E, const EpiSub& ES = EpiSub()) {
;     ...
;             PG8_LDB(B0, 1, 0); PG8_LDB(B1, 1, 1); PG8_SCHED; PG8_LDA(At, 1, 0); PG8_STAGE(PG8_SA(0, 1), a2 + hstepA, voffA);
;             PG8_WAIT_V(8); PG8_WAIT_L(0); PG8_BAR; PG8_MMA(0, 0, At, B0); PG8_MMA(0, 1, At, B1); PG8_BAR; PG8_SCHED;
	s_setprio 0
	s_add_i32 s86, 0, 0x18000
	s_add_i32 s87, 0, 0x1c000
	v_add_u32_e32 v116, s86, v198
	v_add_u32_e32 v156, s87, v198
	ds_read_b128 v[96:99], v116
	ds_read_b128 v[100:103], v116 offset:1024
	ds_read_b128 v[108:111], v116 offset:2048
	ds_read_b128 v[116:119], v116 offset:3072
	ds_read_b128 v[144:147], v156
	ds_read_b128 v[148:151], v156 offset:1024
	ds_read_b128 v[152:155], v156 offset:2048
	ds_read_b128 v[156:159], v156 offset:3072
	s_add_u32 s46, s46, 0x160000
	s_addc_u32 s47, s47, 0
	s_mov_b32 m0, s50
	v_lshl_add_u64 v[222:223], s[46:47], 0, v[168:169]
	ds_read_b128 v[160:163], v203 offset:32768
	ds_read_b128 v[164:167], v203 offset:33792
	ds_read_b128 v[182:185], v203 offset:34816
	ds_read_b128 v[186:189], v203 offset:35840
	ds_read_b128 v[194:197], v203 offset:36864
	ds_read_b128 v[204:207], v203 offset:37888
	ds_read_b128 v[208:211], v203 offset:38912
	ds_read_b128 v[212:215], v203 offset:39936
	global_load_lds_dwordx4 v[222:223], off
	v_lshl_add_u64 v[222:223], s[46:47], 0, v[172:173]
	s_mov_b32 m0, s51
	s_nop 0
	global_load_lds_dwordx4 v[222:223], off
	s_waitcnt vmcnt(8)
	s_waitcnt lgkmcnt(0)
	s_setprio 1
	s_barrier
	v_mfma_f32_16x16x32_bf16 v[140:143], v[96:99], v[160:163], v[140:143]
	v_mfma_f32_16x16x32_bf16 v[136:139], v[108:111], v[160:163], v[136:139]
	v_mfma_f32_16x16x32_bf16 v[124:127], v[96:99], v[182:185], v[124:127]
	v_mfma_f32_16x16x32_bf16 v[120:123], v[108:111], v[182:185], v[120:123]
	v_mfma_f32_16x16x32_bf16 v[92:95], v[96:99], v[194:197], v[92:95]
	v_mfma_f32_16x16x32_bf16 v[88:91], v[108:111], v[194:197], v[88:91]
	v_mfma_f32_16x16x32_bf16 v[76:79], v[96:99], v[208:211], v[76:79]
	v_mfma_f32_16x16x32_bf16 v[72:75], v[108:111], v[208:211], v[72:75]
	v_mfma_f32_16x16x32_bf16 v[140:143], v[100:103], v[164:167], v[140:143]
	v_mfma_f32_16x16x32_bf16 v[136:139], v[116:119], v[164:167], v[136:139]
	v_mfma_f32_16x16x32_bf16 v[124:127], v[100:103], v[186:189], v[124:127]
	v_mfma_f32_16x16x32_bf16 v[120:123], v[116:119], v[186:189], v[120:123]
	v_mfma_f32_16x16x32_bf16 v[92:95], v[100:103], v[204:207], v[92:95]
	v_mfma_f32_16x16x32_bf16 v[88:91], v[116:119], v[204:207], v[88:91]
	v_mfma_f32_16x16x32_bf16 v[76:79], v[100:103], v[212:215], v[76:79]
	v_mfma_f32_16x16x32_bf16 v[72:75], v[116:119], v[212:215], v[72:75]
	v_mfma_f32_16x16x32_bf16 v[132:135], v[144:147], v[160:163], v[132:135]
	v_mfma_f32_16x16x32_bf16 v[128:131], v[152:155], v[160:163], v[128:131]
	v_mfma_f32_16x16x32_bf16 v[112:115], v[144:147], v[182:185], v[112:115]
	v_mfma_f32_16x16x32_bf16 v[104:107], v[152:155], v[182:185], v[104:107]
	v_mfma_f32_16x16x32_bf16 v[84:87], v[144:147], v[194:197], v[84:87]
	v_mfma_f32_16x16x32_bf16 v[80:83], v[152:155], v[194:197], v[80:83]
	v_mfma_f32_16x16x32_bf16 v[68:71], v[144:147], v[208:211], v[68:71]
	v_mfma_f32_16x16x32_bf16 v[64:67], v[152:155], v[208:211], v[64:67]
	v_mfma_f32_16x16x32_bf16 v[132:135], v[148:151], v[164:167], v[132:135]
	v_mfma_f32_16x16x32_bf16 v[128:131], v[156:159], v[164:167], v[128:131]
	v_mfma_f32_16x16x32_bf16 v[112:115], v[148:151], v[186:189], v[112:115]
	v_mfma_f32_16x16x32_bf16 v[104:107], v[156:159], v[186:189], v[104:107]
	v_mfma_f32_16x16x32_bf16 v[84:87], v[148:151], v[204:207], v[84:87]
	v_mfma_f32_16x16x32_bf16 v[80:83], v[156:159], v[204:207], v[80:83]
	v_mfma_f32_16x16x32_bf16 v[68:71], v[148:151], v[212:215], v[68:71]
	v_mfma_f32_16x16x32_bf16 v[64:67], v[156:159], v[212:215], v[64:67]
	s_barrier
; #define PG8_STAGE(bufoff, gbase, voff) do { _Pragma("unroll") for (int _i = 0; _i < 2; ++_i) \
;         __builtin_amdgcn_global_load_lds((const unsigned*)((const char*)(gbase) + (voff)[_i]), (LAS unsigned*)(lds + (bufoff) + ldsw + _i * 8192), 16, 0, 0); } while (0)
; #define PG8_LDA(dst, b, h) do { _Pragma("unroll") for (int m = 0; m < 4; ++m) _Pragma("unroll") for (int k = 0; k < 2; ++k) dst[m][k] = *(const LAS bf16x8*)(lds + PG8_SA(b, h) + aoff + m * 2048 + k * 1024); } while (0)
; #define PG8_MMA(ai, bj, At, Bt) do { __builtin_amdgcn_s_setprio(1); _Pragma("unroll") for (int m = 0; m < 4; ++m) _Pragma("unroll") for (int n = 0; n < 2; ++n) _Pragma("unroll") for (int k = 0; k < 2; ++k) \
;         acc[ai][bj][m][n] = __builtin_amdgcn_mfma_f32_16x16x32_bf16(Bt[n][k], At[m][k], acc[ai][bj][m][n], 0, 0, 0); __builtin_amdgcn_s_setprio(0); } while (0)
; #define PG8_WAIT_V(n) asm volatile("s_waitcnt vmcnt(" #n ")" ::: "memory")
; #define PG8_WAIT_L(n) asm volatile("s_waitcnt lgkmcnt(" #n ")" ::: "memory")
; #define PG8_BAR __builtin_amdgcn_s_barrier()
; #define PG8_SCHED __builtin_amdgcn_sched_barrier(0)
; template <class Epi, class Sched = StaticOrder, class EpiSub = NoSub, bool FAST = false>
; __device__ __forceinline__ void gemm_phase(LAS unsigned char* lds, const Gemm g, const Sched& S, const Epi& E, const EpiSub& ES = EpiSub()) {
;     ...
;             PG8_LDA(At, 1, 1); PG8_STAGE(PG8_SB(1, 0), b3, voffB); PG8_STAGE(PG8_SB(1, 1), b3 + hstepB, voffB); PG8_STAGE(PG8_SA(1, 0), a3, voffA);
;             PG8_WAIT_V(8); PG8_WAIT_L(0); PG8_BAR; PG8_MMA(1, 0, At, B0); PG8_MMA(1, 1, At, B1); PG8_BAR; PG8_SCHED;
;     ...
;         if constexpr (FAST && PG8_ALIGN) { if (wr == 0) PG8_BAR; }
	s_setprio 0
	s_add_i32 s46, s86, s27
	v_lshl_add_u64 v[190:191], v[190:191], 0, s[16:17]
	s_mov_b32 m0, s46
	ds_read_b128 v[160:163], v203 offset:49152
	ds_read_b128 v[164:167], v203 offset:50176
	ds_read_b128 v[182:185], v203 offset:51200
	ds_read_b128 v[186:189], v203 offset:52224
	ds_read_b128 v[194:197], v203 offset:53248
	ds_read_b128 v[204:207], v203 offset:54272
	ds_read_b128 v[208:211], v203 offset:55296
	ds_read_b128 v[212:215], v203 offset:56320
	global_load_lds_dwordx4 v[190:191], off
	s_add_i32 m0, s46, 0x2000
	s_add_u32 s44, s44, 0x160080
	v_lshl_add_u64 v[190:191], v[216:217], 0, s[16:17]
	s_addc_u32 s45, s45, 0
	s_add_i32 s46, s87, s27
	global_load_lds_dwordx4 v[190:191], off
	v_lshl_add_u64 v[190:191], s[44:45], 0, v[170:171]
	s_mov_b32 m0, s46
	s_nop 0
	global_load_lds_dwordx4 v[190:191], off
	v_lshl_add_u64 v[190:191], s[44:45], 0, v[174:175]
	s_add_i32 m0, s46, 0x2000
	s_nop 0
	global_load_lds_dwordx4 v[190:191], off
	v_lshl_add_u64 v[190:191], v[218:219], 0, s[16:17]
	s_mov_b32 m0, s53
	s_nop 0
	global_load_lds_dwordx4 v[190:191], off
	v_lshl_add_u64 v[190:191], v[220:221], 0, s[16:17]
	s_mov_b32 m0, s54
	s_nop 0
	global_load_lds_dwordx4 v[190:191], off
	s_waitcnt vmcnt(8)
	s_waitcnt lgkmcnt(0)
	s_setprio 1
	s_barrier
	v_mfma_f32_16x16x32_bf16 v[60:63], v[96:99], v[160:163], v[60:63]
	v_mfma_f32_16x16x32_bf16 v[56:59], v[108:111], v[160:163], v[56:59]
	v_mfma_f32_16x16x32_bf16 v[44:47], v[96:99], v[182:185], v[44:47]
	v_mfma_f32_16x16x32_bf16 v[40:43], v[108:111], v[182:185], v[40:43]
	v_mfma_f32_16x16x32_bf16 v[28:31], v[96:99], v[194:197], v[28:31]
	v_mfma_f32_16x16x32_bf16 v[24:27], v[108:111], v[194:197], v[24:27]
	v_mfma_f32_16x16x32_bf16 v[12:15], v[96:99], v[208:211], v[12:15]
	v_mfma_f32_16x16x32_bf16 v[8:11], v[108:111], v[208:211], v[8:11]
	v_mfma_f32_16x16x32_bf16 v[60:63], v[100:103], v[164:167], v[60:63]
	v_mfma_f32_16x16x32_bf16 v[56:59], v[116:119], v[164:167], v[56:59]
	v_mfma_f32_16x16x32_bf16 v[44:47], v[100:103], v[186:189], v[44:47]
	v_mfma_f32_16x16x32_bf16 v[40:43], v[116:119], v[186:189], v[40:43]
	v_mfma_f32_16x16x32_bf16 v[28:31], v[100:103], v[204:207], v[28:31]
	v_mfma_f32_16x16x32_bf16 v[24:27], v[116:119], v[204:207], v[24:27]
	v_mfma_f32_16x16x32_bf16 v[12:15], v[100:103], v[212:215], v[12:15]
	v_mfma_f32_16x16x32_bf16 v[8:11], v[116:119], v[212:215], v[8:11]
	v_mfma_f32_16x16x32_bf16 v[52:55], v[144:147], v[160:163], v[52:55]
	v_mfma_f32_16x16x32_bf16 v[48:51], v[152:155], v[160:163], v[48:51]
	v_mfma_f32_16x16x32_bf16 v[36:39], v[144:147], v[182:185], v[36:39]
	v_mfma_f32_16x16x32_bf16 v[32:35], v[152:155], v[182:185], v[32:35]
	v_mfma_f32_16x16x32_bf16 v[20:23], v[144:147], v[194:197], v[20:23]
	v_mfma_f32_16x16x32_bf16 v[16:19], v[152:155], v[194:197], v[16:19]
	v_mfma_f32_16x16x32_bf16 v[4:7], v[144:147], v[208:211], v[4:7]
	v_mfma_f32_16x16x32_bf16 v[0:3], v[152:155], v[208:211], v[0:3]
	v_mfma_f32_16x16x32_bf16 v[52:55], v[148:151], v[164:167], v[52:55]
	v_mfma_f32_16x16x32_bf16 v[48:51], v[156:159], v[164:167], v[48:51]
	v_mfma_f32_16x16x32_bf16 v[36:39], v[148:151], v[186:189], v[36:39]
	v_mfma_f32_16x16x32_bf16 v[32:35], v[156:159], v[186:189], v[32:35]
	v_mfma_f32_16x16x32_bf16 v[20:23], v[148:151], v[204:207], v[20:23]
	v_mfma_f32_16x16x32_bf16 v[16:19], v[156:159], v[204:207], v[16:19]
	v_mfma_f32_16x16x32_bf16 v[4:7], v[148:151], v[212:215], v[4:7]
	v_mfma_f32_16x16x32_bf16 v[0:3], v[156:159], v[212:215], v[0:3]
	s_barrier
	s_setprio 0
	s_add_u32 s42, s42, 0x100
	s_addc_u32 s43, s43, 0
	s_add_u32 s83, s83, 0x100
	s_addc_u32 s84, s84, 0
	s_cmp_ge_u32 s85, s70
	s_mov_b32 s46, s85
	s_cbranch_scc0 .LBB0_1079
.Lkpeel_1079_exit:
	s_and_b64 vcc, exec, s[18:19]
	s_cbranch_vccz .LBB0_1082
	s_barrier
